# v25 with every s_setprio removed from the 7 K-loops (A/B of the template's per-block priority flips)
# baseline (speedup 1.0000x reference)
.LBB0_131:
	s_add_u32 s60, s57, 0xffffff80
	s_addc_u32 s61, s58, -1
	s_cmp_eq_u32 s59, 60
	s_cselect_b32 s36, s17, s57
	s_cselect_b32 s37, s7, s58
	s_cselect_b32 s39, s21, s56
	s_cselect_b32 s38, s33, s55
	s_add_u32 s30, s36, 0x80
	s_addc_u32 s31, s37, 0
	s_add_u32 s34, s38, 0x80
	s_addc_u32 s35, s39, 0
	s_add_i32 s62, 0, 0x10000
	s_add_i32 s63, 0, 0x14000
	v_add_u32_e32 v152, s62, v1
	v_add_u32_e32 v168, s63, v1
	ds_read_b128 v[140:143], v152
	ds_read_b128 v[144:147], v152 offset:1024
	ds_read_b128 v[148:151], v152 offset:2048
	ds_read_b128 v[152:155], v152 offset:3072
	ds_read_b128 v[156:159], v168
	ds_read_b128 v[160:163], v168 offset:1024
	ds_read_b128 v[164:167], v168 offset:2048
	ds_read_b128 v[168:171], v168 offset:3072
	s_add_u32 s60, s60, 0x100000
	s_addc_u32 s61, s61, 0
	v_lshl_add_u64 v[204:205], s[60:61], 0, v[2:3]
	s_add_i32 m0, s29, 0xc000
	ds_read_b128 v[172:175], v5
	ds_read_b128 v[176:179], v5 offset:1024
	ds_read_b128 v[180:183], v5 offset:2048
	ds_read_b128 v[184:187], v5 offset:3072
	ds_read_b128 v[188:191], v5 offset:4096
	ds_read_b128 v[192:195], v5 offset:5120
	ds_read_b128 v[196:199], v5 offset:6144
	ds_read_b128 v[200:203], v5 offset:7168
	global_load_lds_dwordx4 v[204:205], off
	v_lshl_add_u64 v[204:205], s[60:61], 0, v[136:137]
	s_add_i32 m0, s29, 0xe000
	s_nop 0
	global_load_lds_dwordx4 v[204:205], off
	s_waitcnt vmcnt(8)
	s_waitcnt lgkmcnt(0)
	s_barrier
	v_mfma_f32_16x16x32_bf16 v[130:133], v[140:143], v[172:175], v[130:133]
	v_mfma_f32_16x16x32_bf16 v[126:129], v[148:151], v[172:175], v[126:129]
	v_mfma_f32_16x16x32_bf16 v[114:117], v[140:143], v[180:183], v[114:117]
	v_mfma_f32_16x16x32_bf16 v[110:113], v[148:151], v[180:183], v[110:113]
	v_mfma_f32_16x16x32_bf16 v[98:101], v[140:143], v[188:191], v[98:101]
	v_mfma_f32_16x16x32_bf16 v[94:97], v[148:151], v[188:191], v[94:97]
	v_mfma_f32_16x16x32_bf16 v[82:85], v[140:143], v[196:199], v[82:85]
	v_mfma_f32_16x16x32_bf16 v[78:81], v[148:151], v[196:199], v[78:81]
	v_mfma_f32_16x16x32_bf16 v[130:133], v[144:147], v[176:179], v[130:133]
	v_mfma_f32_16x16x32_bf16 v[126:129], v[152:155], v[176:179], v[126:129]
	v_mfma_f32_16x16x32_bf16 v[114:117], v[144:147], v[184:187], v[114:117]
	v_mfma_f32_16x16x32_bf16 v[110:113], v[152:155], v[184:187], v[110:113]
	v_mfma_f32_16x16x32_bf16 v[98:101], v[144:147], v[192:195], v[98:101]
	v_mfma_f32_16x16x32_bf16 v[94:97], v[152:155], v[192:195], v[94:97]
	v_mfma_f32_16x16x32_bf16 v[82:85], v[144:147], v[200:203], v[82:85]
	v_mfma_f32_16x16x32_bf16 v[78:81], v[152:155], v[200:203], v[78:81]
	v_mfma_f32_16x16x32_bf16 v[122:125], v[156:159], v[172:175], v[122:125]
	v_mfma_f32_16x16x32_bf16 v[118:121], v[164:167], v[172:175], v[118:121]
	v_mfma_f32_16x16x32_bf16 v[106:109], v[156:159], v[180:183], v[106:109]
	v_mfma_f32_16x16x32_bf16 v[102:105], v[164:167], v[180:183], v[102:105]
	v_mfma_f32_16x16x32_bf16 v[90:93], v[156:159], v[188:191], v[90:93]
	v_mfma_f32_16x16x32_bf16 v[86:89], v[164:167], v[188:191], v[86:89]
	v_mfma_f32_16x16x32_bf16 v[74:77], v[156:159], v[196:199], v[74:77]
	v_mfma_f32_16x16x32_bf16 v[70:73], v[164:167], v[196:199], v[70:73]
	v_mfma_f32_16x16x32_bf16 v[122:125], v[160:163], v[176:179], v[122:125]
	v_mfma_f32_16x16x32_bf16 v[118:121], v[168:171], v[176:179], v[118:121]
	v_mfma_f32_16x16x32_bf16 v[106:109], v[160:163], v[184:187], v[106:109]
	v_mfma_f32_16x16x32_bf16 v[102:105], v[168:171], v[184:187], v[102:105]
	v_mfma_f32_16x16x32_bf16 v[90:93], v[160:163], v[192:195], v[90:93]
	v_mfma_f32_16x16x32_bf16 v[86:89], v[168:171], v[192:195], v[86:89]
	v_mfma_f32_16x16x32_bf16 v[74:77], v[160:163], v[200:203], v[74:77]
	v_mfma_f32_16x16x32_bf16 v[70:73], v[168:171], v[200:203], v[70:73]
	s_barrier
	s_add_i32 s60, s62, s42
	v_lshl_add_u64 v[204:205], s[38:39], 0, v[134:135]
	s_mov_b32 m0, s60
	ds_read_b128 v[172:175], v5 offset:16384
	ds_read_b128 v[176:179], v5 offset:17408
	ds_read_b128 v[180:183], v5 offset:18432
	ds_read_b128 v[184:187], v5 offset:19456
	ds_read_b128 v[188:191], v5 offset:20480
	ds_read_b128 v[192:195], v5 offset:21504
	ds_read_b128 v[196:199], v5 offset:22528
	ds_read_b128 v[200:203], v5 offset:23552
	global_load_lds_dwordx4 v[204:205], off
	s_add_i32 m0, s60, 0x2000
	v_lshl_add_u64 v[204:205], s[38:39], 0, v[138:139]
	s_add_u32 s38, s38, 0x100000
	s_addc_u32 s39, s39, 0
	s_add_i32 s60, s63, s42
	global_load_lds_dwordx4 v[204:205], off
	v_lshl_add_u64 v[204:205], s[38:39], 0, v[134:135]
	s_mov_b32 m0, s60
	s_nop 0
	global_load_lds_dwordx4 v[204:205], off
	v_lshl_add_u64 v[204:205], s[38:39], 0, v[138:139]
	s_add_i32 m0, s60, 0x2000
	s_nop 0
	global_load_lds_dwordx4 v[204:205], off
	v_lshl_add_u64 v[204:205], s[36:37], 0, v[2:3]
	s_mov_b32 m0, s29
	s_nop 0
	global_load_lds_dwordx4 v[204:205], off
	v_lshl_add_u64 v[204:205], s[36:37], 0, v[136:137]
	s_mov_b32 m0, s43
	s_nop 0
	global_load_lds_dwordx4 v[204:205], off
	s_waitcnt vmcnt(8)
	s_waitcnt lgkmcnt(0)
	s_barrier
	v_mfma_f32_16x16x32_bf16 v[66:69], v[140:143], v[172:175], v[66:69]
	v_mfma_f32_16x16x32_bf16 v[62:65], v[148:151], v[172:175], v[62:65]
	v_mfma_f32_16x16x32_bf16 v[50:53], v[140:143], v[180:183], v[50:53]
	v_mfma_f32_16x16x32_bf16 v[46:49], v[148:151], v[180:183], v[46:49]
	v_mfma_f32_16x16x32_bf16 v[34:37], v[140:143], v[188:191], v[34:37]
	v_mfma_f32_16x16x32_bf16 v[30:33], v[148:151], v[188:191], v[30:33]
	v_mfma_f32_16x16x32_bf16 v[18:21], v[140:143], v[196:199], v[18:21]
	v_mfma_f32_16x16x32_bf16 v[14:17], v[148:151], v[196:199], v[14:17]
	v_mfma_f32_16x16x32_bf16 v[66:69], v[144:147], v[176:179], v[66:69]
	v_mfma_f32_16x16x32_bf16 v[62:65], v[152:155], v[176:179], v[62:65]
	v_mfma_f32_16x16x32_bf16 v[50:53], v[144:147], v[184:187], v[50:53]
	v_mfma_f32_16x16x32_bf16 v[46:49], v[152:155], v[184:187], v[46:49]
	v_mfma_f32_16x16x32_bf16 v[34:37], v[144:147], v[192:195], v[34:37]
	v_mfma_f32_16x16x32_bf16 v[30:33], v[152:155], v[192:195], v[30:33]
	v_mfma_f32_16x16x32_bf16 v[18:21], v[144:147], v[200:203], v[18:21]
	v_mfma_f32_16x16x32_bf16 v[14:17], v[152:155], v[200:203], v[14:17]
	v_mfma_f32_16x16x32_bf16 v[58:61], v[156:159], v[172:175], v[58:61]
	v_mfma_f32_16x16x32_bf16 v[54:57], v[164:167], v[172:175], v[54:57]
	v_mfma_f32_16x16x32_bf16 v[42:45], v[156:159], v[180:183], v[42:45]
	v_mfma_f32_16x16x32_bf16 v[38:41], v[164:167], v[180:183], v[38:41]
	v_mfma_f32_16x16x32_bf16 v[26:29], v[156:159], v[188:191], v[26:29]
	v_mfma_f32_16x16x32_bf16 v[22:25], v[164:167], v[188:191], v[22:25]
	v_mfma_f32_16x16x32_bf16 v[10:13], v[156:159], v[196:199], v[10:13]
	v_mfma_f32_16x16x32_bf16 v[6:9], v[164:167], v[196:199], v[6:9]
	v_mfma_f32_16x16x32_bf16 v[58:61], v[160:163], v[176:179], v[58:61]
	v_mfma_f32_16x16x32_bf16 v[54:57], v[168:171], v[176:179], v[54:57]
	v_mfma_f32_16x16x32_bf16 v[42:45], v[160:163], v[184:187], v[42:45]
	v_mfma_f32_16x16x32_bf16 v[38:41], v[168:171], v[184:187], v[38:41]
	v_mfma_f32_16x16x32_bf16 v[26:29], v[160:163], v[192:195], v[26:29]
	v_mfma_f32_16x16x32_bf16 v[22:25], v[168:171], v[192:195], v[22:25]
	v_mfma_f32_16x16x32_bf16 v[10:13], v[160:163], v[200:203], v[10:13]
	v_mfma_f32_16x16x32_bf16 v[6:9], v[168:171], v[200:203], v[6:9]
	s_barrier
	s_add_i32 s38, 0, 0x18000
	s_add_i32 s39, 0, 0x1c000
	v_add_u32_e32 v152, s38, v1
	v_add_u32_e32 v168, s39, v1
	ds_read_b128 v[140:143], v152
	ds_read_b128 v[144:147], v152 offset:1024
	ds_read_b128 v[148:151], v152 offset:2048
	ds_read_b128 v[152:155], v152 offset:3072
	ds_read_b128 v[156:159], v168
	ds_read_b128 v[160:163], v168 offset:1024
	ds_read_b128 v[164:167], v168 offset:2048
	ds_read_b128 v[168:171], v168 offset:3072
	s_add_u32 s36, s36, 0x100000
	s_addc_u32 s37, s37, 0
	s_mov_b32 m0, s48
	v_lshl_add_u64 v[204:205], s[36:37], 0, v[2:3]
	ds_read_b128 v[172:175], v5 offset:32768
	ds_read_b128 v[176:179], v5 offset:33792
	ds_read_b128 v[180:183], v5 offset:34816
	ds_read_b128 v[184:187], v5 offset:35840
	ds_read_b128 v[188:191], v5 offset:36864
	ds_read_b128 v[192:195], v5 offset:37888
	ds_read_b128 v[196:199], v5 offset:38912
	ds_read_b128 v[200:203], v5 offset:39936
	global_load_lds_dwordx4 v[204:205], off
	v_lshl_add_u64 v[204:205], s[36:37], 0, v[136:137]
	s_mov_b32 m0, s49
	s_nop 0
	global_load_lds_dwordx4 v[204:205], off
	s_waitcnt vmcnt(8)
	s_waitcnt lgkmcnt(0)
	s_barrier
	v_mfma_f32_16x16x32_bf16 v[130:133], v[140:143], v[172:175], v[130:133]
	v_mfma_f32_16x16x32_bf16 v[126:129], v[148:151], v[172:175], v[126:129]
	v_mfma_f32_16x16x32_bf16 v[114:117], v[140:143], v[180:183], v[114:117]
	v_mfma_f32_16x16x32_bf16 v[110:113], v[148:151], v[180:183], v[110:113]
	v_mfma_f32_16x16x32_bf16 v[98:101], v[140:143], v[188:191], v[98:101]
	v_mfma_f32_16x16x32_bf16 v[94:97], v[148:151], v[188:191], v[94:97]
	v_mfma_f32_16x16x32_bf16 v[82:85], v[140:143], v[196:199], v[82:85]
	v_mfma_f32_16x16x32_bf16 v[78:81], v[148:151], v[196:199], v[78:81]
	v_mfma_f32_16x16x32_bf16 v[130:133], v[144:147], v[176:179], v[130:133]
	v_mfma_f32_16x16x32_bf16 v[126:129], v[152:155], v[176:179], v[126:129]
	v_mfma_f32_16x16x32_bf16 v[114:117], v[144:147], v[184:187], v[114:117]
	v_mfma_f32_16x16x32_bf16 v[110:113], v[152:155], v[184:187], v[110:113]
	v_mfma_f32_16x16x32_bf16 v[98:101], v[144:147], v[192:195], v[98:101]
	v_mfma_f32_16x16x32_bf16 v[94:97], v[152:155], v[192:195], v[94:97]
	v_mfma_f32_16x16x32_bf16 v[82:85], v[144:147], v[200:203], v[82:85]
	v_mfma_f32_16x16x32_bf16 v[78:81], v[152:155], v[200:203], v[78:81]
	v_mfma_f32_16x16x32_bf16 v[122:125], v[156:159], v[172:175], v[122:125]
	v_mfma_f32_16x16x32_bf16 v[118:121], v[164:167], v[172:175], v[118:121]
	v_mfma_f32_16x16x32_bf16 v[106:109], v[156:159], v[180:183], v[106:109]
	v_mfma_f32_16x16x32_bf16 v[102:105], v[164:167], v[180:183], v[102:105]
	v_mfma_f32_16x16x32_bf16 v[90:93], v[156:159], v[188:191], v[90:93]
	v_mfma_f32_16x16x32_bf16 v[86:89], v[164:167], v[188:191], v[86:89]
	v_mfma_f32_16x16x32_bf16 v[74:77], v[156:159], v[196:199], v[74:77]
	v_mfma_f32_16x16x32_bf16 v[70:73], v[164:167], v[196:199], v[70:73]
	v_mfma_f32_16x16x32_bf16 v[122:125], v[160:163], v[176:179], v[122:125]
	v_mfma_f32_16x16x32_bf16 v[118:121], v[168:171], v[176:179], v[118:121]
	v_mfma_f32_16x16x32_bf16 v[106:109], v[160:163], v[184:187], v[106:109]
	v_mfma_f32_16x16x32_bf16 v[102:105], v[168:171], v[184:187], v[102:105]
	v_mfma_f32_16x16x32_bf16 v[90:93], v[160:163], v[192:195], v[90:93]
	v_mfma_f32_16x16x32_bf16 v[86:89], v[168:171], v[192:195], v[86:89]
	v_mfma_f32_16x16x32_bf16 v[74:77], v[160:163], v[200:203], v[74:77]
	v_mfma_f32_16x16x32_bf16 v[70:73], v[168:171], v[200:203], v[70:73]
	s_barrier
	s_add_i32 s36, s38, s42
	v_lshl_add_u64 v[204:205], s[34:35], 0, v[134:135]
	s_mov_b32 m0, s36
	ds_read_b128 v[172:175], v5 offset:49152
	ds_read_b128 v[176:179], v5 offset:50176
	ds_read_b128 v[180:183], v5 offset:51200
	ds_read_b128 v[184:187], v5 offset:52224
	ds_read_b128 v[188:191], v5 offset:53248
	ds_read_b128 v[192:195], v5 offset:54272
	ds_read_b128 v[196:199], v5 offset:55296
	ds_read_b128 v[200:203], v5 offset:56320
	global_load_lds_dwordx4 v[204:205], off
	s_add_i32 m0, s36, 0x2000
	v_lshl_add_u64 v[204:205], s[34:35], 0, v[138:139]
	s_add_u32 s34, s34, 0x100000
	s_addc_u32 s35, s35, 0
	s_add_i32 s36, s39, s42
	global_load_lds_dwordx4 v[204:205], off
	v_lshl_add_u64 v[204:205], s[34:35], 0, v[134:135]
	s_mov_b32 m0, s36
	s_nop 0
	global_load_lds_dwordx4 v[204:205], off
	v_lshl_add_u64 v[204:205], s[34:35], 0, v[138:139]
	s_add_i32 m0, s36, 0x2000
	s_nop 0
	global_load_lds_dwordx4 v[204:205], off
	v_lshl_add_u64 v[204:205], s[30:31], 0, v[2:3]
	s_mov_b32 m0, s52
	s_nop 0
	global_load_lds_dwordx4 v[204:205], off
	v_lshl_add_u64 v[204:205], s[30:31], 0, v[136:137]
	s_mov_b32 m0, s53
	s_nop 0
	global_load_lds_dwordx4 v[204:205], off
	s_waitcnt vmcnt(8)
	s_waitcnt lgkmcnt(0)
	s_barrier
	v_mfma_f32_16x16x32_bf16 v[66:69], v[140:143], v[172:175], v[66:69]
	v_mfma_f32_16x16x32_bf16 v[62:65], v[148:151], v[172:175], v[62:65]
	v_mfma_f32_16x16x32_bf16 v[50:53], v[140:143], v[180:183], v[50:53]
	v_mfma_f32_16x16x32_bf16 v[46:49], v[148:151], v[180:183], v[46:49]
	v_mfma_f32_16x16x32_bf16 v[34:37], v[140:143], v[188:191], v[34:37]
	v_mfma_f32_16x16x32_bf16 v[30:33], v[148:151], v[188:191], v[30:33]
	v_mfma_f32_16x16x32_bf16 v[18:21], v[140:143], v[196:199], v[18:21]
	v_mfma_f32_16x16x32_bf16 v[14:17], v[148:151], v[196:199], v[14:17]
	v_mfma_f32_16x16x32_bf16 v[66:69], v[144:147], v[176:179], v[66:69]
	v_mfma_f32_16x16x32_bf16 v[62:65], v[152:155], v[176:179], v[62:65]
	v_mfma_f32_16x16x32_bf16 v[50:53], v[144:147], v[184:187], v[50:53]
	v_mfma_f32_16x16x32_bf16 v[46:49], v[152:155], v[184:187], v[46:49]
	v_mfma_f32_16x16x32_bf16 v[34:37], v[144:147], v[192:195], v[34:37]
	v_mfma_f32_16x16x32_bf16 v[30:33], v[152:155], v[192:195], v[30:33]
	v_mfma_f32_16x16x32_bf16 v[18:21], v[144:147], v[200:203], v[18:21]
	v_mfma_f32_16x16x32_bf16 v[14:17], v[152:155], v[200:203], v[14:17]
	v_mfma_f32_16x16x32_bf16 v[58:61], v[156:159], v[172:175], v[58:61]
	v_mfma_f32_16x16x32_bf16 v[54:57], v[164:167], v[172:175], v[54:57]
	v_mfma_f32_16x16x32_bf16 v[42:45], v[156:159], v[180:183], v[42:45]
	v_mfma_f32_16x16x32_bf16 v[38:41], v[164:167], v[180:183], v[38:41]
	v_mfma_f32_16x16x32_bf16 v[26:29], v[156:159], v[188:191], v[26:29]
	v_mfma_f32_16x16x32_bf16 v[22:25], v[164:167], v[188:191], v[22:25]
	v_mfma_f32_16x16x32_bf16 v[10:13], v[156:159], v[196:199], v[10:13]
	v_mfma_f32_16x16x32_bf16 v[6:9], v[164:167], v[196:199], v[6:9]
	v_mfma_f32_16x16x32_bf16 v[58:61], v[160:163], v[176:179], v[58:61]
	v_mfma_f32_16x16x32_bf16 v[54:57], v[168:171], v[176:179], v[54:57]
	v_mfma_f32_16x16x32_bf16 v[42:45], v[160:163], v[184:187], v[42:45]
	v_mfma_f32_16x16x32_bf16 v[38:41], v[168:171], v[184:187], v[38:41]
	v_mfma_f32_16x16x32_bf16 v[26:29], v[160:163], v[192:195], v[26:29]
	v_mfma_f32_16x16x32_bf16 v[22:25], v[168:171], v[192:195], v[22:25]
	v_mfma_f32_16x16x32_bf16 v[10:13], v[160:163], v[200:203], v[10:13]
	v_mfma_f32_16x16x32_bf16 v[6:9], v[168:171], v[200:203], v[6:9]
	s_barrier
	s_add_i32 s59, s59, 2
	s_add_u32 s55, s55, 0x100
	s_addc_u32 s56, s56, 0
	s_add_u32 s57, s57, 0x100
	s_addc_u32 s58, s58, 0
	s_cmp_gt_u32 s59, 61
	s_cbranch_scc0 .LBB0_131
	s_and_b64 vcc, exec, s[8:9]
	s_cbranch_vccz .LBB0_134
	s_barrier

.LBB0_251:
	s_add_u32 s56, s52, 0xffffff80
	s_addc_u32 s57, s53, -1
	s_cmp_eq_u32 s54, 60
	s_cselect_b32 s28, s2, s52
	s_cselect_b32 s29, s1, s53
	s_cselect_b32 s31, s11, s33
	s_cselect_b32 s30, s15, s19
	s_add_u32 s24, s28, 0x80
	s_addc_u32 s25, s29, 0
	s_add_u32 s26, s30, 0x80
	s_addc_u32 s27, s31, 0
	s_add_i32 s55, 0, 0x10000
	s_add_i32 s58, 0, 0x14000
	v_add_u32_e32 v152, s55, v1
	v_add_u32_e32 v168, s58, v1
	ds_read_b128 v[140:143], v152
	ds_read_b128 v[144:147], v152 offset:1024
	ds_read_b128 v[148:151], v152 offset:2048
	ds_read_b128 v[152:155], v152 offset:3072
	ds_read_b128 v[156:159], v168
	ds_read_b128 v[160:163], v168 offset:1024
	ds_read_b128 v[164:167], v168 offset:2048
	ds_read_b128 v[168:171], v168 offset:3072
	s_add_u32 s56, s56, 0x100000
	s_addc_u32 s57, s57, 0
	v_lshl_add_u64 v[204:205], s[56:57], 0, v[138:139]
	s_add_i32 m0, s23, 0xc000
	ds_read_b128 v[172:175], v5
	ds_read_b128 v[176:179], v5 offset:1024
	ds_read_b128 v[180:183], v5 offset:2048
	ds_read_b128 v[184:187], v5 offset:3072
	ds_read_b128 v[188:191], v5 offset:4096
	ds_read_b128 v[192:195], v5 offset:5120
	ds_read_b128 v[196:199], v5 offset:6144
	ds_read_b128 v[200:203], v5 offset:7168
	global_load_lds_dwordx4 v[204:205], off
	v_lshl_add_u64 v[204:205], s[56:57], 0, v[134:135]
	s_add_i32 m0, s23, 0xe000
	s_nop 0
	global_load_lds_dwordx4 v[204:205], off
	s_waitcnt vmcnt(8)
	s_waitcnt lgkmcnt(0)
	s_barrier
	v_mfma_f32_16x16x32_bf16 v[6:9], v[140:143], v[172:175], v[6:9]
	v_mfma_f32_16x16x32_bf16 v[10:13], v[148:151], v[172:175], v[10:13]
	v_mfma_f32_16x16x32_bf16 v[22:25], v[140:143], v[180:183], v[22:25]
	v_mfma_f32_16x16x32_bf16 v[26:29], v[148:151], v[180:183], v[26:29]
	v_mfma_f32_16x16x32_bf16 v[38:41], v[140:143], v[188:191], v[38:41]
	v_mfma_f32_16x16x32_bf16 v[42:45], v[148:151], v[188:191], v[42:45]
	v_mfma_f32_16x16x32_bf16 v[54:57], v[140:143], v[196:199], v[54:57]
	v_mfma_f32_16x16x32_bf16 v[58:61], v[148:151], v[196:199], v[58:61]
	v_mfma_f32_16x16x32_bf16 v[6:9], v[144:147], v[176:179], v[6:9]
	v_mfma_f32_16x16x32_bf16 v[10:13], v[152:155], v[176:179], v[10:13]
	v_mfma_f32_16x16x32_bf16 v[22:25], v[144:147], v[184:187], v[22:25]
	v_mfma_f32_16x16x32_bf16 v[26:29], v[152:155], v[184:187], v[26:29]
	v_mfma_f32_16x16x32_bf16 v[38:41], v[144:147], v[192:195], v[38:41]
	v_mfma_f32_16x16x32_bf16 v[42:45], v[152:155], v[192:195], v[42:45]
	v_mfma_f32_16x16x32_bf16 v[54:57], v[144:147], v[200:203], v[54:57]
	v_mfma_f32_16x16x32_bf16 v[58:61], v[152:155], v[200:203], v[58:61]
	v_mfma_f32_16x16x32_bf16 v[14:17], v[156:159], v[172:175], v[14:17]
	v_mfma_f32_16x16x32_bf16 v[18:21], v[164:167], v[172:175], v[18:21]
	v_mfma_f32_16x16x32_bf16 v[30:33], v[156:159], v[180:183], v[30:33]
	v_mfma_f32_16x16x32_bf16 v[34:37], v[164:167], v[180:183], v[34:37]
	v_mfma_f32_16x16x32_bf16 v[46:49], v[156:159], v[188:191], v[46:49]
	v_mfma_f32_16x16x32_bf16 v[50:53], v[164:167], v[188:191], v[50:53]
	v_mfma_f32_16x16x32_bf16 v[62:65], v[156:159], v[196:199], v[62:65]
	v_mfma_f32_16x16x32_bf16 v[66:69], v[164:167], v[196:199], v[66:69]
	v_mfma_f32_16x16x32_bf16 v[14:17], v[160:163], v[176:179], v[14:17]
	v_mfma_f32_16x16x32_bf16 v[18:21], v[168:171], v[176:179], v[18:21]
	v_mfma_f32_16x16x32_bf16 v[30:33], v[160:163], v[184:187], v[30:33]
	v_mfma_f32_16x16x32_bf16 v[34:37], v[168:171], v[184:187], v[34:37]
	v_mfma_f32_16x16x32_bf16 v[46:49], v[160:163], v[192:195], v[46:49]
	v_mfma_f32_16x16x32_bf16 v[50:53], v[168:171], v[192:195], v[50:53]
	v_mfma_f32_16x16x32_bf16 v[62:65], v[160:163], v[200:203], v[62:65]
	v_mfma_f32_16x16x32_bf16 v[66:69], v[168:171], v[200:203], v[66:69]
	s_barrier
	s_add_i32 s55, s55, s37
	v_lshl_add_u64 v[204:205], s[30:31], 0, v[136:137]
	s_mov_b32 m0, s55
	ds_read_b128 v[172:175], v5 offset:16384
	ds_read_b128 v[176:179], v5 offset:17408
	ds_read_b128 v[180:183], v5 offset:18432
	ds_read_b128 v[184:187], v5 offset:19456
	ds_read_b128 v[188:191], v5 offset:20480
	ds_read_b128 v[192:195], v5 offset:21504
	ds_read_b128 v[196:199], v5 offset:22528
	ds_read_b128 v[200:203], v5 offset:23552
	global_load_lds_dwordx4 v[204:205], off
	s_add_i32 m0, s55, 0x2000
	v_lshl_add_u64 v[204:205], s[30:31], 0, v[2:3]
	s_add_u32 s30, s30, 0x100000
	s_addc_u32 s31, s31, 0
	s_add_i32 s55, s58, s37
	global_load_lds_dwordx4 v[204:205], off
	v_lshl_add_u64 v[204:205], s[30:31], 0, v[136:137]
	s_mov_b32 m0, s55
	s_nop 0
	global_load_lds_dwordx4 v[204:205], off
	v_lshl_add_u64 v[204:205], s[30:31], 0, v[2:3]
	s_add_i32 m0, s55, 0x2000
	s_nop 0
	global_load_lds_dwordx4 v[204:205], off
	v_lshl_add_u64 v[204:205], s[28:29], 0, v[138:139]
	s_mov_b32 m0, s23
	s_nop 0
	global_load_lds_dwordx4 v[204:205], off
	v_lshl_add_u64 v[204:205], s[28:29], 0, v[134:135]
	s_mov_b32 m0, s40
	s_nop 0
	global_load_lds_dwordx4 v[204:205], off
	s_waitcnt vmcnt(8)
	s_waitcnt lgkmcnt(0)
	s_barrier
	v_mfma_f32_16x16x32_bf16 v[70:73], v[140:143], v[172:175], v[70:73]
	v_mfma_f32_16x16x32_bf16 v[74:77], v[148:151], v[172:175], v[74:77]
	v_mfma_f32_16x16x32_bf16 v[86:89], v[140:143], v[180:183], v[86:89]
	v_mfma_f32_16x16x32_bf16 v[90:93], v[148:151], v[180:183], v[90:93]
	v_mfma_f32_16x16x32_bf16 v[102:105], v[140:143], v[188:191], v[102:105]
	v_mfma_f32_16x16x32_bf16 v[106:109], v[148:151], v[188:191], v[106:109]
	v_mfma_f32_16x16x32_bf16 v[130:133], v[140:143], v[196:199], v[130:133]
	v_mfma_f32_16x16x32_bf16 v[126:129], v[148:151], v[196:199], v[126:129]
	v_mfma_f32_16x16x32_bf16 v[70:73], v[144:147], v[176:179], v[70:73]
	v_mfma_f32_16x16x32_bf16 v[74:77], v[152:155], v[176:179], v[74:77]
	v_mfma_f32_16x16x32_bf16 v[86:89], v[144:147], v[184:187], v[86:89]
	v_mfma_f32_16x16x32_bf16 v[90:93], v[152:155], v[184:187], v[90:93]
	v_mfma_f32_16x16x32_bf16 v[102:105], v[144:147], v[192:195], v[102:105]
	v_mfma_f32_16x16x32_bf16 v[106:109], v[152:155], v[192:195], v[106:109]
	v_mfma_f32_16x16x32_bf16 v[130:133], v[144:147], v[200:203], v[130:133]
	v_mfma_f32_16x16x32_bf16 v[126:129], v[152:155], v[200:203], v[126:129]
	v_mfma_f32_16x16x32_bf16 v[78:81], v[156:159], v[172:175], v[78:81]
	v_mfma_f32_16x16x32_bf16 v[82:85], v[164:167], v[172:175], v[82:85]
	v_mfma_f32_16x16x32_bf16 v[94:97], v[156:159], v[180:183], v[94:97]
	v_mfma_f32_16x16x32_bf16 v[98:101], v[164:167], v[180:183], v[98:101]
	v_mfma_f32_16x16x32_bf16 v[110:113], v[156:159], v[188:191], v[110:113]
	v_mfma_f32_16x16x32_bf16 v[114:117], v[164:167], v[188:191], v[114:117]
	v_mfma_f32_16x16x32_bf16 v[122:125], v[156:159], v[196:199], v[122:125]
	v_mfma_f32_16x16x32_bf16 v[118:121], v[164:167], v[196:199], v[118:121]
	v_mfma_f32_16x16x32_bf16 v[78:81], v[160:163], v[176:179], v[78:81]
	v_mfma_f32_16x16x32_bf16 v[82:85], v[168:171], v[176:179], v[82:85]
	v_mfma_f32_16x16x32_bf16 v[94:97], v[160:163], v[184:187], v[94:97]
	v_mfma_f32_16x16x32_bf16 v[98:101], v[168:171], v[184:187], v[98:101]
	v_mfma_f32_16x16x32_bf16 v[110:113], v[160:163], v[192:195], v[110:113]
	v_mfma_f32_16x16x32_bf16 v[114:117], v[168:171], v[192:195], v[114:117]
	v_mfma_f32_16x16x32_bf16 v[122:125], v[160:163], v[200:203], v[122:125]
	v_mfma_f32_16x16x32_bf16 v[118:121], v[168:171], v[200:203], v[118:121]
	s_barrier
	s_add_i32 s30, 0, 0x18000
	s_add_i32 s31, 0, 0x1c000
	v_add_u32_e32 v152, s30, v1
	v_add_u32_e32 v168, s31, v1
	ds_read_b128 v[140:143], v152
	ds_read_b128 v[144:147], v152 offset:1024
	ds_read_b128 v[148:151], v152 offset:2048
	ds_read_b128 v[152:155], v152 offset:3072
	ds_read_b128 v[156:159], v168
	ds_read_b128 v[160:163], v168 offset:1024
	ds_read_b128 v[164:167], v168 offset:2048
	ds_read_b128 v[168:171], v168 offset:3072
	s_add_u32 s28, s28, 0x100000
	s_addc_u32 s29, s29, 0
	s_mov_b32 m0, s41
	v_lshl_add_u64 v[204:205], s[28:29], 0, v[138:139]
	ds_read_b128 v[172:175], v5 offset:32768
	ds_read_b128 v[176:179], v5 offset:33792
	ds_read_b128 v[180:183], v5 offset:34816
	ds_read_b128 v[184:187], v5 offset:35840
	ds_read_b128 v[188:191], v5 offset:36864
	ds_read_b128 v[192:195], v5 offset:37888
	ds_read_b128 v[196:199], v5 offset:38912
	ds_read_b128 v[200:203], v5 offset:39936
	global_load_lds_dwordx4 v[204:205], off
	v_lshl_add_u64 v[204:205], s[28:29], 0, v[134:135]
	s_mov_b32 m0, s42
	s_nop 0
	global_load_lds_dwordx4 v[204:205], off
	s_waitcnt vmcnt(8)
	s_waitcnt lgkmcnt(0)
	s_barrier
	v_mfma_f32_16x16x32_bf16 v[6:9], v[140:143], v[172:175], v[6:9]
	v_mfma_f32_16x16x32_bf16 v[10:13], v[148:151], v[172:175], v[10:13]
	v_mfma_f32_16x16x32_bf16 v[22:25], v[140:143], v[180:183], v[22:25]
	v_mfma_f32_16x16x32_bf16 v[26:29], v[148:151], v[180:183], v[26:29]
	v_mfma_f32_16x16x32_bf16 v[38:41], v[140:143], v[188:191], v[38:41]
	v_mfma_f32_16x16x32_bf16 v[42:45], v[148:151], v[188:191], v[42:45]
	v_mfma_f32_16x16x32_bf16 v[54:57], v[140:143], v[196:199], v[54:57]
	v_mfma_f32_16x16x32_bf16 v[58:61], v[148:151], v[196:199], v[58:61]
	v_mfma_f32_16x16x32_bf16 v[6:9], v[144:147], v[176:179], v[6:9]
	v_mfma_f32_16x16x32_bf16 v[10:13], v[152:155], v[176:179], v[10:13]
	v_mfma_f32_16x16x32_bf16 v[22:25], v[144:147], v[184:187], v[22:25]
	v_mfma_f32_16x16x32_bf16 v[26:29], v[152:155], v[184:187], v[26:29]
	v_mfma_f32_16x16x32_bf16 v[38:41], v[144:147], v[192:195], v[38:41]
	v_mfma_f32_16x16x32_bf16 v[42:45], v[152:155], v[192:195], v[42:45]
	v_mfma_f32_16x16x32_bf16 v[54:57], v[144:147], v[200:203], v[54:57]
	v_mfma_f32_16x16x32_bf16 v[58:61], v[152:155], v[200:203], v[58:61]
	v_mfma_f32_16x16x32_bf16 v[14:17], v[156:159], v[172:175], v[14:17]
	v_mfma_f32_16x16x32_bf16 v[18:21], v[164:167], v[172:175], v[18:21]
	v_mfma_f32_16x16x32_bf16 v[30:33], v[156:159], v[180:183], v[30:33]
	v_mfma_f32_16x16x32_bf16 v[34:37], v[164:167], v[180:183], v[34:37]
	v_mfma_f32_16x16x32_bf16 v[46:49], v[156:159], v[188:191], v[46:49]
	v_mfma_f32_16x16x32_bf16 v[50:53], v[164:167], v[188:191], v[50:53]
	v_mfma_f32_16x16x32_bf16 v[62:65], v[156:159], v[196:199], v[62:65]
	v_mfma_f32_16x16x32_bf16 v[66:69], v[164:167], v[196:199], v[66:69]
	v_mfma_f32_16x16x32_bf16 v[14:17], v[160:163], v[176:179], v[14:17]
	v_mfma_f32_16x16x32_bf16 v[18:21], v[168:171], v[176:179], v[18:21]
	v_mfma_f32_16x16x32_bf16 v[30:33], v[160:163], v[184:187], v[30:33]
	v_mfma_f32_16x16x32_bf16 v[34:37], v[168:171], v[184:187], v[34:37]
	v_mfma_f32_16x16x32_bf16 v[46:49], v[160:163], v[192:195], v[46:49]
	v_mfma_f32_16x16x32_bf16 v[50:53], v[168:171], v[192:195], v[50:53]
	v_mfma_f32_16x16x32_bf16 v[62:65], v[160:163], v[200:203], v[62:65]
	v_mfma_f32_16x16x32_bf16 v[66:69], v[168:171], v[200:203], v[66:69]
	s_barrier
	s_add_i32 s28, s30, s37
	v_lshl_add_u64 v[204:205], s[26:27], 0, v[136:137]
	s_mov_b32 m0, s28
	ds_read_b128 v[172:175], v5 offset:49152
	ds_read_b128 v[176:179], v5 offset:50176
	ds_read_b128 v[180:183], v5 offset:51200
	ds_read_b128 v[184:187], v5 offset:52224
	ds_read_b128 v[188:191], v5 offset:53248
	ds_read_b128 v[192:195], v5 offset:54272
	ds_read_b128 v[196:199], v5 offset:55296
	ds_read_b128 v[200:203], v5 offset:56320
	global_load_lds_dwordx4 v[204:205], off
	s_add_i32 m0, s28, 0x2000
	v_lshl_add_u64 v[204:205], s[26:27], 0, v[2:3]
	s_add_u32 s26, s26, 0x100000
	s_addc_u32 s27, s27, 0
	s_add_i32 s28, s31, s37
	global_load_lds_dwordx4 v[204:205], off
	v_lshl_add_u64 v[204:205], s[26:27], 0, v[136:137]
	s_mov_b32 m0, s28
	s_nop 0
	global_load_lds_dwordx4 v[204:205], off
	v_lshl_add_u64 v[204:205], s[26:27], 0, v[2:3]
	s_add_i32 m0, s28, 0x2000
	s_nop 0
	global_load_lds_dwordx4 v[204:205], off
	v_lshl_add_u64 v[204:205], s[24:25], 0, v[138:139]
	s_mov_b32 m0, s49
	s_nop 0
	global_load_lds_dwordx4 v[204:205], off
	v_lshl_add_u64 v[204:205], s[24:25], 0, v[134:135]
	s_mov_b32 m0, s50
	s_nop 0
	global_load_lds_dwordx4 v[204:205], off
	s_waitcnt vmcnt(8)
	s_waitcnt lgkmcnt(0)
	s_barrier
	v_mfma_f32_16x16x32_bf16 v[70:73], v[140:143], v[172:175], v[70:73]
	v_mfma_f32_16x16x32_bf16 v[74:77], v[148:151], v[172:175], v[74:77]
	v_mfma_f32_16x16x32_bf16 v[86:89], v[140:143], v[180:183], v[86:89]
	v_mfma_f32_16x16x32_bf16 v[90:93], v[148:151], v[180:183], v[90:93]
	v_mfma_f32_16x16x32_bf16 v[102:105], v[140:143], v[188:191], v[102:105]
	v_mfma_f32_16x16x32_bf16 v[106:109], v[148:151], v[188:191], v[106:109]
	v_mfma_f32_16x16x32_bf16 v[130:133], v[140:143], v[196:199], v[130:133]
	v_mfma_f32_16x16x32_bf16 v[126:129], v[148:151], v[196:199], v[126:129]
	v_mfma_f32_16x16x32_bf16 v[70:73], v[144:147], v[176:179], v[70:73]
	v_mfma_f32_16x16x32_bf16 v[74:77], v[152:155], v[176:179], v[74:77]
	v_mfma_f32_16x16x32_bf16 v[86:89], v[144:147], v[184:187], v[86:89]
	v_mfma_f32_16x16x32_bf16 v[90:93], v[152:155], v[184:187], v[90:93]
	v_mfma_f32_16x16x32_bf16 v[102:105], v[144:147], v[192:195], v[102:105]
	v_mfma_f32_16x16x32_bf16 v[106:109], v[152:155], v[192:195], v[106:109]
	v_mfma_f32_16x16x32_bf16 v[130:133], v[144:147], v[200:203], v[130:133]
	v_mfma_f32_16x16x32_bf16 v[126:129], v[152:155], v[200:203], v[126:129]
	v_mfma_f32_16x16x32_bf16 v[78:81], v[156:159], v[172:175], v[78:81]
	v_mfma_f32_16x16x32_bf16 v[82:85], v[164:167], v[172:175], v[82:85]
	v_mfma_f32_16x16x32_bf16 v[94:97], v[156:159], v[180:183], v[94:97]
	v_mfma_f32_16x16x32_bf16 v[98:101], v[164:167], v[180:183], v[98:101]
	v_mfma_f32_16x16x32_bf16 v[110:113], v[156:159], v[188:191], v[110:113]
	v_mfma_f32_16x16x32_bf16 v[114:117], v[164:167], v[188:191], v[114:117]
	v_mfma_f32_16x16x32_bf16 v[122:125], v[156:159], v[196:199], v[122:125]
	v_mfma_f32_16x16x32_bf16 v[118:121], v[164:167], v[196:199], v[118:121]
	v_mfma_f32_16x16x32_bf16 v[78:81], v[160:163], v[176:179], v[78:81]
	v_mfma_f32_16x16x32_bf16 v[82:85], v[168:171], v[176:179], v[82:85]
	v_mfma_f32_16x16x32_bf16 v[94:97], v[160:163], v[184:187], v[94:97]
	v_mfma_f32_16x16x32_bf16 v[98:101], v[168:171], v[184:187], v[98:101]
	v_mfma_f32_16x16x32_bf16 v[110:113], v[160:163], v[192:195], v[110:113]
	v_mfma_f32_16x16x32_bf16 v[114:117], v[168:171], v[192:195], v[114:117]
	v_mfma_f32_16x16x32_bf16 v[122:125], v[160:163], v[200:203], v[122:125]
	v_mfma_f32_16x16x32_bf16 v[118:121], v[168:171], v[200:203], v[118:121]
	s_barrier
	s_add_i32 s54, s54, 2
	s_add_u32 s19, s19, 0x100
	s_addc_u32 s33, s33, 0
	s_add_u32 s52, s52, 0x100
	s_addc_u32 s53, s53, 0
	s_cmp_gt_u32 s54, 61
	s_cbranch_scc0 .LBB0_251
	v_mov_b32_e32 v141, v0
	s_lshl_b32 s1, s0, 8
	s_mov_b64 s[24:25], s[84:85]
	s_add_i32 s1, s1, s43
	v_and_or_b32 v140, v141, 15, s1
	v_lshrrev_b32_e32 v141, 1, v141
	s_add_u32 s26, s24, s6
	v_and_or_b32 v148, v141, 24, s48
	s_addc_u32 s27, s25, s7
	v_ashrrev_i32_e32 v141, 31, v140
	v_lshl_add_u64 v[142:143], v[140:141], 2, s[26:27]
	s_mov_b64 s[26:27], 0x10000
	v_lshl_add_u64 v[144:145], v[142:143], 0, s[26:27]
	v_add_co_u32_e32 v142, vcc, s91, v142
	global_load_dword v146, v[144:145], off offset:512
	s_nop 0
	v_addc_co_u32_e32 v143, vcc, 0, v143, vcc
	global_load_dword v142, v[142:143], off
	s_cmp_lt_i32 s22, 8
	s_mov_b64 s[26:27], -1
	global_load_dword v205, v[144:145], off offset:64
	global_load_dword v204, v[144:145], off offset:128
	global_load_dword v203, v[144:145], off offset:192
	global_load_dword v202, v[144:145], off offset:576
	global_load_dword v201, v[144:145], off offset:640
	global_load_dword v200, v[144:145], off offset:704
	s_waitcnt vmcnt(0)
	v_fmamk_f32 v146, v146, 0x39800000, v246
	v_mul_f32_e32 v147, 0x4b800000, v146
	v_fmamk_f32 v142, v142, 0x39800000, v246
	v_cmp_gt_f32_e32 vcc, s95, v142
	v_mul_f32_e32 v143, 0x4b800000, v142
	s_nop 0
	v_cndmask_b32_e32 v142, v142, v143, vcc
	v_rsq_f32_e32 v142, v142
	s_nop 0
	v_mul_f32_e32 v143, 0x45800000, v142
	v_cndmask_b32_e32 v142, v142, v143, vcc
	v_pk_mul_f32 v[8:9], v[8:9], v[142:143] op_sel_hi:[1,0]
	v_pk_mul_f32 v[6:7], v[6:7], v[142:143] op_sel_hi:[1,0]
	v_pk_mul_f32 v[12:13], v[12:13], v[142:143] op_sel_hi:[1,0]
	v_pk_mul_f32 v[10:11], v[10:11], v[142:143] op_sel_hi:[1,0]
	v_pk_mul_f32 v[16:17], v[16:17], v[142:143] op_sel_hi:[1,0]
	v_pk_mul_f32 v[14:15], v[14:15], v[142:143] op_sel_hi:[1,0]
	v_pk_mul_f32 v[20:21], v[20:21], v[142:143] op_sel_hi:[1,0]
	v_pk_mul_f32 v[18:19], v[18:19], v[142:143] op_sel_hi:[1,0]
	s_waitcnt vmcnt(0)
	v_fmamk_f32 v142, v205, 0x39800000, v246
	v_cmp_gt_f32_e32 vcc, s95, v142
	v_mul_f32_e32 v143, 0x4b800000, v142
	s_nop 0
	v_cndmask_b32_e32 v142, v142, v143, vcc
	v_rsq_f32_e32 v142, v142
	s_nop 0
	v_mul_f32_e32 v143, 0x45800000, v142
	v_cndmask_b32_e32 v142, v142, v143, vcc
	v_pk_mul_f32 v[24:25], v[24:25], v[142:143] op_sel_hi:[1,0]
	v_pk_mul_f32 v[22:23], v[22:23], v[142:143] op_sel_hi:[1,0]
	v_pk_mul_f32 v[28:29], v[28:29], v[142:143] op_sel_hi:[1,0]
	v_pk_mul_f32 v[26:27], v[26:27], v[142:143] op_sel_hi:[1,0]
	v_pk_mul_f32 v[32:33], v[32:33], v[142:143] op_sel_hi:[1,0]
	v_pk_mul_f32 v[30:31], v[30:31], v[142:143] op_sel_hi:[1,0]
	v_pk_mul_f32 v[36:37], v[36:37], v[142:143] op_sel_hi:[1,0]
	v_pk_mul_f32 v[34:35], v[34:35], v[142:143] op_sel_hi:[1,0]
	s_waitcnt vmcnt(0)
	v_fmamk_f32 v142, v204, 0x39800000, v246
	v_cmp_gt_f32_e32 vcc, s95, v142
	v_mul_f32_e32 v143, 0x4b800000, v142
	s_nop 0
	v_cndmask_b32_e32 v142, v142, v143, vcc
	v_rsq_f32_e32 v142, v142
	s_nop 0
	v_mul_f32_e32 v143, 0x45800000, v142
	v_cndmask_b32_e32 v142, v142, v143, vcc
	v_pk_mul_f32 v[40:41], v[40:41], v[142:143] op_sel_hi:[1,0]
	v_pk_mul_f32 v[38:39], v[38:39], v[142:143] op_sel_hi:[1,0]
	v_pk_mul_f32 v[44:45], v[44:45], v[142:143] op_sel_hi:[1,0]
	v_pk_mul_f32 v[42:43], v[42:43], v[142:143] op_sel_hi:[1,0]
	v_pk_mul_f32 v[48:49], v[48:49], v[142:143] op_sel_hi:[1,0]
	v_pk_mul_f32 v[46:47], v[46:47], v[142:143] op_sel_hi:[1,0]
	v_pk_mul_f32 v[52:53], v[52:53], v[142:143] op_sel_hi:[1,0]
	v_pk_mul_f32 v[50:51], v[50:51], v[142:143] op_sel_hi:[1,0]
	s_waitcnt vmcnt(0)
	v_fmamk_f32 v142, v203, 0x39800000, v246
	v_cmp_gt_f32_e32 vcc, s95, v142
	v_mul_f32_e32 v143, 0x4b800000, v142
	s_nop 0
	v_cndmask_b32_e32 v142, v142, v143, vcc
	v_rsq_f32_e32 v142, v142
	s_nop 0
	v_mul_f32_e32 v143, 0x45800000, v142
	v_cndmask_b32_e32 v142, v142, v143, vcc
	v_cmp_gt_f32_e32 vcc, s95, v146
	v_pk_mul_f32 v[56:57], v[56:57], v[142:143] op_sel_hi:[1,0]
	v_pk_mul_f32 v[54:55], v[54:55], v[142:143] op_sel_hi:[1,0]
	v_cndmask_b32_e32 v146, v146, v147, vcc
	v_rsq_f32_e32 v146, v146
	v_pk_mul_f32 v[60:61], v[60:61], v[142:143] op_sel_hi:[1,0]
	v_pk_mul_f32 v[58:59], v[58:59], v[142:143] op_sel_hi:[1,0]
	v_pk_mul_f32 v[64:65], v[64:65], v[142:143] op_sel_hi:[1,0]
	v_mul_f32_e32 v147, 0x45800000, v146
	v_cndmask_b32_e32 v146, v146, v147, vcc
	v_pk_mul_f32 v[72:73], v[72:73], v[146:147] op_sel_hi:[1,0]
	v_pk_mul_f32 v[70:71], v[70:71], v[146:147] op_sel_hi:[1,0]
	v_pk_mul_f32 v[76:77], v[76:77], v[146:147] op_sel_hi:[1,0]
	v_pk_mul_f32 v[74:75], v[74:75], v[146:147] op_sel_hi:[1,0]
	v_pk_mul_f32 v[80:81], v[80:81], v[146:147] op_sel_hi:[1,0]
	v_pk_mul_f32 v[78:79], v[78:79], v[146:147] op_sel_hi:[1,0]
	v_pk_mul_f32 v[84:85], v[84:85], v[146:147] op_sel_hi:[1,0]
	v_pk_mul_f32 v[82:83], v[82:83], v[146:147] op_sel_hi:[1,0]
	v_pk_mul_f32 v[62:63], v[62:63], v[142:143] op_sel_hi:[1,0]
	v_pk_mul_f32 v[68:69], v[68:69], v[142:143] op_sel_hi:[1,0]
	v_pk_mul_f32 v[66:67], v[66:67], v[142:143] op_sel_hi:[1,0]
	v_add_u32_e32 v142, 0x80, v140
	v_ashrrev_i32_e32 v143, 31, v142
	s_waitcnt vmcnt(0)
	v_fmamk_f32 v146, v202, 0x39800000, v246
	v_cmp_gt_f32_e32 vcc, s95, v146
	v_mul_f32_e32 v147, 0x4b800000, v146
	s_nop 0
	v_cndmask_b32_e32 v146, v146, v147, vcc
	v_rsq_f32_e32 v146, v146
	s_nop 0
	v_mul_f32_e32 v147, 0x45800000, v146
	v_cndmask_b32_e32 v146, v146, v147, vcc
	v_pk_mul_f32 v[88:89], v[88:89], v[146:147] op_sel_hi:[1,0]
	v_pk_mul_f32 v[86:87], v[86:87], v[146:147] op_sel_hi:[1,0]
	v_pk_mul_f32 v[92:93], v[92:93], v[146:147] op_sel_hi:[1,0]
	v_pk_mul_f32 v[90:91], v[90:91], v[146:147] op_sel_hi:[1,0]
	v_pk_mul_f32 v[96:97], v[96:97], v[146:147] op_sel_hi:[1,0]
	v_pk_mul_f32 v[94:95], v[94:95], v[146:147] op_sel_hi:[1,0]
	v_pk_mul_f32 v[100:101], v[100:101], v[146:147] op_sel_hi:[1,0]
	v_pk_mul_f32 v[98:99], v[98:99], v[146:147] op_sel_hi:[1,0]
	s_waitcnt vmcnt(0)
	v_fmamk_f32 v146, v201, 0x39800000, v246
	v_cmp_gt_f32_e32 vcc, s95, v146
	v_mul_f32_e32 v147, 0x4b800000, v146
	s_waitcnt vmcnt(0)
	v_fmamk_f32 v144, v200, 0x39800000, v246
	v_cndmask_b32_e32 v146, v146, v147, vcc
	v_rsq_f32_e32 v146, v146
	v_mul_f32_e32 v145, 0x4b800000, v144
	v_mul_f32_e32 v147, 0x45800000, v146
	v_cndmask_b32_e32 v146, v146, v147, vcc
	v_cmp_gt_f32_e32 vcc, s95, v144
	v_pk_mul_f32 v[104:105], v[104:105], v[146:147] op_sel_hi:[1,0]
	v_pk_mul_f32 v[102:103], v[102:103], v[146:147] op_sel_hi:[1,0]
	v_cndmask_b32_e32 v144, v144, v145, vcc
	v_rsq_f32_e32 v144, v144
	v_pk_mul_f32 v[108:109], v[108:109], v[146:147] op_sel_hi:[1,0]
	v_pk_mul_f32 v[106:107], v[106:107], v[146:147] op_sel_hi:[1,0]
	v_pk_mul_f32 v[112:113], v[112:113], v[146:147] op_sel_hi:[1,0]
	v_mul_f32_e32 v145, 0x45800000, v144
	v_cndmask_b32_e32 v144, v144, v145, vcc
	v_pk_mul_f32 v[110:111], v[110:111], v[146:147] op_sel_hi:[1,0]
	v_pk_mul_f32 v[116:117], v[116:117], v[146:147] op_sel_hi:[1,0]
	v_pk_mul_f32 v[114:115], v[114:115], v[146:147] op_sel_hi:[1,0]
	v_pk_mul_f32 v[132:133], v[132:133], v[144:145] op_sel_hi:[1,0]
	v_pk_mul_f32 v[130:131], v[130:131], v[144:145] op_sel_hi:[1,0]
	v_pk_mul_f32 v[128:129], v[128:129], v[144:145] op_sel_hi:[1,0]
	v_pk_mul_f32 v[126:127], v[126:127], v[144:145] op_sel_hi:[1,0]
	v_pk_mul_f32 v[124:125], v[124:125], v[144:145] op_sel_hi:[1,0]
	v_pk_mul_f32 v[122:123], v[122:123], v[144:145] op_sel_hi:[1,0]
	v_pk_mul_f32 v[120:121], v[120:121], v[144:145] op_sel_hi:[1,0]
	v_pk_mul_f32 v[118:119], v[118:119], v[144:145] op_sel_hi:[1,0]
	s_cbranch_scc1 .LBB0_254
	v_mul_f32_e32 v145, 0xbfb8aa3b, v7
	v_mul_f32_e32 v146, 0xbfb8aa3b, v8
	v_exp_f32_e32 v145, v145
	v_exp_f32_e32 v146, v146
	v_mul_f32_e32 v144, 0xbfb8aa3b, v6
	v_exp_f32_e32 v144, v144
	v_add_f32_e32 v145, 1.0, v145
	v_add_f32_e32 v146, 1.0, v146
	v_rcp_f32_e32 v145, v145
	v_rcp_f32_e32 v149, v146
	v_add_f32_e32 v144, 1.0, v144
	v_mul_f32_e32 v146, 0xbfb8aa3b, v9
	v_mul_f32_e32 v147, v7, v145
	v_mul_f32_e32 v195, v8, v149
	v_mul_f32_e32 v145, 0xbfb8aa3b, v10
	v_mul_f32_e32 v149, 0xbfb8aa3b, v11
	v_rcp_f32_e32 v144, v144
	v_exp_f32_e32 v150, v146
	v_exp_f32_e32 v145, v145
	v_exp_f32_e32 v149, v149
	v_mul_f32_e32 v146, v6, v144
	v_add_f32_e32 v144, 1.0, v150
	v_add_f32_e32 v145, 1.0, v145
	v_add_f32_e32 v149, 1.0, v149
	v_mul_f32_e32 v150, 0xbfb8aa3b, v12
	v_rcp_f32_e32 v144, v144
	v_rcp_f32_e32 v145, v145
	v_rcp_f32_e32 v149, v149
	v_exp_f32_e32 v150, v150
	v_mul_f32_e32 v209, v9, v144
	v_mul_f32_e32 v144, v10, v145
	v_mul_f32_e32 v145, v11, v149
	v_add_f32_e32 v149, 1.0, v150
	v_mul_f32_e32 v150, 0xbfb8aa3b, v13
	v_exp_f32_e32 v150, v150
	v_mul_f32_e32 v151, 0xbfb8aa3b, v14
	v_exp_f32_e32 v151, v151
	v_mul_f32_e32 v240, 0xbfb8aa3b, v99
	v_add_f32_e32 v150, 1.0, v150
	v_rcp_f32_e32 v150, v150
	v_add_f32_e32 v151, 1.0, v151
	v_rcp_f32_e32 v151, v151
	v_exp_f32_e32 v240, v240
	v_mul_f32_e32 v206, v13, v150
	v_mul_f32_e32 v150, 0xbfb8aa3b, v16
	v_mul_f32_e32 v194, v14, v151
	v_exp_f32_e32 v150, v150
	v_mul_f32_e32 v151, 0xbfb8aa3b, v17
	v_exp_f32_e32 v151, v151
	v_mul_f32_e32 v152, 0xbfb8aa3b, v15
	v_rcp_f32_e32 v149, v149
	v_exp_f32_e32 v152, v152
	v_add_f32_e32 v150, 1.0, v150
	v_rcp_f32_e32 v150, v150
	v_add_f32_e32 v151, 1.0, v151
	v_add_f32_e32 v242, 1.0, v240
	v_cvt_pk_bf16_f32 v240, v146, v147
	v_mul_f32_e32 v146, 0xbfb8aa3b, v100
	v_rcp_f32_e32 v151, v151
	v_exp_f32_e32 v146, v146
	v_mul_f32_e32 v147, 0xbfb8aa3b, v101
	v_exp_f32_e32 v147, v147
	v_mul_f32_e32 v205, v12, v149
	v_add_f32_e32 v149, 1.0, v152
	v_mul_f32_e32 v152, 0xbfb8aa3b, v18
	s_lshl_b32 s1, s22, 8
	v_rcp_f32_e32 v149, v149
	v_exp_f32_e32 v152, v152
	v_mul_f32_e32 v203, v16, v150
	v_mul_f32_e32 v150, 0xbfb8aa3b, v19
	v_cvt_pk_bf16_f32 v241, v195, v209
	v_rcp_f32_e32 v195, v242
	s_addk_i32 s1, 0xf800
	v_cvt_pk_bf16_f32 v242, v144, v145
	v_cvt_pk_bf16_f32 v243, v205, v206
	v_mul_f32_e32 v205, 0xbfb8aa3b, v102
	v_mul_f32_e32 v204, v17, v151
	v_exp_f32_e32 v150, v150
	v_mul_f32_e32 v151, 0xbfb8aa3b, v20
	v_add_f32_e32 v146, 1.0, v146
	v_or_b32_e32 v144, s1, v148
	v_mov_b32_e32 v145, v4
	v_exp_f32_e32 v205, v205
	v_exp_f32_e32 v151, v151
	v_rcp_f32_e32 v209, v146
	v_add_f32_e32 v146, 1.0, v147
	v_lshl_add_u64 v[144:145], v[144:145], 1, s[24:25]
	s_mov_b64 s[26:27], 0x1b480000
	v_rcp_f32_e32 v244, v146
	v_lshl_add_u64 v[146:147], v[144:145], 0, s[26:27]
	v_lshlrev_b64 v[144:145], 13, v[140:141]
	v_mul_f32_e32 v202, v15, v149
	v_add_f32_e32 v149, 1.0, v152
	v_lshl_add_u64 v[144:145], v[146:147], 0, v[144:145]
	v_rcp_f32_e32 v149, v149
	v_add_f32_e32 v150, 1.0, v150
	global_store_dwordx4 v[144:145], v[240:243], off nt
	v_add_f32_e32 v205, 1.0, v205
	v_rcp_f32_e32 v150, v150
	v_mul_f32_e32 v240, 0xbfb8aa3b, v103
	v_add_f32_e32 v151, 1.0, v151
	v_exp_f32_e32 v240, v240
	v_cvt_pk_bf16_f32 v202, v194, v202
	v_cvt_pk_bf16_f32 v203, v203, v204
	v_rcp_f32_e32 v204, v205
	v_rcp_f32_e32 v151, v151
	v_mul_f32_e32 v152, 0xbfb8aa3b, v21
	v_mul_f32_e32 v200, v18, v149
	v_exp_f32_e32 v152, v152
	v_mul_f32_e32 v201, v19, v150
	v_add_f32_e32 v205, 1.0, v240
	v_mul_f32_e32 v240, 0xbfb8aa3b, v105
	v_mul_f32_e32 v241, v102, v204
	v_cvt_pk_bf16_f32 v204, v200, v201
	v_mul_f32_e32 v200, 0xbfb8aa3b, v106
	v_mul_f32_e32 v192, v20, v151
	v_mul_f32_e32 v151, 0xbfb8aa3b, v23
	v_rcp_f32_e32 v205, v205
	v_exp_f32_e32 v240, v240
	v_exp_f32_e32 v200, v200
	v_exp_f32_e32 v151, v151
	v_mul_f32_e32 v150, 0xbfb8aa3b, v22
	v_add_f32_e32 v149, 1.0, v152
	v_exp_f32_e32 v150, v150
	v_rcp_f32_e32 v149, v149
	v_mul_f32_e32 v242, v103, v205
	v_add_f32_e32 v205, 1.0, v240
	v_mul_f32_e32 v201, 0xbfb8aa3b, v107
	v_add_f32_e32 v200, 1.0, v200
	v_add_f32_e32 v151, 1.0, v151
	v_exp_f32_e32 v201, v201
	v_rcp_f32_e32 v240, v205
	v_rcp_f32_e32 v200, v200
	v_rcp_f32_e32 v151, v151
	v_add_f32_e32 v150, 1.0, v150
	v_rcp_f32_e32 v150, v150
	v_mul_f32_e32 v197, v21, v149
	v_mul_f32_e32 v152, 0xbfb8aa3b, v24
	v_add_f32_e32 v201, 1.0, v201
	v_cvt_pk_bf16_f32 v205, v192, v197
	v_mul_f32_e32 v197, v105, v240
	v_mul_f32_e32 v240, v106, v200
	v_mul_f32_e32 v200, 0xbfb8aa3b, v109
	v_exp_f32_e32 v152, v152
	v_mul_f32_e32 v181, v23, v151
	v_mul_f32_e32 v151, 0xbfb8aa3b, v26
	v_rcp_f32_e32 v201, v201
	v_exp_f32_e32 v200, v200
	v_exp_f32_e32 v151, v151
	v_mul_f32_e32 v179, v22, v150
	v_mul_f32_e32 v150, 0xbfb8aa3b, v25
	v_exp_f32_e32 v150, v150
	v_add_f32_e32 v149, 1.0, v152
	v_mul_f32_e32 v152, 0xbfb8aa3b, v27
	v_mul_f32_e32 v243, v107, v201
	v_mul_f32_e32 v201, 0xbfb8aa3b, v110
	v_add_f32_e32 v200, 1.0, v200
	v_rcp_f32_e32 v149, v149
	v_add_f32_e32 v151, 1.0, v151
	v_exp_f32_e32 v152, v152
	v_exp_f32_e32 v201, v201
	v_rcp_f32_e32 v200, v200
	v_rcp_f32_e32 v151, v151
	v_add_f32_e32 v150, 1.0, v150
	v_rcp_f32_e32 v150, v150
	global_store_dwordx4 v[144:145], v[202:205], off offset:256 nt
	v_mul_f32_e32 v188, v24, v149
	v_add_f32_e32 v149, 1.0, v152
	v_mul_f32_e32 v202, 0xbfb8aa3b, v111
	v_add_f32_e32 v201, 1.0, v201
	v_exp_f32_e32 v202, v202
	v_mul_f32_e32 v204, v109, v200
	v_cvt_pk_bf16_f32 v200, v179, v181
	v_mul_f32_e32 v181, 0xbfb8aa3b, v113
	v_mul_f32_e32 v178, v26, v151
	v_mul_f32_e32 v151, 0xbfb8aa3b, v29
	v_rcp_f32_e32 v149, v149
	v_rcp_f32_e32 v201, v201
	v_exp_f32_e32 v181, v181
	v_exp_f32_e32 v151, v151
	v_mul_f32_e32 v179, 0xbfb8aa3b, v112
	v_mul_f32_e32 v189, v25, v150
	v_mul_f32_e32 v150, 0xbfb8aa3b, v28
	v_exp_f32_e32 v179, v179
	v_exp_f32_e32 v150, v150
	v_add_f32_e32 v202, 1.0, v202
	v_mul_f32_e32 v187, v27, v149
	v_mul_f32_e32 v205, v110, v201
	v_cvt_pk_bf16_f32 v201, v188, v189
	v_rcp_f32_e32 v188, v202
	v_add_f32_e32 v181, 1.0, v181
	v_cvt_pk_bf16_f32 v202, v178, v187
	v_mul_f32_e32 v178, 0xbfb8aa3b, v114
	v_add_f32_e32 v151, 1.0, v151
	v_rcp_f32_e32 v181, v181
	v_exp_f32_e32 v178, v178
	v_rcp_f32_e32 v151, v151
	v_add_f32_e32 v179, 1.0, v179
	v_add_f32_e32 v150, 1.0, v150
	v_rcp_f32_e32 v179, v179
	v_rcp_f32_e32 v150, v150
	v_mul_f32_e32 v245, v113, v181
	v_add_f32_e32 v181, 1.0, v178
	v_mul_f32_e32 v178, 0xbfb8aa3b, v115
	v_mul_f32_e32 v182, v29, v151
	v_mul_f32_e32 v151, 0xbfb8aa3b, v32
	v_exp_f32_e32 v248, v178
	v_or_b32_e32 v178, 16, v140
	v_exp_f32_e32 v151, v151
	v_mul_f32_e32 v206, v100, v209
	v_mul_f32_e32 v209, v101, v244
	v_mul_f32_e32 v244, v112, v179
	v_ashrrev_i32_e32 v179, 31, v178
	v_mul_f32_e32 v152, 0xbfb8aa3b, v30
	v_mul_f32_e32 v180, v28, v150
	v_mul_f32_e32 v150, 0xbfb8aa3b, v31
	v_lshlrev_b64 v[178:179], 13, v[178:179]
	v_exp_f32_e32 v152, v152
	v_exp_f32_e32 v150, v150
	v_mul_f32_e32 v187, v111, v188
	v_lshl_add_u64 v[188:189], v[146:147], 0, v[178:179]
	v_mul_f32_e32 v178, 0xbfb8aa3b, v116
	v_exp_f32_e32 v178, v178
	v_add_f32_e32 v151, 1.0, v151
	v_rcp_f32_e32 v151, v151
	v_add_f32_e32 v149, 1.0, v152
	v_add_f32_e32 v150, 1.0, v150
	v_rcp_f32_e32 v149, v149
	v_rcp_f32_e32 v150, v150
	v_add_f32_e32 v178, 1.0, v178
	v_rcp_f32_e32 v178, v178
	v_mul_f32_e32 v173, v32, v151
	v_mul_f32_e32 v151, 0xbfb8aa3b, v35
	v_exp_f32_e32 v151, v151
	v_mul_f32_e32 v152, 0xbfb8aa3b, v33
	v_mul_f32_e32 v170, v30, v149
	v_mul_f32_e32 v172, v31, v150
	v_mul_f32_e32 v150, 0xbfb8aa3b, v34
	v_exp_f32_e32 v152, v152
	v_exp_f32_e32 v150, v150
	v_cvt_pk_bf16_f32 v203, v180, v182
	global_store_dwordx4 v[188:189], v[200:203], off nt
	v_add_f32_e32 v151, 1.0, v151
	v_rcp_f32_e32 v151, v151
	v_mul_f32_e32 v201, v116, v178
	v_cvt_pk_bf16_f32 v178, v170, v172
	v_mul_f32_e32 v170, 0xbfb8aa3b, v130
	v_exp_f32_e32 v170, v170
	v_add_f32_e32 v149, 1.0, v152
	v_add_f32_e32 v150, 1.0, v150
	v_rcp_f32_e32 v149, v149
	v_rcp_f32_e32 v150, v150
	v_add_f32_e32 v170, 1.0, v170
	v_rcp_f32_e32 v179, v181
	v_rcp_f32_e32 v170, v170
	v_mul_f32_e32 v152, 0xbfb8aa3b, v36
	v_mul_f32_e32 v169, v35, v151
	v_mul_f32_e32 v151, 0xbfb8aa3b, v38
	v_exp_f32_e32 v152, v152
	v_exp_f32_e32 v151, v151
	v_add_f32_e32 v180, 1.0, v248
	v_mul_f32_e32 v181, 0xbfb8aa3b, v117
	v_mul_f32_e32 v183, v33, v149
	v_mul_f32_e32 v168, v34, v150
	v_mul_f32_e32 v150, 0xbfb8aa3b, v37
	v_rcp_f32_e32 v180, v180
	v_exp_f32_e32 v181, v181
	v_exp_f32_e32 v150, v150
	v_mul_f32_e32 v182, v114, v179
	v_cvt_pk_bf16_f32 v179, v173, v183
	v_mul_f32_e32 v183, v130, v170
	v_mul_f32_e32 v170, 0xbfb8aa3b, v126
	v_exp_f32_e32 v170, v170
	v_add_f32_e32 v149, 1.0, v152
	v_add_f32_e32 v151, 1.0, v151
	v_rcp_f32_e32 v149, v149
	v_rcp_f32_e32 v151, v151
	v_mul_f32_e32 v200, v115, v180
	v_add_f32_e32 v180, 1.0, v181
	v_add_f32_e32 v150, 1.0, v150
	v_rcp_f32_e32 v173, v180
	v_cvt_pk_bf16_f32 v180, v168, v169
	v_mul_f32_e32 v168, 0xbfb8aa3b, v132
	v_mul_f32_e32 v169, 0xbfb8aa3b, v133
	v_rcp_f32_e32 v150, v150
	v_exp_f32_e32 v168, v168
	v_exp_f32_e32 v169, v169
	v_add_f32_e32 v170, 1.0, v170
	v_rcp_f32_e32 v170, v170
	v_mul_f32_e32 v171, v36, v149
	v_mul_f32_e32 v149, v38, v151
	v_mul_f32_e32 v151, 0xbfb8aa3b, v40
	v_mul_f32_e32 v152, 0xbfb8aa3b, v39
	v_exp_f32_e32 v151, v151
	v_exp_f32_e32 v152, v152
	v_mul_f32_e32 v174, v37, v150
	v_add_f32_e32 v168, 1.0, v168
	v_cvt_pk_bf16_f32 v181, v171, v174
	v_add_f32_e32 v169, 1.0, v169
	v_mul_f32_e32 v171, 0xbfb8aa3b, v127
	v_rcp_f32_e32 v168, v168
	v_rcp_f32_e32 v169, v169
	v_exp_f32_e32 v171, v171
	v_mul_f32_e32 v203, v126, v170
	v_mul_f32_e32 v170, 0xbfb8aa3b, v129
	v_exp_f32_e32 v170, v170
	v_add_f32_e32 v151, 1.0, v151
	v_add_f32_e32 v150, 1.0, v152
	v_mul_f32_e32 v152, 0xbfb8aa3b, v41
	v_rcp_f32_e32 v151, v151
	v_exp_f32_e32 v152, v152
	v_mul_f32_e32 v174, v132, v168
	v_mul_f32_e32 v202, v133, v169
	v_add_f32_e32 v168, 1.0, v171
	v_mul_f32_e32 v169, 0xbfb8aa3b, v128
	v_exp_f32_e32 v169, v169
	v_rcp_f32_e32 v168, v168
	v_add_f32_e32 v170, 1.0, v170
	v_mul_f32_e32 v171, 0xbfb8aa3b, v122
	v_rcp_f32_e32 v170, v170
	v_exp_f32_e32 v171, v171
	v_mul_f32_e32 v153, 0xbfb8aa3b, v42
	v_mul_f32_e32 v154, v40, v151
	v_mul_f32_e32 v151, 0xbfb8aa3b, v43
	v_rcp_f32_e32 v150, v150
	v_add_f32_e32 v152, 1.0, v152
	v_exp_f32_e32 v156, v153
	v_exp_f32_e32 v151, v151
	v_rcp_f32_e32 v152, v152
	global_store_dwordx4 v[188:189], v[178:181], off offset:256 nt
	v_add_f32_e32 v169, 1.0, v169
	v_rcp_f32_e32 v169, v169
	v_mul_f32_e32 v178, v127, v168
	v_mul_f32_e32 v168, 0xbfb8aa3b, v123
	v_mul_f32_e32 v180, v129, v170
	v_add_f32_e32 v170, 1.0, v171
	v_exp_f32_e32 v171, v168
	v_mul_f32_e32 v153, v39, v150
	v_add_f32_e32 v150, 1.0, v156
	v_add_f32_e32 v151, 1.0, v151
	v_mul_f32_e32 v156, 0xbfb8aa3b, v45
	v_mul_f32_e32 v155, v41, v152
	v_mul_f32_e32 v152, 0xbfb8aa3b, v44
	v_rcp_f32_e32 v150, v150
	v_rcp_f32_e32 v151, v151
	v_exp_f32_e32 v158, v156
	v_exp_f32_e32 v152, v152
	v_mul_f32_e32 v179, v128, v169
	v_cvt_pk_bf16_f32 v168, v149, v153
	v_cvt_pk_bf16_f32 v169, v154, v155
	v_add_f32_e32 v154, 1.0, v171
	v_mul_f32_e32 v155, 0xbfb8aa3b, v125
	v_rcp_f32_e32 v153, v170
	v_rcp_f32_e32 v154, v154
	v_exp_f32_e32 v155, v155
	v_mul_f32_e32 v156, v42, v150
	v_mul_f32_e32 v157, v43, v151
	v_add_f32_e32 v150, 1.0, v158
	v_mul_f32_e32 v151, 0xbfb8aa3b, v46
	v_mul_f32_e32 v158, 0xbfb8aa3b, v47
	v_add_f32_e32 v152, 1.0, v152
	v_exp_f32_e32 v151, v151
	v_exp_f32_e32 v158, v158
	v_rcp_f32_e32 v152, v152
	v_mul_f32_e32 v185, 0xbfb8aa3b, v61
	v_mul_f32_e32 v181, v122, v153
	v_mul_f32_e32 v188, v123, v154
	v_add_f32_e32 v153, 1.0, v155
	v_mul_f32_e32 v154, 0xbfb8aa3b, v118
	v_rcp_f32_e32 v150, v150
	v_exp_f32_e32 v185, v185
	v_mul_f32_e32 v186, 0xbfb8aa3b, v62
	v_rcp_f32_e32 v153, v153
	v_exp_f32_e32 v154, v154
	v_mul_f32_e32 v184, 0xbfb8aa3b, v60
	v_exp_f32_e32 v186, v186
	v_add_f32_e32 v151, 1.0, v151
	v_add_f32_e32 v158, 1.0, v158
	v_mul_f32_e32 v159, 0xbfb8aa3b, v48
	v_exp_f32_e32 v184, v184
	v_mul_f32_e32 v210, 0xbfb8aa3b, v71
	v_mul_f32_e32 v155, 0xbfb8aa3b, v119
	v_mul_f32_e32 v152, v44, v152
	v_rcp_f32_e32 v151, v151
	v_rcp_f32_e32 v158, v158
	v_exp_f32_e32 v159, v159
	v_mul_f32_e32 v207, 0xbfb8aa3b, v69
	v_mul_f32_e32 v208, 0xbfb8aa3b, v70
	v_exp_f32_e32 v210, v210
	v_mul_f32_e32 v226, 0xbfb8aa3b, v85
	v_exp_f32_e32 v155, v155
	v_mul_f32_e32 v161, v45, v150
	v_add_f32_e32 v185, 1.0, v185
	v_exp_f32_e32 v207, v207
	v_exp_f32_e32 v208, v208
	v_exp_f32_e32 v226, v226
	v_mul_f32_e32 v227, 0xbfb8aa3b, v86
	v_cvt_pk_bf16_f32 v170, v156, v157
	v_mul_f32_e32 v156, v125, v153
	v_add_f32_e32 v153, 1.0, v154
	v_cvt_pk_bf16_f32 v171, v152, v161
	v_or_b32_e32 v152, 32, v140
	v_rcp_f32_e32 v190, v185
	v_add_f32_e32 v185, 1.0, v186
	v_mul_f32_e32 v225, 0xbfb8aa3b, v84
	v_exp_f32_e32 v227, v227
	v_mul_f32_e32 v236, 0xbfb8aa3b, v95
	v_rcp_f32_e32 v157, v153
	v_ashrrev_i32_e32 v153, 31, v152
	v_add_f32_e32 v184, 1.0, v184
	v_rcp_f32_e32 v191, v185
	v_mul_f32_e32 v185, 0xbfb8aa3b, v63
	v_exp_f32_e32 v225, v225
	v_mul_f32_e32 v234, 0xbfb8aa3b, v93
	v_mul_f32_e32 v235, 0xbfb8aa3b, v94
	v_exp_f32_e32 v236, v236
	v_lshlrev_b64 v[152:153], 13, v[152:153]
	v_mul_f32_e32 v150, v46, v151
	v_mul_f32_e32 v151, v47, v158
	v_add_f32_e32 v158, 1.0, v159
	v_mul_f32_e32 v159, 0xbfb8aa3b, v49
	v_mul_f32_e32 v160, 0xbfb8aa3b, v50
	v_mul_f32_e32 v162, 0xbfb8aa3b, v51
	v_mul_f32_e32 v163, 0xbfb8aa3b, v52
	v_mul_f32_e32 v164, 0xbfb8aa3b, v53
	v_rcp_f32_e32 v184, v184
	v_exp_f32_e32 v193, v185
	v_add_f32_e32 v210, 1.0, v210
	v_exp_f32_e32 v234, v234
	v_exp_f32_e32 v235, v235
	v_add_f32_e32 v189, 1.0, v155
	v_lshl_add_u64 v[154:155], v[146:147], 0, v[152:153]
	v_mul_f32_e32 v152, 0xbfb8aa3b, v120
	v_mul_f32_e32 v153, 0xbfb8aa3b, v121
	v_exp_f32_e32 v159, v159
	v_exp_f32_e32 v160, v160
	v_exp_f32_e32 v162, v162
	v_exp_f32_e32 v163, v163
	v_exp_f32_e32 v164, v164
	v_add_f32_e32 v207, 1.0, v207
	v_add_f32_e32 v208, 1.0, v208
	v_rcp_f32_e32 v211, v210
	v_mul_f32_e32 v210, 0xbfb8aa3b, v72
	v_add_f32_e32 v226, 1.0, v226
	v_exp_f32_e32 v152, v152
	v_exp_f32_e32 v153, v153
	v_rcp_f32_e32 v207, v207
	v_rcp_f32_e32 v208, v208
	v_exp_f32_e32 v212, v210
	v_rcp_f32_e32 v228, v226
	v_add_f32_e32 v226, 1.0, v227
	v_mul_f32_e32 v165, 0xbfb8aa3b, v54
	v_mul_f32_e32 v166, 0xbfb8aa3b, v55
	v_mul_f32_e32 v167, 0xbfb8aa3b, v56
	v_mul_f32_e32 v175, 0xbfb8aa3b, v57
	v_add_f32_e32 v225, 1.0, v225
	v_rcp_f32_e32 v229, v226
	v_mul_f32_e32 v226, 0xbfb8aa3b, v87
	v_add_f32_e32 v236, 1.0, v236
	v_exp_f32_e32 v165, v165
	v_exp_f32_e32 v166, v166
	v_exp_f32_e32 v167, v167
	v_exp_f32_e32 v175, v175
	v_mul_f32_e32 v176, 0xbfb8aa3b, v58
	v_mul_f32_e32 v177, 0xbfb8aa3b, v59
	v_mul_f32_e32 v185, v60, v184
	v_mul_f32_e32 v186, v61, v190
	v_mul_f32_e32 v184, v62, v191
	v_add_f32_e32 v190, 1.0, v193
	v_mul_f32_e32 v191, 0xbfb8aa3b, v64
	v_mul_f32_e32 v193, 0xbfb8aa3b, v65
	v_rcp_f32_e32 v225, v225
	v_exp_f32_e32 v230, v226
	v_add_f32_e32 v234, 1.0, v234
	v_add_f32_e32 v235, 1.0, v235
	v_rcp_f32_e32 v237, v236
	v_mul_f32_e32 v236, 0xbfb8aa3b, v96
	v_add_f32_e32 v159, 1.0, v159
	v_add_f32_e32 v160, 1.0, v160
	v_add_f32_e32 v162, 1.0, v162
	v_add_f32_e32 v163, 1.0, v163
	v_add_f32_e32 v164, 1.0, v164
	v_exp_f32_e32 v176, v176
	v_exp_f32_e32 v177, v177
	v_exp_f32_e32 v191, v191
	v_exp_f32_e32 v193, v193
	v_mul_f32_e32 v196, 0xbfb8aa3b, v66
	v_mul_f32_e32 v198, 0xbfb8aa3b, v67
	v_mul_f32_e32 v199, 0xbfb8aa3b, v68
	v_rcp_f32_e32 v234, v234
	v_rcp_f32_e32 v235, v235
	v_exp_f32_e32 v238, v236
	v_add_f32_e32 v152, 1.0, v152
	v_add_f32_e32 v153, 1.0, v153
	v_rcp_f32_e32 v158, v158
	v_rcp_f32_e32 v159, v159
	v_rcp_f32_e32 v160, v160
	v_rcp_f32_e32 v162, v162
	v_rcp_f32_e32 v163, v163
	v_rcp_f32_e32 v164, v164
	v_exp_f32_e32 v196, v196
	v_exp_f32_e32 v198, v198
	v_exp_f32_e32 v199, v199
	v_mul_f32_e32 v210, v69, v207
	v_mul_f32_e32 v207, v70, v208
	v_mul_f32_e32 v208, v71, v211
	v_add_f32_e32 v211, 1.0, v212
	v_mul_f32_e32 v212, 0xbfb8aa3b, v73
	v_mul_f32_e32 v213, 0xbfb8aa3b, v74
	v_mul_f32_e32 v216, 0xbfb8aa3b, v75
	v_mul_f32_e32 v217, 0xbfb8aa3b, v76
	v_mul_f32_e32 v218, 0xbfb8aa3b, v77
	v_rcp_f32_e32 v152, v152
	v_rcp_f32_e32 v153, v153
	v_exp_f32_e32 v212, v212
	v_exp_f32_e32 v213, v213
	v_exp_f32_e32 v216, v216
	v_exp_f32_e32 v217, v217
	v_exp_f32_e32 v218, v218
	v_mul_f32_e32 v219, 0xbfb8aa3b, v78
	v_mul_f32_e32 v220, 0xbfb8aa3b, v79
	v_mul_f32_e32 v221, 0xbfb8aa3b, v80
	v_mul_f32_e32 v222, 0xbfb8aa3b, v81
	v_mul_f32_e32 v223, 0xbfb8aa3b, v82
	v_mul_f32_e32 v224, 0xbfb8aa3b, v83
	v_add_f32_e32 v165, 1.0, v165
	v_add_f32_e32 v166, 1.0, v166
	v_add_f32_e32 v167, 1.0, v167
	v_add_f32_e32 v175, 1.0, v175
	v_exp_f32_e32 v219, v219
	v_exp_f32_e32 v220, v220
	v_exp_f32_e32 v221, v221
	v_exp_f32_e32 v222, v222
	v_exp_f32_e32 v223, v223
	v_exp_f32_e32 v224, v224
	v_mul_f32_e32 v226, v84, v225
	v_mul_f32_e32 v227, v85, v228
	v_mul_f32_e32 v225, v86, v229
	v_add_f32_e32 v228, 1.0, v230
	v_mul_f32_e32 v229, 0xbfb8aa3b, v88
	v_mul_f32_e32 v230, 0xbfb8aa3b, v89
	v_mul_f32_e32 v231, 0xbfb8aa3b, v90
	v_mul_f32_e32 v232, 0xbfb8aa3b, v91
	v_mul_f32_e32 v233, 0xbfb8aa3b, v92
	v_rcp_f32_e32 v165, v165
	v_rcp_f32_e32 v166, v166
	v_rcp_f32_e32 v167, v167
	v_rcp_f32_e32 v175, v175
	v_add_f32_e32 v176, 1.0, v176
	v_add_f32_e32 v177, 1.0, v177
	v_add_f32_e32 v191, 1.0, v191
	v_add_f32_e32 v193, 1.0, v193
	v_exp_f32_e32 v229, v229
	v_exp_f32_e32 v230, v230
	v_exp_f32_e32 v231, v231
	v_exp_f32_e32 v232, v232
	v_exp_f32_e32 v233, v233
	v_mul_f32_e32 v236, v93, v234
	v_mul_f32_e32 v234, v94, v235
	v_mul_f32_e32 v235, v95, v237
	v_add_f32_e32 v237, 1.0, v238
	v_mul_f32_e32 v238, 0xbfb8aa3b, v97
	v_mul_f32_e32 v239, 0xbfb8aa3b, v98
	global_store_dwordx4 v[154:155], v[168:171], off nt
	v_cvt_pk_bf16_f32 v150, v150, v151
	v_mul_f32_e32 v158, v48, v158
	v_mul_f32_e32 v159, v49, v159
	v_mul_f32_e32 v160, v50, v160
	v_mul_f32_e32 v162, v51, v162
	v_mul_f32_e32 v163, v52, v163
	v_mul_f32_e32 v164, v53, v164
	v_rcp_f32_e32 v176, v176
	v_rcp_f32_e32 v177, v177
	v_rcp_f32_e32 v190, v190
	v_rcp_f32_e32 v191, v191
	v_rcp_f32_e32 v193, v193
	v_add_f32_e32 v196, 1.0, v196
	v_add_f32_e32 v198, 1.0, v198
	v_add_f32_e32 v199, 1.0, v199
	v_exp_f32_e32 v238, v238
	v_exp_f32_e32 v239, v239
	v_mul_f32_e32 v194, 0xbfb8aa3b, v104
	v_mul_f32_e32 v192, 0xbfb8aa3b, v108
	v_mul_f32_e32 v168, v120, v152
	v_mul_f32_e32 v169, v121, v153
	v_cvt_pk_bf16_f32 v151, v158, v159
	v_cvt_pk_bf16_f32 v152, v160, v162
	v_cvt_pk_bf16_f32 v153, v163, v164
	global_store_dwordx4 v[154:155], v[150:153], off offset:256 nt
	v_rcp_f32_e32 v196, v196
	v_rcp_f32_e32 v198, v198
	v_or_b32_e32 v150, 48, v140
	v_rcp_f32_e32 v199, v199
	v_add_f32_e32 v212, 1.0, v212
	v_add_f32_e32 v213, 1.0, v213
	v_add_f32_e32 v216, 1.0, v216
	v_add_f32_e32 v217, 1.0, v217
	v_add_f32_e32 v218, 1.0, v218
	v_exp_f32_e32 v194, v194
	v_exp_f32_e32 v192, v192
	v_ashrrev_i32_e32 v151, 31, v150
	v_rcp_f32_e32 v211, v211
	v_rcp_f32_e32 v212, v212
	v_rcp_f32_e32 v213, v213
	v_rcp_f32_e32 v216, v216
	v_rcp_f32_e32 v217, v217
	v_rcp_f32_e32 v218, v218
	v_add_f32_e32 v219, 1.0, v219
	v_add_f32_e32 v220, 1.0, v220
	v_add_f32_e32 v221, 1.0, v221
	v_add_f32_e32 v222, 1.0, v222
	v_add_f32_e32 v223, 1.0, v223
	v_add_f32_e32 v224, 1.0, v224
	v_mul_f32_e32 v172, 0xbfb8aa3b, v131
	v_mul_f32_e32 v149, 0xbfb8aa3b, v124
	v_lshlrev_b64 v[150:151], 13, v[150:151]
	v_mul_f32_e32 v165, v54, v165
	v_mul_f32_e32 v166, v55, v166
	v_mul_f32_e32 v167, v56, v167
	v_mul_f32_e32 v175, v57, v175
	v_rcp_f32_e32 v219, v219
	v_rcp_f32_e32 v220, v220
	v_rcp_f32_e32 v221, v221
	v_rcp_f32_e32 v222, v222
	v_rcp_f32_e32 v223, v223
	v_rcp_f32_e32 v224, v224
	v_add_f32_e32 v229, 1.0, v229
	v_add_f32_e32 v230, 1.0, v230
	v_add_f32_e32 v231, 1.0, v231
	v_add_f32_e32 v232, 1.0, v232
	v_add_f32_e32 v233, 1.0, v233
	v_exp_f32_e32 v172, v172
	v_exp_f32_e32 v149, v149
	v_lshl_add_u64 v[154:155], v[146:147], 0, v[150:151]
	v_cvt_pk_bf16_f32 v150, v165, v166
	v_cvt_pk_bf16_f32 v151, v167, v175
	v_mul_f32_e32 v176, v58, v176
	v_mul_f32_e32 v177, v59, v177
	v_mul_f32_e32 v190, v63, v190
	v_mul_f32_e32 v191, v64, v191
	v_mul_f32_e32 v193, v65, v193
	v_rcp_f32_e32 v228, v228
	v_rcp_f32_e32 v229, v229
	v_rcp_f32_e32 v230, v230
	v_rcp_f32_e32 v231, v231
	v_rcp_f32_e32 v232, v232
	v_rcp_f32_e32 v233, v233
	v_add_f32_e32 v238, 1.0, v238
	v_add_f32_e32 v239, 1.0, v239
	v_cvt_pk_bf16_f32 v152, v176, v177
	v_cvt_pk_bf16_f32 v153, v185, v186
	global_store_dwordx4 v[154:155], v[150:153], off nt
	v_mul_f32_e32 v196, v66, v196
	v_mul_f32_e32 v198, v67, v198
	v_cvt_pk_bf16_f32 v150, v184, v190
	v_cvt_pk_bf16_f32 v151, v191, v193
	v_mul_f32_e32 v199, v68, v199
	v_rcp_f32_e32 v237, v237
	v_rcp_f32_e32 v238, v238
	v_rcp_f32_e32 v239, v239
	v_add_f32_e32 v194, 1.0, v194
	v_add_f32_e32 v192, 1.0, v192
	v_cvt_pk_bf16_f32 v152, v196, v198
	v_cvt_pk_bf16_f32 v153, v199, v210
	global_store_dwordx4 v[154:155], v[150:153], off offset:256 nt
	v_mul_f32_e32 v211, v72, v211
	v_mul_f32_e32 v212, v73, v212
	v_lshlrev_b64 v[150:151], 13, v[142:143]
	v_mul_f32_e32 v213, v74, v213
	v_mul_f32_e32 v216, v75, v216
	v_mul_f32_e32 v217, v76, v217
	v_mul_f32_e32 v218, v77, v218
	v_rcp_f32_e32 v194, v194
	v_rcp_f32_e32 v192, v192
	v_lshl_add_u64 v[146:147], v[146:147], 0, v[150:151]
	v_cvt_pk_bf16_f32 v150, v207, v208
	v_cvt_pk_bf16_f32 v151, v211, v212
	v_cvt_pk_bf16_f32 v152, v213, v216
	v_cvt_pk_bf16_f32 v153, v217, v218
	v_add_co_u32_e32 v154, vcc, s72, v144
	v_mul_f32_e32 v219, v78, v219
	v_mul_f32_e32 v220, v79, v220
	v_mul_f32_e32 v221, v80, v221
	v_mul_f32_e32 v222, v81, v222
	v_mul_f32_e32 v223, v82, v223
	v_mul_f32_e32 v224, v83, v224
	v_add_f32_e32 v172, 1.0, v172
	v_add_f32_e32 v149, 1.0, v149
	global_store_dwordx4 v[146:147], v[150:153], off nt
	s_mov_b64 s[26:27], 0x120000
	v_addc_co_u32_e32 v155, vcc, 0, v145, vcc
	v_cvt_pk_bf16_f32 v150, v219, v220
	v_cvt_pk_bf16_f32 v151, v221, v222
	v_cvt_pk_bf16_f32 v152, v223, v224
	v_cvt_pk_bf16_f32 v153, v226, v227
	global_store_dwordx4 v[146:147], v[150:153], off offset:256 nt
	v_mul_f32_e32 v228, v87, v228
	v_mul_f32_e32 v229, v88, v229
	v_mul_f32_e32 v230, v89, v230
	v_mul_f32_e32 v231, v90, v231
	v_mul_f32_e32 v232, v91, v232
	v_mul_f32_e32 v233, v92, v233
	v_rcp_f32_e32 v172, v172
	v_rcp_f32_e32 v149, v149
	v_rcp_f32_e32 v161, v189
	v_lshl_add_u64 v[146:147], v[144:145], 0, s[26:27]
	v_cvt_pk_bf16_f32 v150, v225, v228
	v_cvt_pk_bf16_f32 v151, v229, v230
	v_cvt_pk_bf16_f32 v152, v231, v232
	v_cvt_pk_bf16_f32 v153, v233, v236
	global_store_dwordx4 v[154:155], v[150:153], off nt
	s_mov_b64 s[26:27], 0x140000
	v_add_co_u32_e32 v154, vcc, s73, v144
	v_mul_f32_e32 v237, v96, v237
	v_mul_f32_e32 v238, v97, v238
	v_mul_f32_e32 v239, v98, v239
	v_mul_f32_e32 v195, v99, v195
	v_cvt_pk_bf16_f32 v150, v234, v235
	v_cvt_pk_bf16_f32 v151, v237, v238
	v_cvt_pk_bf16_f32 v152, v239, v195
	v_cvt_pk_bf16_f32 v153, v206, v209
	global_store_dwordx4 v[146:147], v[150:153], off offset:256 nt
	v_lshl_add_u64 v[146:147], v[144:145], 0, s[26:27]
	v_addc_co_u32_e32 v155, vcc, 0, v145, vcc
	s_mov_b64 s[26:27], 0x160000
	v_mul_f32_e32 v194, v104, v194
	v_mul_f32_e32 v192, v108, v192
	v_cvt_pk_bf16_f32 v150, v241, v242
	v_cvt_pk_bf16_f32 v151, v194, v197
	v_cvt_pk_bf16_f32 v152, v240, v243
	v_cvt_pk_bf16_f32 v153, v192, v204
	global_store_dwordx4 v[154:155], v[150:153], off nt
	v_lshl_add_u64 v[154:155], v[144:145], 0, s[26:27]
	v_add_co_u32_e32 v144, vcc, 0x160000, v144
	v_mul_f32_e32 v173, v117, v173
	v_cvt_pk_bf16_f32 v150, v205, v187
	v_cvt_pk_bf16_f32 v151, v244, v245
	v_cvt_pk_bf16_f32 v152, v182, v200
	v_cvt_pk_bf16_f32 v153, v201, v173
	global_store_dwordx4 v[146:147], v[150:153], off offset:256 nt
	v_addc_co_u32_e32 v145, vcc, 0, v145, vcc
	v_mul_f32_e32 v172, v131, v172
	v_mul_f32_e32 v149, v124, v149
	v_mul_f32_e32 v157, v118, v157
	v_mul_f32_e32 v161, v119, v161
	v_cvt_pk_bf16_f32 v150, v183, v172
	v_cvt_pk_bf16_f32 v151, v174, v202
	v_cvt_pk_bf16_f32 v152, v203, v178
	v_cvt_pk_bf16_f32 v153, v179, v180
	global_store_dwordx4 v[144:145], v[150:153], off nt
	v_cvt_pk_bf16_f32 v144, v181, v188
	v_cvt_pk_bf16_f32 v145, v149, v156
	v_cvt_pk_bf16_f32 v146, v157, v161
	v_cvt_pk_bf16_f32 v147, v168, v169
	global_store_dwordx4 v[154:155], v[144:147], off offset:256 nt
	s_mov_b64 s[26:27], 0

.LBB0_346:
	s_add_u32 s54, s33, 0xffffff80
	s_addc_u32 s55, s52, -1
	s_cmp_eq_u32 s53, 60
	s_cselect_b32 s28, s2, s33
	s_cselect_b32 s29, s1, s52
	s_cselect_b32 s31, s11, s23
	s_cselect_b32 s30, s15, s19
	s_add_u32 s24, s28, 0x80
	s_addc_u32 s25, s29, 0
	s_add_u32 s26, s30, 0x80
	s_addc_u32 s27, s31, 0
	s_add_i32 s56, 0, 0x10000
	s_add_i32 s57, 0, 0x14000
	v_add_u32_e32 v152, s56, v1
	v_add_u32_e32 v168, s57, v1
	ds_read_b128 v[140:143], v152
	ds_read_b128 v[144:147], v152 offset:1024
	ds_read_b128 v[148:151], v152 offset:2048
	ds_read_b128 v[152:155], v152 offset:3072
	ds_read_b128 v[156:159], v168
	ds_read_b128 v[160:163], v168 offset:1024
	ds_read_b128 v[164:167], v168 offset:2048
	ds_read_b128 v[168:171], v168 offset:3072
	s_add_u32 s54, s54, 0x100000
	s_addc_u32 s55, s55, 0
	v_lshl_add_u64 v[204:205], s[54:55], 0, v[2:3]
	s_add_i32 m0, s41, 0xc000
	ds_read_b128 v[172:175], v5
	ds_read_b128 v[176:179], v5 offset:1024
	ds_read_b128 v[180:183], v5 offset:2048
	ds_read_b128 v[184:187], v5 offset:3072
	ds_read_b128 v[188:191], v5 offset:4096
	ds_read_b128 v[192:195], v5 offset:5120
	ds_read_b128 v[196:199], v5 offset:6144
	ds_read_b128 v[200:203], v5 offset:7168
	global_load_lds_dwordx4 v[204:205], off
	v_lshl_add_u64 v[204:205], s[54:55], 0, v[136:137]
	s_add_i32 m0, s41, 0xe000
	s_nop 0
	global_load_lds_dwordx4 v[204:205], off
	s_waitcnt vmcnt(8)
	s_waitcnt lgkmcnt(0)
	s_barrier
	v_mfma_f32_16x16x32_bf16 v[130:133], v[140:143], v[172:175], v[130:133]
	v_mfma_f32_16x16x32_bf16 v[126:129], v[148:151], v[172:175], v[126:129]
	v_mfma_f32_16x16x32_bf16 v[114:117], v[140:143], v[180:183], v[114:117]
	v_mfma_f32_16x16x32_bf16 v[110:113], v[148:151], v[180:183], v[110:113]
	v_mfma_f32_16x16x32_bf16 v[98:101], v[140:143], v[188:191], v[98:101]
	v_mfma_f32_16x16x32_bf16 v[94:97], v[148:151], v[188:191], v[94:97]
	v_mfma_f32_16x16x32_bf16 v[82:85], v[140:143], v[196:199], v[82:85]
	v_mfma_f32_16x16x32_bf16 v[78:81], v[148:151], v[196:199], v[78:81]
	v_mfma_f32_16x16x32_bf16 v[130:133], v[144:147], v[176:179], v[130:133]
	v_mfma_f32_16x16x32_bf16 v[126:129], v[152:155], v[176:179], v[126:129]
	v_mfma_f32_16x16x32_bf16 v[114:117], v[144:147], v[184:187], v[114:117]
	v_mfma_f32_16x16x32_bf16 v[110:113], v[152:155], v[184:187], v[110:113]
	v_mfma_f32_16x16x32_bf16 v[98:101], v[144:147], v[192:195], v[98:101]
	v_mfma_f32_16x16x32_bf16 v[94:97], v[152:155], v[192:195], v[94:97]
	v_mfma_f32_16x16x32_bf16 v[82:85], v[144:147], v[200:203], v[82:85]
	v_mfma_f32_16x16x32_bf16 v[78:81], v[152:155], v[200:203], v[78:81]
	v_mfma_f32_16x16x32_bf16 v[122:125], v[156:159], v[172:175], v[122:125]
	v_mfma_f32_16x16x32_bf16 v[118:121], v[164:167], v[172:175], v[118:121]
	v_mfma_f32_16x16x32_bf16 v[106:109], v[156:159], v[180:183], v[106:109]
	v_mfma_f32_16x16x32_bf16 v[102:105], v[164:167], v[180:183], v[102:105]
	v_mfma_f32_16x16x32_bf16 v[90:93], v[156:159], v[188:191], v[90:93]
	v_mfma_f32_16x16x32_bf16 v[86:89], v[164:167], v[188:191], v[86:89]
	v_mfma_f32_16x16x32_bf16 v[74:77], v[156:159], v[196:199], v[74:77]
	v_mfma_f32_16x16x32_bf16 v[70:73], v[164:167], v[196:199], v[70:73]
	v_mfma_f32_16x16x32_bf16 v[122:125], v[160:163], v[176:179], v[122:125]
	v_mfma_f32_16x16x32_bf16 v[118:121], v[168:171], v[176:179], v[118:121]
	v_mfma_f32_16x16x32_bf16 v[106:109], v[160:163], v[184:187], v[106:109]
	v_mfma_f32_16x16x32_bf16 v[102:105], v[168:171], v[184:187], v[102:105]
	v_mfma_f32_16x16x32_bf16 v[90:93], v[160:163], v[192:195], v[90:93]
	v_mfma_f32_16x16x32_bf16 v[86:89], v[168:171], v[192:195], v[86:89]
	v_mfma_f32_16x16x32_bf16 v[74:77], v[160:163], v[200:203], v[74:77]
	v_mfma_f32_16x16x32_bf16 v[70:73], v[168:171], v[200:203], v[70:73]
	s_barrier
	s_add_i32 s54, s56, s38
	v_lshl_add_u64 v[204:205], s[30:31], 0, v[134:135]
	s_mov_b32 m0, s54
	ds_read_b128 v[172:175], v5 offset:16384
	ds_read_b128 v[176:179], v5 offset:17408
	ds_read_b128 v[180:183], v5 offset:18432
	ds_read_b128 v[184:187], v5 offset:19456
	ds_read_b128 v[188:191], v5 offset:20480
	ds_read_b128 v[192:195], v5 offset:21504
	ds_read_b128 v[196:199], v5 offset:22528
	ds_read_b128 v[200:203], v5 offset:23552
	global_load_lds_dwordx4 v[204:205], off
	s_add_i32 m0, s54, 0x2000
	v_lshl_add_u64 v[204:205], s[30:31], 0, v[138:139]
	s_add_u32 s30, s30, 0x100000
	s_addc_u32 s31, s31, 0
	s_add_i32 s54, s57, s38
	global_load_lds_dwordx4 v[204:205], off
	v_lshl_add_u64 v[204:205], s[30:31], 0, v[134:135]
	s_mov_b32 m0, s54
	s_nop 0
	global_load_lds_dwordx4 v[204:205], off
	v_lshl_add_u64 v[204:205], s[30:31], 0, v[138:139]
	s_add_i32 m0, s54, 0x2000
	s_nop 0
	global_load_lds_dwordx4 v[204:205], off
	v_lshl_add_u64 v[204:205], s[28:29], 0, v[2:3]
	s_mov_b32 m0, s41
	s_nop 0
	global_load_lds_dwordx4 v[204:205], off
	v_lshl_add_u64 v[204:205], s[28:29], 0, v[136:137]
	s_mov_b32 m0, s3
	s_nop 0
	global_load_lds_dwordx4 v[204:205], off
	s_waitcnt vmcnt(8)
	s_waitcnt lgkmcnt(0)
	s_barrier
	v_mfma_f32_16x16x32_bf16 v[66:69], v[140:143], v[172:175], v[66:69]
	v_mfma_f32_16x16x32_bf16 v[62:65], v[148:151], v[172:175], v[62:65]
	v_mfma_f32_16x16x32_bf16 v[50:53], v[140:143], v[180:183], v[50:53]
	v_mfma_f32_16x16x32_bf16 v[46:49], v[148:151], v[180:183], v[46:49]
	v_mfma_f32_16x16x32_bf16 v[34:37], v[140:143], v[188:191], v[34:37]
	v_mfma_f32_16x16x32_bf16 v[30:33], v[148:151], v[188:191], v[30:33]
	v_mfma_f32_16x16x32_bf16 v[18:21], v[140:143], v[196:199], v[18:21]
	v_mfma_f32_16x16x32_bf16 v[14:17], v[148:151], v[196:199], v[14:17]
	v_mfma_f32_16x16x32_bf16 v[66:69], v[144:147], v[176:179], v[66:69]
	v_mfma_f32_16x16x32_bf16 v[62:65], v[152:155], v[176:179], v[62:65]
	v_mfma_f32_16x16x32_bf16 v[50:53], v[144:147], v[184:187], v[50:53]
	v_mfma_f32_16x16x32_bf16 v[46:49], v[152:155], v[184:187], v[46:49]
	v_mfma_f32_16x16x32_bf16 v[34:37], v[144:147], v[192:195], v[34:37]
	v_mfma_f32_16x16x32_bf16 v[30:33], v[152:155], v[192:195], v[30:33]
	v_mfma_f32_16x16x32_bf16 v[18:21], v[144:147], v[200:203], v[18:21]
	v_mfma_f32_16x16x32_bf16 v[14:17], v[152:155], v[200:203], v[14:17]
	v_mfma_f32_16x16x32_bf16 v[58:61], v[156:159], v[172:175], v[58:61]
	v_mfma_f32_16x16x32_bf16 v[54:57], v[164:167], v[172:175], v[54:57]
	v_mfma_f32_16x16x32_bf16 v[42:45], v[156:159], v[180:183], v[42:45]
	v_mfma_f32_16x16x32_bf16 v[38:41], v[164:167], v[180:183], v[38:41]
	v_mfma_f32_16x16x32_bf16 v[26:29], v[156:159], v[188:191], v[26:29]
	v_mfma_f32_16x16x32_bf16 v[22:25], v[164:167], v[188:191], v[22:25]
	v_mfma_f32_16x16x32_bf16 v[10:13], v[156:159], v[196:199], v[10:13]
	v_mfma_f32_16x16x32_bf16 v[6:9], v[164:167], v[196:199], v[6:9]
	v_mfma_f32_16x16x32_bf16 v[58:61], v[160:163], v[176:179], v[58:61]
	v_mfma_f32_16x16x32_bf16 v[54:57], v[168:171], v[176:179], v[54:57]
	v_mfma_f32_16x16x32_bf16 v[42:45], v[160:163], v[184:187], v[42:45]
	v_mfma_f32_16x16x32_bf16 v[38:41], v[168:171], v[184:187], v[38:41]
	v_mfma_f32_16x16x32_bf16 v[26:29], v[160:163], v[192:195], v[26:29]
	v_mfma_f32_16x16x32_bf16 v[22:25], v[168:171], v[192:195], v[22:25]
	v_mfma_f32_16x16x32_bf16 v[10:13], v[160:163], v[200:203], v[10:13]
	v_mfma_f32_16x16x32_bf16 v[6:9], v[168:171], v[200:203], v[6:9]
	s_barrier
	s_add_i32 s30, 0, 0x18000
	s_add_i32 s31, 0, 0x1c000
	v_add_u32_e32 v152, s30, v1
	v_add_u32_e32 v168, s31, v1
	ds_read_b128 v[140:143], v152
	ds_read_b128 v[144:147], v152 offset:1024
	ds_read_b128 v[148:151], v152 offset:2048
	ds_read_b128 v[152:155], v152 offset:3072
	ds_read_b128 v[156:159], v168
	ds_read_b128 v[160:163], v168 offset:1024
	ds_read_b128 v[164:167], v168 offset:2048
	ds_read_b128 v[168:171], v168 offset:3072
	s_add_u32 s28, s28, 0x100000
	s_addc_u32 s29, s29, 0
	s_mov_b32 m0, s43
	v_lshl_add_u64 v[204:205], s[28:29], 0, v[2:3]
	ds_read_b128 v[172:175], v5 offset:32768
	ds_read_b128 v[176:179], v5 offset:33792
	ds_read_b128 v[180:183], v5 offset:34816
	ds_read_b128 v[184:187], v5 offset:35840
	ds_read_b128 v[188:191], v5 offset:36864
	ds_read_b128 v[192:195], v5 offset:37888
	ds_read_b128 v[196:199], v5 offset:38912
	ds_read_b128 v[200:203], v5 offset:39936
	global_load_lds_dwordx4 v[204:205], off
	v_lshl_add_u64 v[204:205], s[28:29], 0, v[136:137]
	s_mov_b32 m0, s46
	s_nop 0
	global_load_lds_dwordx4 v[204:205], off
	s_waitcnt vmcnt(8)
	s_waitcnt lgkmcnt(0)
	s_barrier
	v_mfma_f32_16x16x32_bf16 v[130:133], v[140:143], v[172:175], v[130:133]
	v_mfma_f32_16x16x32_bf16 v[126:129], v[148:151], v[172:175], v[126:129]
	v_mfma_f32_16x16x32_bf16 v[114:117], v[140:143], v[180:183], v[114:117]
	v_mfma_f32_16x16x32_bf16 v[110:113], v[148:151], v[180:183], v[110:113]
	v_mfma_f32_16x16x32_bf16 v[98:101], v[140:143], v[188:191], v[98:101]
	v_mfma_f32_16x16x32_bf16 v[94:97], v[148:151], v[188:191], v[94:97]
	v_mfma_f32_16x16x32_bf16 v[82:85], v[140:143], v[196:199], v[82:85]
	v_mfma_f32_16x16x32_bf16 v[78:81], v[148:151], v[196:199], v[78:81]
	v_mfma_f32_16x16x32_bf16 v[130:133], v[144:147], v[176:179], v[130:133]
	v_mfma_f32_16x16x32_bf16 v[126:129], v[152:155], v[176:179], v[126:129]
	v_mfma_f32_16x16x32_bf16 v[114:117], v[144:147], v[184:187], v[114:117]
	v_mfma_f32_16x16x32_bf16 v[110:113], v[152:155], v[184:187], v[110:113]
	v_mfma_f32_16x16x32_bf16 v[98:101], v[144:147], v[192:195], v[98:101]
	v_mfma_f32_16x16x32_bf16 v[94:97], v[152:155], v[192:195], v[94:97]
	v_mfma_f32_16x16x32_bf16 v[82:85], v[144:147], v[200:203], v[82:85]
	v_mfma_f32_16x16x32_bf16 v[78:81], v[152:155], v[200:203], v[78:81]
	v_mfma_f32_16x16x32_bf16 v[122:125], v[156:159], v[172:175], v[122:125]
	v_mfma_f32_16x16x32_bf16 v[118:121], v[164:167], v[172:175], v[118:121]
	v_mfma_f32_16x16x32_bf16 v[106:109], v[156:159], v[180:183], v[106:109]
	v_mfma_f32_16x16x32_bf16 v[102:105], v[164:167], v[180:183], v[102:105]
	v_mfma_f32_16x16x32_bf16 v[90:93], v[156:159], v[188:191], v[90:93]
	v_mfma_f32_16x16x32_bf16 v[86:89], v[164:167], v[188:191], v[86:89]
	v_mfma_f32_16x16x32_bf16 v[74:77], v[156:159], v[196:199], v[74:77]
	v_mfma_f32_16x16x32_bf16 v[70:73], v[164:167], v[196:199], v[70:73]
	v_mfma_f32_16x16x32_bf16 v[122:125], v[160:163], v[176:179], v[122:125]
	v_mfma_f32_16x16x32_bf16 v[118:121], v[168:171], v[176:179], v[118:121]
	v_mfma_f32_16x16x32_bf16 v[106:109], v[160:163], v[184:187], v[106:109]
	v_mfma_f32_16x16x32_bf16 v[102:105], v[168:171], v[184:187], v[102:105]
	v_mfma_f32_16x16x32_bf16 v[90:93], v[160:163], v[192:195], v[90:93]
	v_mfma_f32_16x16x32_bf16 v[86:89], v[168:171], v[192:195], v[86:89]
	v_mfma_f32_16x16x32_bf16 v[74:77], v[160:163], v[200:203], v[74:77]
	v_mfma_f32_16x16x32_bf16 v[70:73], v[168:171], v[200:203], v[70:73]
	s_barrier
	s_add_i32 s28, s30, s38
	v_lshl_add_u64 v[204:205], s[26:27], 0, v[134:135]
	s_mov_b32 m0, s28
	ds_read_b128 v[172:175], v5 offset:49152
	ds_read_b128 v[176:179], v5 offset:50176
	ds_read_b128 v[180:183], v5 offset:51200
	ds_read_b128 v[184:187], v5 offset:52224
	ds_read_b128 v[188:191], v5 offset:53248
	ds_read_b128 v[192:195], v5 offset:54272
	ds_read_b128 v[196:199], v5 offset:55296
	ds_read_b128 v[200:203], v5 offset:56320
	global_load_lds_dwordx4 v[204:205], off
	s_add_i32 m0, s28, 0x2000
	v_lshl_add_u64 v[204:205], s[26:27], 0, v[138:139]
	s_add_u32 s26, s26, 0x100000
	s_addc_u32 s27, s27, 0
	s_add_i32 s28, s31, s38
	global_load_lds_dwordx4 v[204:205], off
	v_lshl_add_u64 v[204:205], s[26:27], 0, v[134:135]
	s_mov_b32 m0, s28
	s_nop 0
	global_load_lds_dwordx4 v[204:205], off
	v_lshl_add_u64 v[204:205], s[26:27], 0, v[138:139]
	s_add_i32 m0, s28, 0x2000
	s_nop 0
	global_load_lds_dwordx4 v[204:205], off
	v_lshl_add_u64 v[204:205], s[24:25], 0, v[2:3]
	s_mov_b32 m0, s49
	s_nop 0
	global_load_lds_dwordx4 v[204:205], off
	v_lshl_add_u64 v[204:205], s[24:25], 0, v[136:137]
	s_mov_b32 m0, s50
	s_nop 0
	global_load_lds_dwordx4 v[204:205], off
	s_waitcnt vmcnt(8)
	s_waitcnt lgkmcnt(0)
	s_barrier
	v_mfma_f32_16x16x32_bf16 v[66:69], v[140:143], v[172:175], v[66:69]
	v_mfma_f32_16x16x32_bf16 v[62:65], v[148:151], v[172:175], v[62:65]
	v_mfma_f32_16x16x32_bf16 v[50:53], v[140:143], v[180:183], v[50:53]
	v_mfma_f32_16x16x32_bf16 v[46:49], v[148:151], v[180:183], v[46:49]
	v_mfma_f32_16x16x32_bf16 v[34:37], v[140:143], v[188:191], v[34:37]
	v_mfma_f32_16x16x32_bf16 v[30:33], v[148:151], v[188:191], v[30:33]
	v_mfma_f32_16x16x32_bf16 v[18:21], v[140:143], v[196:199], v[18:21]
	v_mfma_f32_16x16x32_bf16 v[14:17], v[148:151], v[196:199], v[14:17]
	v_mfma_f32_16x16x32_bf16 v[66:69], v[144:147], v[176:179], v[66:69]
	v_mfma_f32_16x16x32_bf16 v[62:65], v[152:155], v[176:179], v[62:65]
	v_mfma_f32_16x16x32_bf16 v[50:53], v[144:147], v[184:187], v[50:53]
	v_mfma_f32_16x16x32_bf16 v[46:49], v[152:155], v[184:187], v[46:49]
	v_mfma_f32_16x16x32_bf16 v[34:37], v[144:147], v[192:195], v[34:37]
	v_mfma_f32_16x16x32_bf16 v[30:33], v[152:155], v[192:195], v[30:33]
	v_mfma_f32_16x16x32_bf16 v[18:21], v[144:147], v[200:203], v[18:21]
	v_mfma_f32_16x16x32_bf16 v[14:17], v[152:155], v[200:203], v[14:17]
	v_mfma_f32_16x16x32_bf16 v[58:61], v[156:159], v[172:175], v[58:61]
	v_mfma_f32_16x16x32_bf16 v[54:57], v[164:167], v[172:175], v[54:57]
	v_mfma_f32_16x16x32_bf16 v[42:45], v[156:159], v[180:183], v[42:45]
	v_mfma_f32_16x16x32_bf16 v[38:41], v[164:167], v[180:183], v[38:41]
	v_mfma_f32_16x16x32_bf16 v[26:29], v[156:159], v[188:191], v[26:29]
	v_mfma_f32_16x16x32_bf16 v[22:25], v[164:167], v[188:191], v[22:25]
	v_mfma_f32_16x16x32_bf16 v[10:13], v[156:159], v[196:199], v[10:13]
	v_mfma_f32_16x16x32_bf16 v[6:9], v[164:167], v[196:199], v[6:9]
	v_mfma_f32_16x16x32_bf16 v[58:61], v[160:163], v[176:179], v[58:61]
	v_mfma_f32_16x16x32_bf16 v[54:57], v[168:171], v[176:179], v[54:57]
	v_mfma_f32_16x16x32_bf16 v[42:45], v[160:163], v[184:187], v[42:45]
	v_mfma_f32_16x16x32_bf16 v[38:41], v[168:171], v[184:187], v[38:41]
	v_mfma_f32_16x16x32_bf16 v[26:29], v[160:163], v[192:195], v[26:29]
	v_mfma_f32_16x16x32_bf16 v[22:25], v[168:171], v[192:195], v[22:25]
	v_mfma_f32_16x16x32_bf16 v[10:13], v[160:163], v[200:203], v[10:13]
	v_mfma_f32_16x16x32_bf16 v[6:9], v[168:171], v[200:203], v[6:9]
	s_barrier
	s_add_i32 s53, s53, 2
	s_add_u32 s19, s19, 0x100
	s_addc_u32 s23, s23, 0
	s_add_u32 s33, s33, 0x100
	s_addc_u32 s52, s52, 0
	s_cmp_gt_u32 s53, 61
	s_cbranch_scc0 .LBB0_346
	v_mov_b32_e32 v140, v0
	s_lshl_b32 s1, s0, 8
	s_mov_b64 s[24:25], s[84:85]
	s_add_i32 s1, s1, s47
	v_bfe_u32 v210, v140, 4, 2
	v_and_or_b32 v140, v140, 15, s1
	s_add_u32 s26, s24, s6
	s_addc_u32 s27, s25, s7
	v_ashrrev_i32_e32 v141, 31, v140
	v_lshl_add_u64 v[142:143], v[140:141], 2, s[26:27]
	s_mov_b64 s[26:27], 0x10000
	v_lshl_add_u64 v[154:155], v[142:143], 0, s[26:27]
	v_add_co_u32_e32 v142, vcc, s91, v142
	s_cmp_gt_i32 s22, 3
	s_nop 0
	v_addc_co_u32_e32 v143, vcc, 0, v143, vcc
	global_load_dword v142, v[142:143], off
	s_cselect_b64 s[28:29], -1, 0
	s_cmp_lt_i32 s22, 4
	s_cselect_b64 s[26:27], -1, 0
	global_load_dword v205, v[154:155], off offset:64
	global_load_dword v204, v[154:155], off offset:128
	global_load_dword v203, v[154:155], off offset:192
	global_load_dword v202, v[154:155], off offset:512
	global_load_dword v201, v[154:155], off offset:576
	global_load_dword v200, v[154:155], off offset:640
	global_load_dword v199, v[154:155], off offset:704
	s_waitcnt vmcnt(0)
	v_fmamk_f32 v142, v142, 0x39800000, v246
	v_cmp_gt_f32_e32 vcc, s95, v142
	v_mul_f32_e32 v143, 0x4b800000, v142
	s_nop 0
	v_cndmask_b32_e32 v142, v142, v143, vcc
	v_rsq_f32_e32 v142, v142
	s_nop 0
	v_mul_f32_e32 v143, 0x45800000, v142
	v_cndmask_b32_e32 v142, v142, v143, vcc
	v_pk_mul_f32 v[132:133], v[132:133], v[142:143] op_sel_hi:[1,0]
	v_pk_mul_f32 v[130:131], v[130:131], v[142:143] op_sel_hi:[1,0]
	v_pk_mul_f32 v[128:129], v[128:129], v[142:143] op_sel_hi:[1,0]
	v_pk_mul_f32 v[126:127], v[126:127], v[142:143] op_sel_hi:[1,0]
	v_pk_mul_f32 v[124:125], v[124:125], v[142:143] op_sel_hi:[1,0]
	v_pk_mul_f32 v[122:123], v[122:123], v[142:143] op_sel_hi:[1,0]
	v_pk_mul_f32 v[120:121], v[120:121], v[142:143] op_sel_hi:[1,0]
	v_pk_mul_f32 v[118:119], v[118:119], v[142:143] op_sel_hi:[1,0]
	s_waitcnt vmcnt(0)
	v_fmamk_f32 v142, v205, 0x39800000, v246
	v_cmp_gt_f32_e32 vcc, s95, v142
	v_mul_f32_e32 v143, 0x4b800000, v142
	s_nop 0
	v_cndmask_b32_e32 v142, v142, v143, vcc
	v_rsq_f32_e32 v142, v142
	s_nop 0
	v_mul_f32_e32 v143, 0x45800000, v142
	v_cndmask_b32_e32 v142, v142, v143, vcc
	v_pk_mul_f32 v[116:117], v[116:117], v[142:143] op_sel_hi:[1,0]
	v_pk_mul_f32 v[114:115], v[114:115], v[142:143] op_sel_hi:[1,0]
	v_pk_mul_f32 v[112:113], v[112:113], v[142:143] op_sel_hi:[1,0]
	v_pk_mul_f32 v[110:111], v[110:111], v[142:143] op_sel_hi:[1,0]
	v_pk_mul_f32 v[108:109], v[108:109], v[142:143] op_sel_hi:[1,0]
	v_pk_mul_f32 v[106:107], v[106:107], v[142:143] op_sel_hi:[1,0]
	v_pk_mul_f32 v[104:105], v[104:105], v[142:143] op_sel_hi:[1,0]
	v_pk_mul_f32 v[102:103], v[102:103], v[142:143] op_sel_hi:[1,0]
	s_waitcnt vmcnt(0)
	v_fmamk_f32 v142, v204, 0x39800000, v246
	v_cmp_gt_f32_e32 vcc, s95, v142
	v_mul_f32_e32 v143, 0x4b800000, v142
	s_nop 0
	v_cndmask_b32_e32 v142, v142, v143, vcc
	v_rsq_f32_e32 v142, v142
	s_nop 0
	v_mul_f32_e32 v143, 0x45800000, v142
	v_cndmask_b32_e32 v142, v142, v143, vcc
	v_pk_mul_f32 v[150:151], v[94:95], v[142:143] op_sel_hi:[1,0]
	v_pk_mul_f32 v[152:153], v[98:99], v[142:143] op_sel_hi:[1,0]
	v_pk_mul_f32 v[100:101], v[100:101], v[142:143] op_sel_hi:[1,0]
	v_pk_mul_f32 v[92:93], v[92:93], v[142:143] op_sel_hi:[1,0]
	v_pk_mul_f32 v[90:91], v[90:91], v[142:143] op_sel_hi:[1,0]
	v_pk_mul_f32 v[86:87], v[86:87], v[142:143] op_sel_hi:[1,0]
	v_pk_mul_f32 v[96:97], v[96:97], v[142:143] op_sel_hi:[1,0]
	v_pk_mul_f32 v[88:89], v[88:89], v[142:143] op_sel_hi:[1,0]
	s_waitcnt vmcnt(0)
	v_fmamk_f32 v94, v203, 0x39800000, v246
	v_cmp_gt_f32_e32 vcc, s95, v94
	v_mul_f32_e32 v95, 0x4b800000, v94
	s_nop 0
	v_cndmask_b32_e32 v94, v94, v95, vcc
	v_rsq_f32_e32 v94, v94
	s_nop 0
	v_mul_f32_e32 v95, 0x45800000, v94
	v_cndmask_b32_e32 v94, v94, v95, vcc
	v_pk_mul_f32 v[164:165], v[80:81], v[94:95] op_sel_hi:[1,0]
	v_pk_mul_f32 v[80:81], v[74:75], v[94:95] op_sel_hi:[1,0]
	v_pk_mul_f32 v[166:167], v[84:85], v[94:95] op_sel_hi:[1,0]
	v_pk_mul_f32 v[170:171], v[82:83], v[94:95] op_sel_hi:[1,0]
	v_pk_mul_f32 v[168:169], v[78:79], v[94:95] op_sel_hi:[1,0]
	v_pk_mul_f32 v[78:79], v[76:77], v[94:95] op_sel_hi:[1,0]
	v_pk_mul_f32 v[72:73], v[72:73], v[94:95] op_sel_hi:[1,0]
	v_pk_mul_f32 v[70:71], v[70:71], v[94:95] op_sel_hi:[1,0]
	s_waitcnt vmcnt(0)
	v_fmamk_f32 v74, v202, 0x39800000, v246
	v_cmp_gt_f32_e32 vcc, s95, v74
	v_mul_f32_e32 v75, 0x4b800000, v74
	s_nop 0
	v_cndmask_b32_e32 v74, v74, v75, vcc
	v_rsq_f32_e32 v74, v74
	s_nop 0
	v_mul_f32_e32 v75, 0x45800000, v74
	v_cndmask_b32_e32 v98, v74, v75, vcc
	v_pk_mul_f32 v[76:77], v[68:69], v[98:99] op_sel_hi:[1,0]
	v_pk_mul_f32 v[176:177], v[66:67], v[98:99] op_sel_hi:[1,0]
	v_pk_mul_f32 v[74:75], v[64:65], v[98:99] op_sel_hi:[1,0]
	v_pk_mul_f32 v[174:175], v[62:63], v[98:99] op_sel_hi:[1,0]
	v_pk_mul_f32 v[84:85], v[60:61], v[98:99] op_sel_hi:[1,0]
	v_pk_mul_f32 v[94:95], v[58:59], v[98:99] op_sel_hi:[1,0]
	v_pk_mul_f32 v[82:83], v[56:57], v[98:99] op_sel_hi:[1,0]
	v_pk_mul_f32 v[98:99], v[54:55], v[98:99] op_sel_hi:[1,0]
	s_waitcnt vmcnt(0)
	v_fmamk_f32 v54, v201, 0x39800000, v246
	v_cmp_gt_f32_e32 vcc, s95, v54
	v_mul_f32_e32 v55, 0x4b800000, v54
	s_nop 0
	v_cndmask_b32_e32 v54, v54, v55, vcc
	v_rsq_f32_e32 v54, v54
	s_nop 0
	v_mul_f32_e32 v55, 0x45800000, v54
	v_cndmask_b32_e32 v54, v54, v55, vcc
	v_pk_mul_f32 v[146:147], v[38:39], v[54:55] op_sel_hi:[1,0]
	v_pk_mul_f32 v[180:181], v[52:53], v[54:55] op_sel_hi:[1,0]
	v_pk_mul_f32 v[184:185], v[50:51], v[54:55] op_sel_hi:[1,0]
	v_pk_mul_f32 v[144:145], v[44:45], v[54:55] op_sel_hi:[1,0]
	v_pk_mul_f32 v[148:149], v[42:43], v[54:55] op_sel_hi:[1,0]
	v_pk_mul_f32 v[182:183], v[46:47], v[54:55] op_sel_hi:[1,0]
	v_pk_mul_f32 v[178:179], v[48:49], v[54:55] op_sel_hi:[1,0]
	v_pk_mul_f32 v[142:143], v[40:41], v[54:55] op_sel_hi:[1,0]
	s_waitcnt vmcnt(0)
	v_fmamk_f32 v38, v200, 0x39800000, v246
	v_cmp_gt_f32_e32 vcc, s95, v38
	v_mul_f32_e32 v39, 0x4b800000, v38
	s_nop 0
	v_cndmask_b32_e32 v38, v38, v39, vcc
	v_rsq_f32_e32 v38, v38
	s_nop 0
	v_mul_f32_e32 v39, 0x45800000, v38
	v_cndmask_b32_e32 v38, v38, v39, vcc
	v_pk_mul_f32 v[160:161], v[22:23], v[38:39] op_sel_hi:[1,0]
	v_pk_mul_f32 v[188:189], v[36:37], v[38:39] op_sel_hi:[1,0]
	v_pk_mul_f32 v[192:193], v[34:35], v[38:39] op_sel_hi:[1,0]
	v_pk_mul_f32 v[158:159], v[28:29], v[38:39] op_sel_hi:[1,0]
	v_pk_mul_f32 v[162:163], v[26:27], v[38:39] op_sel_hi:[1,0]
	v_pk_mul_f32 v[186:187], v[32:33], v[38:39] op_sel_hi:[1,0]
	v_pk_mul_f32 v[190:191], v[30:31], v[38:39] op_sel_hi:[1,0]
	v_pk_mul_f32 v[156:157], v[24:25], v[38:39] op_sel_hi:[1,0]
	v_mul_f32_e32 v24, v95, v95
	v_mul_f32_e32 v25, v85, v85
	v_mul_f32_e32 v26, v185, v185
	v_mul_f32_e32 v27, v181, v181
	v_mul_f32_e32 v28, v149, v149
	v_mul_f32_e32 v29, v145, v145
	v_mul_f32_e32 v30, v193, v193
	v_mul_f32_e32 v31, v189, v189
	v_mul_f32_e32 v32, v163, v163
	v_mul_f32_e32 v33, v159, v159
	v_fmac_f32_e32 v24, v94, v94
	v_fmac_f32_e32 v25, v84, v84
	v_fmac_f32_e32 v26, v184, v184
	v_fmac_f32_e32 v27, v180, v180
	v_fmac_f32_e32 v28, v148, v148
	v_fmac_f32_e32 v29, v144, v144
	v_fmac_f32_e32 v30, v192, v192
	v_fmac_f32_e32 v31, v188, v188
	v_fmac_f32_e32 v32, v162, v162
	v_fmac_f32_e32 v33, v158, v158
	v_add_f32_e32 v24, v24, v25
	v_mul_f32_e32 v25, v99, v99
	v_add_f32_e32 v26, v26, v27
	v_mul_f32_e32 v27, v183, v183
	v_add_f32_e32 v28, v28, v29
	v_mul_f32_e32 v29, v147, v147
	v_add_f32_e32 v30, v30, v31
	v_mul_f32_e32 v31, v191, v191
	v_add_f32_e32 v32, v32, v33
	v_mul_f32_e32 v33, v161, v161
	v_fmac_f32_e32 v25, v98, v98
	v_fmac_f32_e32 v27, v182, v182
	v_fmac_f32_e32 v29, v146, v146
	v_fmac_f32_e32 v31, v190, v190
	v_fmac_f32_e32 v33, v160, v160
	v_add_f32_e32 v24, v25, v24
	v_mul_f32_e32 v25, v83, v83
	v_add_f32_e32 v26, v27, v26
	v_mul_f32_e32 v27, v179, v179
	v_add_f32_e32 v28, v29, v28
	v_mul_f32_e32 v29, v143, v143
	v_add_f32_e32 v30, v31, v30
	v_mul_f32_e32 v31, v187, v187
	v_add_f32_e32 v32, v33, v32
	v_mul_f32_e32 v33, v157, v157
	v_fmac_f32_e32 v25, v82, v82
	v_fmac_f32_e32 v27, v178, v178
	v_fmac_f32_e32 v29, v142, v142
	v_fmac_f32_e32 v31, v186, v186
	v_fmac_f32_e32 v33, v156, v156
	v_add_f32_e32 v24, v25, v24
	v_add_f32_e32 v26, v27, v26
	v_add_f32_e32 v28, v29, v28
	v_add_f32_e32 v30, v31, v30
	v_add_f32_e32 v32, v33, v32
	ds_swizzle_b32 v25, v24 offset:swizzle(SWAP,16)
	ds_swizzle_b32 v27, v26 offset:swizzle(SWAP,16)
	ds_swizzle_b32 v29, v28 offset:swizzle(SWAP,16)
	ds_swizzle_b32 v31, v30 offset:swizzle(SWAP,16)
	ds_swizzle_b32 v33, v32 offset:swizzle(SWAP,16)
	s_waitcnt lgkmcnt(4)
	v_add_f32_e32 v24, v24, v25
	s_waitcnt lgkmcnt(3)
	v_add_f32_e32 v26, v26, v27
	s_waitcnt lgkmcnt(2)
	v_add_f32_e32 v28, v28, v29
	s_waitcnt lgkmcnt(1)
	v_add_f32_e32 v30, v30, v31
	s_waitcnt lgkmcnt(0)
	v_add_f32_e32 v32, v32, v33
	v_mov_b32_e32 v25, v24
	v_mov_b32_e32 v27, v26
	v_mov_b32_e32 v29, v28
	v_mov_b32_e32 v31, v30
	v_mov_b32_e32 v33, v32
	v_permlane32_swap_b32_e32 v24, v25
	s_waitcnt vmcnt(0)
	v_fmamk_f32 v22, v199, 0x39800000, v246
	v_cmp_gt_f32_e32 vcc, s95, v22
	v_mul_f32_e32 v23, 0x4b800000, v22
	v_permlane32_swap_b32_e32 v26, v27
	v_cndmask_b32_e32 v22, v22, v23, vcc
	v_rsq_f32_e32 v22, v22
	v_permlane32_swap_b32_e32 v28, v29
	v_permlane32_swap_b32_e32 v30, v31
	v_mul_f32_e32 v23, 0x45800000, v22
	v_cndmask_b32_e32 v22, v22, v23, vcc
	v_pk_mul_f32 v[202:203], v[20:21], v[22:23] op_sel_hi:[1,0]
	v_pk_mul_f32 v[204:205], v[18:19], v[22:23] op_sel_hi:[1,0]
	v_pk_mul_f32 v[194:195], v[12:13], v[22:23] op_sel_hi:[1,0]
	v_pk_mul_f32 v[196:197], v[10:11], v[22:23] op_sel_hi:[1,0]
	v_pk_mul_f32 v[206:207], v[16:17], v[22:23] op_sel_hi:[1,0]
	v_pk_mul_f32 v[208:209], v[14:15], v[22:23] op_sel_hi:[1,0]
	v_pk_mul_f32 v[198:199], v[8:9], v[22:23] op_sel_hi:[1,0]
	v_pk_mul_f32 v[200:201], v[6:7], v[22:23] op_sel_hi:[1,0]
	v_mul_f32_e32 v6, v131, v131
	v_mul_f32_e32 v7, v133, v133
	v_mul_f32_e32 v8, v123, v123
	v_mul_f32_e32 v9, v125, v125
	v_mul_f32_e32 v10, v115, v115
	v_mul_f32_e32 v11, v117, v117
	v_mul_f32_e32 v12, v107, v107
	v_mul_f32_e32 v13, v109, v109
	v_mul_f32_e32 v14, v153, v153
	v_mul_f32_e32 v15, v101, v101
	v_mul_f32_e32 v16, v91, v91
	v_mul_f32_e32 v17, v93, v93
	v_mul_f32_e32 v18, v171, v171
	v_mul_f32_e32 v19, v167, v167
	v_mul_f32_e32 v20, v81, v81
	v_mul_f32_e32 v21, v79, v79
	v_mul_f32_e32 v22, v177, v177
	v_mul_f32_e32 v23, v77, v77
	v_mul_f32_e32 v34, v205, v205
	v_mul_f32_e32 v35, v203, v203
	v_mul_f32_e32 v36, v197, v197
	v_mul_f32_e32 v37, v195, v195
	v_fmac_f32_e32 v6, v130, v130
	v_fmac_f32_e32 v7, v132, v132
	v_fmac_f32_e32 v8, v122, v122
	v_fmac_f32_e32 v9, v124, v124
	v_fmac_f32_e32 v10, v114, v114
	v_fmac_f32_e32 v11, v116, v116
	v_fmac_f32_e32 v12, v106, v106
	v_fmac_f32_e32 v13, v108, v108
	v_fmac_f32_e32 v14, v152, v152
	v_fmac_f32_e32 v15, v100, v100
	v_fmac_f32_e32 v16, v90, v90
	v_fmac_f32_e32 v17, v92, v92
	v_fmac_f32_e32 v18, v170, v170
	v_fmac_f32_e32 v19, v166, v166
	v_fmac_f32_e32 v20, v80, v80
	v_fmac_f32_e32 v21, v78, v78
	v_fmac_f32_e32 v22, v176, v176
	v_fmac_f32_e32 v23, v76, v76
	v_fmac_f32_e32 v34, v204, v204
	v_fmac_f32_e32 v35, v202, v202
	v_fmac_f32_e32 v36, v196, v196
	v_fmac_f32_e32 v37, v194, v194
	v_add_f32_e32 v6, v6, v7
	v_mul_f32_e32 v7, v127, v127
	v_add_f32_e32 v8, v8, v9
	v_mul_f32_e32 v9, v119, v119
	v_add_f32_e32 v10, v10, v11
	v_mul_f32_e32 v11, v111, v111
	v_add_f32_e32 v12, v12, v13
	v_mul_f32_e32 v13, v103, v103
	v_add_f32_e32 v14, v14, v15
	v_mul_f32_e32 v15, v151, v151
	v_add_f32_e32 v16, v16, v17
	v_mul_f32_e32 v17, v87, v87
	v_add_f32_e32 v18, v18, v19
	v_mul_f32_e32 v19, v169, v169
	v_add_f32_e32 v20, v20, v21
	v_mul_f32_e32 v21, v71, v71
	v_add_f32_e32 v22, v22, v23
	v_mul_f32_e32 v23, v175, v175
	v_add_f32_e32 v34, v34, v35
	v_mul_f32_e32 v35, v209, v209
	v_add_f32_e32 v36, v36, v37
	v_mul_f32_e32 v37, v201, v201
	v_fmac_f32_e32 v7, v126, v126
	v_fmac_f32_e32 v9, v118, v118
	v_fmac_f32_e32 v11, v110, v110
	v_fmac_f32_e32 v13, v102, v102
	v_fmac_f32_e32 v15, v150, v150
	v_fmac_f32_e32 v17, v86, v86
	v_fmac_f32_e32 v19, v168, v168
	v_fmac_f32_e32 v21, v70, v70
	v_fmac_f32_e32 v23, v174, v174
	v_fmac_f32_e32 v35, v208, v208
	v_fmac_f32_e32 v37, v200, v200
	v_add_f32_e32 v6, v7, v6
	v_mul_f32_e32 v7, v129, v129
	v_add_f32_e32 v8, v9, v8
	v_mul_f32_e32 v9, v121, v121
	v_add_f32_e32 v10, v11, v10
	v_mul_f32_e32 v11, v113, v113
	v_add_f32_e32 v12, v13, v12
	v_mul_f32_e32 v13, v105, v105
	v_add_f32_e32 v14, v15, v14
	v_mul_f32_e32 v15, v97, v97
	v_add_f32_e32 v16, v17, v16
	v_mul_f32_e32 v17, v89, v89
	v_add_f32_e32 v18, v19, v18
	v_mul_f32_e32 v19, v165, v165
	v_add_f32_e32 v20, v21, v20
	v_mul_f32_e32 v21, v73, v73
	v_add_f32_e32 v22, v23, v22
	v_mul_f32_e32 v23, v75, v75
	v_add_f32_e32 v34, v35, v34
	v_mul_f32_e32 v35, v207, v207
	v_add_f32_e32 v36, v37, v36
	v_mul_f32_e32 v37, v199, v199
	v_fmac_f32_e32 v7, v128, v128
	v_fmac_f32_e32 v9, v120, v120
	v_fmac_f32_e32 v11, v112, v112
	v_fmac_f32_e32 v13, v104, v104
	v_fmac_f32_e32 v15, v96, v96
	v_fmac_f32_e32 v17, v88, v88
	v_fmac_f32_e32 v19, v164, v164
	v_fmac_f32_e32 v21, v72, v72
	v_fmac_f32_e32 v23, v74, v74
	v_fmac_f32_e32 v35, v206, v206
	v_fmac_f32_e32 v37, v198, v198
	v_add_f32_e32 v6, v7, v6
	v_add_f32_e32 v8, v9, v8
	v_add_f32_e32 v10, v11, v10
	v_add_f32_e32 v12, v13, v12
	v_add_f32_e32 v14, v15, v14
	v_add_f32_e32 v16, v17, v16
	v_add_f32_e32 v18, v19, v18
	v_add_f32_e32 v20, v21, v20
	v_add_f32_e32 v22, v23, v22
	v_add_f32_e32 v34, v35, v34
	v_add_f32_e32 v36, v37, v36
	ds_swizzle_b32 v7, v6 offset:swizzle(SWAP,16)
	ds_swizzle_b32 v9, v8 offset:swizzle(SWAP,16)
	ds_swizzle_b32 v11, v10 offset:swizzle(SWAP,16)
	ds_swizzle_b32 v13, v12 offset:swizzle(SWAP,16)
	ds_swizzle_b32 v15, v14 offset:swizzle(SWAP,16)
	ds_swizzle_b32 v17, v16 offset:swizzle(SWAP,16)
	ds_swizzle_b32 v19, v18 offset:swizzle(SWAP,16)
	ds_swizzle_b32 v21, v20 offset:swizzle(SWAP,16)
	ds_swizzle_b32 v23, v22 offset:swizzle(SWAP,16)
	ds_swizzle_b32 v35, v34 offset:swizzle(SWAP,16)
	ds_swizzle_b32 v37, v36 offset:swizzle(SWAP,16)
	s_waitcnt lgkmcnt(10)
	v_add_f32_e32 v6, v6, v7
	s_waitcnt lgkmcnt(9)
	v_add_f32_e32 v8, v8, v9
	s_waitcnt lgkmcnt(8)
	v_add_f32_e32 v10, v10, v11
	s_waitcnt lgkmcnt(7)
	v_add_f32_e32 v12, v12, v13
	s_waitcnt lgkmcnt(6)
	v_add_f32_e32 v14, v14, v15
	s_waitcnt lgkmcnt(5)
	v_add_f32_e32 v16, v16, v17
	s_waitcnt lgkmcnt(4)
	v_add_f32_e32 v18, v18, v19
	s_waitcnt lgkmcnt(3)
	v_add_f32_e32 v20, v20, v21
	s_waitcnt lgkmcnt(2)
	v_add_f32_e32 v22, v22, v23
	s_waitcnt lgkmcnt(1)
	v_add_f32_e32 v34, v34, v35
	s_waitcnt lgkmcnt(0)
	v_add_f32_e32 v36, v36, v37
	v_mov_b32_e32 v7, v6
	v_mov_b32_e32 v9, v8
	v_mov_b32_e32 v11, v10
	v_mov_b32_e32 v13, v12
	v_mov_b32_e32 v15, v14
	v_mov_b32_e32 v17, v16
	v_mov_b32_e32 v19, v18
	v_mov_b32_e32 v21, v20
	v_mov_b32_e32 v23, v22
	v_mov_b32_e32 v35, v34
	v_mov_b32_e32 v37, v36
	v_permlane32_swap_b32_e32 v6, v7
	v_permlane32_swap_b32_e32 v8, v9
	v_permlane32_swap_b32_e32 v10, v11
	v_permlane32_swap_b32_e32 v12, v13
	v_permlane32_swap_b32_e32 v14, v15
	v_permlane32_swap_b32_e32 v16, v17
	v_permlane32_swap_b32_e32 v18, v19
	v_permlane32_swap_b32_e32 v20, v21
	v_permlane32_swap_b32_e32 v22, v23
	v_permlane32_swap_b32_e32 v32, v33
	v_permlane32_swap_b32_e32 v34, v35
	v_permlane32_swap_b32_e32 v36, v37
	v_cmp_eq_u32_e32 vcc, 0, v210
	s_and_saveexec_b64 s[30:31], vcc
	s_cbranch_execz .LBB0_349
	s_and_b64 s[52:53], s[28:29], exec
	s_mov_b32 s1, 0x31000
	s_cselect_b32 s1, s1, 0x20800
	s_add_u32 s1, s24, s1
	s_addc_u32 s2, s25, 0
	s_add_u32 s52, s1, s6
	v_add_f32_e32 v8, v8, v9
	v_add_f32_e32 v9, v6, v7
	s_addc_u32 s53, s2, s7
	v_add_f32_e32 v12, v12, v13
	v_add_f32_e32 v10, v10, v11
	v_lshl_add_u64 v[6:7], v[140:141], 2, s[52:53]
	v_add_f32_e32 v8, v9, v8
	v_add_f32_e32 v16, v16, v17
	v_add_f32_e32 v14, v14, v15
	global_atomic_add_f32 v[6:7], v8, off
	v_add_f32_e32 v8, v10, v12
	v_add_f32_e32 v20, v20, v21
	v_add_f32_e32 v18, v18, v19
	global_atomic_add_f32 v[6:7], v8, off offset:64
	v_add_f32_e32 v8, v14, v16
	v_add_f32_e32 v24, v24, v25
	v_add_f32_e32 v22, v22, v23
	global_atomic_add_f32 v[6:7], v8, off offset:128
	v_add_f32_e32 v8, v18, v20
	v_add_f32_e32 v28, v28, v29
	v_add_f32_e32 v26, v26, v27
	global_atomic_add_f32 v[6:7], v8, off offset:192
	v_add_f32_e32 v8, v22, v24
	v_add_f32_e32 v32, v32, v33
	v_add_f32_e32 v30, v30, v31
	global_atomic_add_f32 v[6:7], v8, off offset:512
	v_add_f32_e32 v8, v26, v28
	v_add_f32_e32 v36, v36, v37
	v_add_f32_e32 v34, v34, v35
	global_atomic_add_f32 v[6:7], v8, off offset:576
	v_add_f32_e32 v8, v30, v32
	global_atomic_add_f32 v[6:7], v8, off offset:640
	v_add_f32_e32 v8, v34, v36
	global_atomic_add_f32 v[6:7], v8, off offset:704

.LBB0_454:
	s_add_u32 s66, s62, 0xffffff80
	s_addc_u32 s67, s63, -1
	s_cmp_eq_u32 s64, 12
	s_cselect_b32 s38, s21, s62
	s_cselect_b32 s39, s3, s63
	s_cselect_b32 s41, s23, s61
	s_cselect_b32 s40, s31, s33
	s_add_u32 s34, s38, 0x80
	s_addc_u32 s35, s39, 0
	s_add_u32 s36, s40, 0x80
	s_addc_u32 s37, s41, 0
	s_add_i32 s65, 0, 0x10000
	s_add_i32 s68, 0, 0x14000
	v_add_u32_e32 v152, s65, v1
	v_add_u32_e32 v168, s68, v1
	ds_read_b128 v[140:143], v152
	ds_read_b128 v[144:147], v152 offset:1024
	ds_read_b128 v[148:151], v152 offset:2048
	ds_read_b128 v[152:155], v152 offset:3072
	ds_read_b128 v[156:159], v168
	ds_read_b128 v[160:163], v168 offset:1024
	ds_read_b128 v[164:167], v168 offset:2048
	ds_read_b128 v[168:171], v168 offset:3072
	s_add_u32 s66, s66, 0x40000
	s_addc_u32 s67, s67, 0
	v_lshl_add_u64 v[204:205], s[66:67], 0, v[2:3]
	s_add_i32 m0, s29, 0xc000
	ds_read_b128 v[172:175], v5
	ds_read_b128 v[176:179], v5 offset:1024
	ds_read_b128 v[180:183], v5 offset:2048
	ds_read_b128 v[184:187], v5 offset:3072
	ds_read_b128 v[188:191], v5 offset:4096
	ds_read_b128 v[192:195], v5 offset:5120
	ds_read_b128 v[196:199], v5 offset:6144
	ds_read_b128 v[200:203], v5 offset:7168
	global_load_lds_dwordx4 v[204:205], off
	v_lshl_add_u64 v[204:205], s[66:67], 0, v[136:137]
	s_add_i32 m0, s29, 0xe000
	s_nop 0
	global_load_lds_dwordx4 v[204:205], off
	s_waitcnt vmcnt(8)
	s_waitcnt lgkmcnt(0)
	s_barrier
	v_mfma_f32_16x16x32_bf16 v[130:133], v[140:143], v[172:175], v[130:133]
	v_mfma_f32_16x16x32_bf16 v[126:129], v[148:151], v[172:175], v[126:129]
	v_mfma_f32_16x16x32_bf16 v[114:117], v[140:143], v[180:183], v[114:117]
	v_mfma_f32_16x16x32_bf16 v[110:113], v[148:151], v[180:183], v[110:113]
	v_mfma_f32_16x16x32_bf16 v[98:101], v[140:143], v[188:191], v[98:101]
	v_mfma_f32_16x16x32_bf16 v[94:97], v[148:151], v[188:191], v[94:97]
	v_mfma_f32_16x16x32_bf16 v[82:85], v[140:143], v[196:199], v[82:85]
	v_mfma_f32_16x16x32_bf16 v[78:81], v[148:151], v[196:199], v[78:81]
	v_mfma_f32_16x16x32_bf16 v[130:133], v[144:147], v[176:179], v[130:133]
	v_mfma_f32_16x16x32_bf16 v[126:129], v[152:155], v[176:179], v[126:129]
	v_mfma_f32_16x16x32_bf16 v[114:117], v[144:147], v[184:187], v[114:117]
	v_mfma_f32_16x16x32_bf16 v[110:113], v[152:155], v[184:187], v[110:113]
	v_mfma_f32_16x16x32_bf16 v[98:101], v[144:147], v[192:195], v[98:101]
	v_mfma_f32_16x16x32_bf16 v[94:97], v[152:155], v[192:195], v[94:97]
	v_mfma_f32_16x16x32_bf16 v[82:85], v[144:147], v[200:203], v[82:85]
	v_mfma_f32_16x16x32_bf16 v[78:81], v[152:155], v[200:203], v[78:81]
	v_mfma_f32_16x16x32_bf16 v[122:125], v[156:159], v[172:175], v[122:125]
	v_mfma_f32_16x16x32_bf16 v[118:121], v[164:167], v[172:175], v[118:121]
	v_mfma_f32_16x16x32_bf16 v[106:109], v[156:159], v[180:183], v[106:109]
	v_mfma_f32_16x16x32_bf16 v[102:105], v[164:167], v[180:183], v[102:105]
	v_mfma_f32_16x16x32_bf16 v[90:93], v[156:159], v[188:191], v[90:93]
	v_mfma_f32_16x16x32_bf16 v[86:89], v[164:167], v[188:191], v[86:89]
	v_mfma_f32_16x16x32_bf16 v[74:77], v[156:159], v[196:199], v[74:77]
	v_mfma_f32_16x16x32_bf16 v[70:73], v[164:167], v[196:199], v[70:73]
	v_mfma_f32_16x16x32_bf16 v[122:125], v[160:163], v[176:179], v[122:125]
	v_mfma_f32_16x16x32_bf16 v[118:121], v[168:171], v[176:179], v[118:121]
	v_mfma_f32_16x16x32_bf16 v[106:109], v[160:163], v[184:187], v[106:109]
	v_mfma_f32_16x16x32_bf16 v[102:105], v[168:171], v[184:187], v[102:105]
	v_mfma_f32_16x16x32_bf16 v[90:93], v[160:163], v[192:195], v[90:93]
	v_mfma_f32_16x16x32_bf16 v[86:89], v[168:171], v[192:195], v[86:89]
	v_mfma_f32_16x16x32_bf16 v[74:77], v[160:163], v[200:203], v[74:77]
	v_mfma_f32_16x16x32_bf16 v[70:73], v[168:171], v[200:203], v[70:73]
	s_barrier
	s_add_i32 s65, s65, s46
	v_lshl_add_u64 v[204:205], s[40:41], 0, v[134:135]
	s_mov_b32 m0, s65
	ds_read_b128 v[172:175], v5 offset:16384
	ds_read_b128 v[176:179], v5 offset:17408
	ds_read_b128 v[180:183], v5 offset:18432
	ds_read_b128 v[184:187], v5 offset:19456
	ds_read_b128 v[188:191], v5 offset:20480
	ds_read_b128 v[192:195], v5 offset:21504
	ds_read_b128 v[196:199], v5 offset:22528
	ds_read_b128 v[200:203], v5 offset:23552
	global_load_lds_dwordx4 v[204:205], off
	s_add_i32 m0, s65, 0x2000
	v_lshl_add_u64 v[204:205], s[40:41], 0, v[138:139]
	s_add_u32 s40, s40, 0x40000
	s_addc_u32 s41, s41, 0
	s_add_i32 s65, s68, s46
	global_load_lds_dwordx4 v[204:205], off
	v_lshl_add_u64 v[204:205], s[40:41], 0, v[134:135]
	s_mov_b32 m0, s65
	s_nop 0
	global_load_lds_dwordx4 v[204:205], off
	v_lshl_add_u64 v[204:205], s[40:41], 0, v[138:139]
	s_add_i32 m0, s65, 0x2000
	s_nop 0
	global_load_lds_dwordx4 v[204:205], off
	v_lshl_add_u64 v[204:205], s[38:39], 0, v[2:3]
	s_mov_b32 m0, s29
	s_nop 0
	global_load_lds_dwordx4 v[204:205], off
	v_lshl_add_u64 v[204:205], s[38:39], 0, v[136:137]
	s_mov_b32 m0, s51
	s_nop 0
	global_load_lds_dwordx4 v[204:205], off
	s_waitcnt vmcnt(8)
	s_waitcnt lgkmcnt(0)
	s_barrier
	v_mfma_f32_16x16x32_bf16 v[66:69], v[140:143], v[172:175], v[66:69]
	v_mfma_f32_16x16x32_bf16 v[62:65], v[148:151], v[172:175], v[62:65]
	v_mfma_f32_16x16x32_bf16 v[50:53], v[140:143], v[180:183], v[50:53]
	v_mfma_f32_16x16x32_bf16 v[46:49], v[148:151], v[180:183], v[46:49]
	v_mfma_f32_16x16x32_bf16 v[34:37], v[140:143], v[188:191], v[34:37]
	v_mfma_f32_16x16x32_bf16 v[30:33], v[148:151], v[188:191], v[30:33]
	v_mfma_f32_16x16x32_bf16 v[18:21], v[140:143], v[196:199], v[18:21]
	v_mfma_f32_16x16x32_bf16 v[14:17], v[148:151], v[196:199], v[14:17]
	v_mfma_f32_16x16x32_bf16 v[66:69], v[144:147], v[176:179], v[66:69]
	v_mfma_f32_16x16x32_bf16 v[62:65], v[152:155], v[176:179], v[62:65]
	v_mfma_f32_16x16x32_bf16 v[50:53], v[144:147], v[184:187], v[50:53]
	v_mfma_f32_16x16x32_bf16 v[46:49], v[152:155], v[184:187], v[46:49]
	v_mfma_f32_16x16x32_bf16 v[34:37], v[144:147], v[192:195], v[34:37]
	v_mfma_f32_16x16x32_bf16 v[30:33], v[152:155], v[192:195], v[30:33]
	v_mfma_f32_16x16x32_bf16 v[18:21], v[144:147], v[200:203], v[18:21]
	v_mfma_f32_16x16x32_bf16 v[14:17], v[152:155], v[200:203], v[14:17]
	v_mfma_f32_16x16x32_bf16 v[58:61], v[156:159], v[172:175], v[58:61]
	v_mfma_f32_16x16x32_bf16 v[54:57], v[164:167], v[172:175], v[54:57]
	v_mfma_f32_16x16x32_bf16 v[42:45], v[156:159], v[180:183], v[42:45]
	v_mfma_f32_16x16x32_bf16 v[38:41], v[164:167], v[180:183], v[38:41]
	v_mfma_f32_16x16x32_bf16 v[26:29], v[156:159], v[188:191], v[26:29]
	v_mfma_f32_16x16x32_bf16 v[22:25], v[164:167], v[188:191], v[22:25]
	v_mfma_f32_16x16x32_bf16 v[10:13], v[156:159], v[196:199], v[10:13]
	v_mfma_f32_16x16x32_bf16 v[6:9], v[164:167], v[196:199], v[6:9]
	v_mfma_f32_16x16x32_bf16 v[58:61], v[160:163], v[176:179], v[58:61]
	v_mfma_f32_16x16x32_bf16 v[54:57], v[168:171], v[176:179], v[54:57]
	v_mfma_f32_16x16x32_bf16 v[42:45], v[160:163], v[184:187], v[42:45]
	v_mfma_f32_16x16x32_bf16 v[38:41], v[168:171], v[184:187], v[38:41]
	v_mfma_f32_16x16x32_bf16 v[26:29], v[160:163], v[192:195], v[26:29]
	v_mfma_f32_16x16x32_bf16 v[22:25], v[168:171], v[192:195], v[22:25]
	v_mfma_f32_16x16x32_bf16 v[10:13], v[160:163], v[200:203], v[10:13]
	v_mfma_f32_16x16x32_bf16 v[6:9], v[168:171], v[200:203], v[6:9]
	s_barrier
	s_add_i32 s40, 0, 0x18000
	s_add_i32 s41, 0, 0x1c000
	v_add_u32_e32 v152, s40, v1
	v_add_u32_e32 v168, s41, v1
	ds_read_b128 v[140:143], v152
	ds_read_b128 v[144:147], v152 offset:1024
	ds_read_b128 v[148:151], v152 offset:2048
	ds_read_b128 v[152:155], v152 offset:3072
	ds_read_b128 v[156:159], v168
	ds_read_b128 v[160:163], v168 offset:1024
	ds_read_b128 v[164:167], v168 offset:2048
	ds_read_b128 v[168:171], v168 offset:3072
	s_add_u32 s38, s38, 0x40000
	s_addc_u32 s39, s39, 0
	s_mov_b32 m0, s52
	v_lshl_add_u64 v[204:205], s[38:39], 0, v[2:3]
	ds_read_b128 v[172:175], v5 offset:32768
	ds_read_b128 v[176:179], v5 offset:33792
	ds_read_b128 v[180:183], v5 offset:34816
	ds_read_b128 v[184:187], v5 offset:35840
	ds_read_b128 v[188:191], v5 offset:36864
	ds_read_b128 v[192:195], v5 offset:37888
	ds_read_b128 v[196:199], v5 offset:38912
	ds_read_b128 v[200:203], v5 offset:39936
	global_load_lds_dwordx4 v[204:205], off
	v_lshl_add_u64 v[204:205], s[38:39], 0, v[136:137]
	s_mov_b32 m0, s53
	s_nop 0
	global_load_lds_dwordx4 v[204:205], off
	s_waitcnt vmcnt(8)
	s_waitcnt lgkmcnt(0)
	s_barrier
	v_mfma_f32_16x16x32_bf16 v[130:133], v[140:143], v[172:175], v[130:133]
	v_mfma_f32_16x16x32_bf16 v[126:129], v[148:151], v[172:175], v[126:129]
	v_mfma_f32_16x16x32_bf16 v[114:117], v[140:143], v[180:183], v[114:117]
	v_mfma_f32_16x16x32_bf16 v[110:113], v[148:151], v[180:183], v[110:113]
	v_mfma_f32_16x16x32_bf16 v[98:101], v[140:143], v[188:191], v[98:101]
	v_mfma_f32_16x16x32_bf16 v[94:97], v[148:151], v[188:191], v[94:97]
	v_mfma_f32_16x16x32_bf16 v[82:85], v[140:143], v[196:199], v[82:85]
	v_mfma_f32_16x16x32_bf16 v[78:81], v[148:151], v[196:199], v[78:81]
	v_mfma_f32_16x16x32_bf16 v[130:133], v[144:147], v[176:179], v[130:133]
	v_mfma_f32_16x16x32_bf16 v[126:129], v[152:155], v[176:179], v[126:129]
	v_mfma_f32_16x16x32_bf16 v[114:117], v[144:147], v[184:187], v[114:117]
	v_mfma_f32_16x16x32_bf16 v[110:113], v[152:155], v[184:187], v[110:113]
	v_mfma_f32_16x16x32_bf16 v[98:101], v[144:147], v[192:195], v[98:101]
	v_mfma_f32_16x16x32_bf16 v[94:97], v[152:155], v[192:195], v[94:97]
	v_mfma_f32_16x16x32_bf16 v[82:85], v[144:147], v[200:203], v[82:85]
	v_mfma_f32_16x16x32_bf16 v[78:81], v[152:155], v[200:203], v[78:81]
	v_mfma_f32_16x16x32_bf16 v[122:125], v[156:159], v[172:175], v[122:125]
	v_mfma_f32_16x16x32_bf16 v[118:121], v[164:167], v[172:175], v[118:121]
	v_mfma_f32_16x16x32_bf16 v[106:109], v[156:159], v[180:183], v[106:109]
	v_mfma_f32_16x16x32_bf16 v[102:105], v[164:167], v[180:183], v[102:105]
	v_mfma_f32_16x16x32_bf16 v[90:93], v[156:159], v[188:191], v[90:93]
	v_mfma_f32_16x16x32_bf16 v[86:89], v[164:167], v[188:191], v[86:89]
	v_mfma_f32_16x16x32_bf16 v[74:77], v[156:159], v[196:199], v[74:77]
	v_mfma_f32_16x16x32_bf16 v[70:73], v[164:167], v[196:199], v[70:73]
	v_mfma_f32_16x16x32_bf16 v[122:125], v[160:163], v[176:179], v[122:125]
	v_mfma_f32_16x16x32_bf16 v[118:121], v[168:171], v[176:179], v[118:121]
	v_mfma_f32_16x16x32_bf16 v[106:109], v[160:163], v[184:187], v[106:109]
	v_mfma_f32_16x16x32_bf16 v[102:105], v[168:171], v[184:187], v[102:105]
	v_mfma_f32_16x16x32_bf16 v[90:93], v[160:163], v[192:195], v[90:93]
	v_mfma_f32_16x16x32_bf16 v[86:89], v[168:171], v[192:195], v[86:89]
	v_mfma_f32_16x16x32_bf16 v[74:77], v[160:163], v[200:203], v[74:77]
	v_mfma_f32_16x16x32_bf16 v[70:73], v[168:171], v[200:203], v[70:73]
	s_barrier
	s_add_i32 s38, s40, s46
	v_lshl_add_u64 v[204:205], s[36:37], 0, v[134:135]
	s_mov_b32 m0, s38
	ds_read_b128 v[172:175], v5 offset:49152
	ds_read_b128 v[176:179], v5 offset:50176
	ds_read_b128 v[180:183], v5 offset:51200
	ds_read_b128 v[184:187], v5 offset:52224
	ds_read_b128 v[188:191], v5 offset:53248
	ds_read_b128 v[192:195], v5 offset:54272
	ds_read_b128 v[196:199], v5 offset:55296
	ds_read_b128 v[200:203], v5 offset:56320
	global_load_lds_dwordx4 v[204:205], off
	s_add_i32 m0, s38, 0x2000
	v_lshl_add_u64 v[204:205], s[36:37], 0, v[138:139]
	s_add_u32 s36, s36, 0x40000
	s_addc_u32 s37, s37, 0
	s_add_i32 s38, s41, s46
	global_load_lds_dwordx4 v[204:205], off
	v_lshl_add_u64 v[204:205], s[36:37], 0, v[134:135]
	s_mov_b32 m0, s38
	s_nop 0
	global_load_lds_dwordx4 v[204:205], off
	v_lshl_add_u64 v[204:205], s[36:37], 0, v[138:139]
	s_add_i32 m0, s38, 0x2000
	s_nop 0
	global_load_lds_dwordx4 v[204:205], off
	v_lshl_add_u64 v[204:205], s[34:35], 0, v[2:3]
	s_mov_b32 m0, s56
	s_nop 0
	global_load_lds_dwordx4 v[204:205], off
	v_lshl_add_u64 v[204:205], s[34:35], 0, v[136:137]
	s_mov_b32 m0, s57
	s_nop 0
	global_load_lds_dwordx4 v[204:205], off
	s_waitcnt vmcnt(8)
	s_waitcnt lgkmcnt(0)
	s_barrier
	v_mfma_f32_16x16x32_bf16 v[66:69], v[140:143], v[172:175], v[66:69]
	v_mfma_f32_16x16x32_bf16 v[62:65], v[148:151], v[172:175], v[62:65]
	v_mfma_f32_16x16x32_bf16 v[50:53], v[140:143], v[180:183], v[50:53]
	v_mfma_f32_16x16x32_bf16 v[46:49], v[148:151], v[180:183], v[46:49]
	v_mfma_f32_16x16x32_bf16 v[34:37], v[140:143], v[188:191], v[34:37]
	v_mfma_f32_16x16x32_bf16 v[30:33], v[148:151], v[188:191], v[30:33]
	v_mfma_f32_16x16x32_bf16 v[18:21], v[140:143], v[196:199], v[18:21]
	v_mfma_f32_16x16x32_bf16 v[14:17], v[148:151], v[196:199], v[14:17]
	v_mfma_f32_16x16x32_bf16 v[66:69], v[144:147], v[176:179], v[66:69]
	v_mfma_f32_16x16x32_bf16 v[62:65], v[152:155], v[176:179], v[62:65]
	v_mfma_f32_16x16x32_bf16 v[50:53], v[144:147], v[184:187], v[50:53]
	v_mfma_f32_16x16x32_bf16 v[46:49], v[152:155], v[184:187], v[46:49]
	v_mfma_f32_16x16x32_bf16 v[34:37], v[144:147], v[192:195], v[34:37]
	v_mfma_f32_16x16x32_bf16 v[30:33], v[152:155], v[192:195], v[30:33]
	v_mfma_f32_16x16x32_bf16 v[18:21], v[144:147], v[200:203], v[18:21]
	v_mfma_f32_16x16x32_bf16 v[14:17], v[152:155], v[200:203], v[14:17]
	v_mfma_f32_16x16x32_bf16 v[58:61], v[156:159], v[172:175], v[58:61]
	v_mfma_f32_16x16x32_bf16 v[54:57], v[164:167], v[172:175], v[54:57]
	v_mfma_f32_16x16x32_bf16 v[42:45], v[156:159], v[180:183], v[42:45]
	v_mfma_f32_16x16x32_bf16 v[38:41], v[164:167], v[180:183], v[38:41]
	v_mfma_f32_16x16x32_bf16 v[26:29], v[156:159], v[188:191], v[26:29]
	v_mfma_f32_16x16x32_bf16 v[22:25], v[164:167], v[188:191], v[22:25]
	v_mfma_f32_16x16x32_bf16 v[10:13], v[156:159], v[196:199], v[10:13]
	v_mfma_f32_16x16x32_bf16 v[6:9], v[164:167], v[196:199], v[6:9]
	v_mfma_f32_16x16x32_bf16 v[58:61], v[160:163], v[176:179], v[58:61]
	v_mfma_f32_16x16x32_bf16 v[54:57], v[168:171], v[176:179], v[54:57]
	v_mfma_f32_16x16x32_bf16 v[42:45], v[160:163], v[184:187], v[42:45]
	v_mfma_f32_16x16x32_bf16 v[38:41], v[168:171], v[184:187], v[38:41]
	v_mfma_f32_16x16x32_bf16 v[26:29], v[160:163], v[192:195], v[26:29]
	v_mfma_f32_16x16x32_bf16 v[22:25], v[168:171], v[192:195], v[22:25]
	v_mfma_f32_16x16x32_bf16 v[10:13], v[160:163], v[200:203], v[10:13]
	v_mfma_f32_16x16x32_bf16 v[6:9], v[168:171], v[200:203], v[6:9]
	s_barrier
	s_add_i32 s64, s64, 2
	s_add_u32 s33, s33, 0x100
	s_addc_u32 s61, s61, 0
	s_add_u32 s62, s62, 0x100
	s_addc_u32 s63, s63, 0
	s_cmp_gt_u32 s64, 13
	s_cbranch_scc0 .LBB0_454
	s_and_b64 vcc, exec, s[8:9]
	s_cbranch_vccz .LBB0_457
	s_barrier

.LBB0_480:
	s_add_u32 s58, s54, 0xffffff80
	s_addc_u32 s59, s55, -1
	s_cmp_eq_u32 s56, 4
	s_cselect_b32 s30, s25, s54
	s_cselect_b32 s31, s15, s55
	s_cselect_b32 s35, s17, s53
	s_cselect_b32 s34, s33, s52
	s_add_u32 s26, s30, 0x80
	s_addc_u32 s27, s31, 0
	s_add_u32 s28, s34, 0x80
	s_addc_u32 s29, s35, 0
	s_add_i32 s57, 0, 0x10000
	s_add_i32 s60, 0, 0x14000
	v_add_u32_e32 v152, s57, v1
	v_add_u32_e32 v168, s60, v1
	ds_read_b128 v[140:143], v152
	ds_read_b128 v[144:147], v152 offset:1024
	ds_read_b128 v[148:151], v152 offset:2048
	ds_read_b128 v[152:155], v152 offset:3072
	ds_read_b128 v[156:159], v168
	ds_read_b128 v[160:163], v168 offset:1024
	ds_read_b128 v[164:167], v168 offset:2048
	ds_read_b128 v[168:171], v168 offset:3072
	s_add_u32 s58, s58, 0x20000
	s_addc_u32 s59, s59, 0
	v_lshl_add_u64 v[204:205], s[58:59], 0, v[2:3]
	s_add_i32 m0, s43, 0xc000
	ds_read_b128 v[172:175], v5
	ds_read_b128 v[176:179], v5 offset:1024
	ds_read_b128 v[180:183], v5 offset:2048
	ds_read_b128 v[184:187], v5 offset:3072
	ds_read_b128 v[188:191], v5 offset:4096
	ds_read_b128 v[192:195], v5 offset:5120
	ds_read_b128 v[196:199], v5 offset:6144
	ds_read_b128 v[200:203], v5 offset:7168
	global_load_lds_dwordx4 v[204:205], off
	v_lshl_add_u64 v[204:205], s[58:59], 0, v[136:137]
	s_add_i32 m0, s43, 0xe000
	s_nop 0
	global_load_lds_dwordx4 v[204:205], off
	s_waitcnt vmcnt(8)
	s_waitcnt lgkmcnt(0)
	s_barrier
	v_mfma_f32_16x16x32_bf16 v[130:133], v[140:143], v[172:175], v[130:133]
	v_mfma_f32_16x16x32_bf16 v[126:129], v[148:151], v[172:175], v[126:129]
	v_mfma_f32_16x16x32_bf16 v[114:117], v[140:143], v[180:183], v[114:117]
	v_mfma_f32_16x16x32_bf16 v[110:113], v[148:151], v[180:183], v[110:113]
	v_mfma_f32_16x16x32_bf16 v[98:101], v[140:143], v[188:191], v[98:101]
	v_mfma_f32_16x16x32_bf16 v[94:97], v[148:151], v[188:191], v[94:97]
	v_mfma_f32_16x16x32_bf16 v[82:85], v[140:143], v[196:199], v[82:85]
	v_mfma_f32_16x16x32_bf16 v[78:81], v[148:151], v[196:199], v[78:81]
	v_mfma_f32_16x16x32_bf16 v[130:133], v[144:147], v[176:179], v[130:133]
	v_mfma_f32_16x16x32_bf16 v[126:129], v[152:155], v[176:179], v[126:129]
	v_mfma_f32_16x16x32_bf16 v[114:117], v[144:147], v[184:187], v[114:117]
	v_mfma_f32_16x16x32_bf16 v[110:113], v[152:155], v[184:187], v[110:113]
	v_mfma_f32_16x16x32_bf16 v[98:101], v[144:147], v[192:195], v[98:101]
	v_mfma_f32_16x16x32_bf16 v[94:97], v[152:155], v[192:195], v[94:97]
	v_mfma_f32_16x16x32_bf16 v[82:85], v[144:147], v[200:203], v[82:85]
	v_mfma_f32_16x16x32_bf16 v[78:81], v[152:155], v[200:203], v[78:81]
	v_mfma_f32_16x16x32_bf16 v[122:125], v[156:159], v[172:175], v[122:125]
	v_mfma_f32_16x16x32_bf16 v[118:121], v[164:167], v[172:175], v[118:121]
	v_mfma_f32_16x16x32_bf16 v[106:109], v[156:159], v[180:183], v[106:109]
	v_mfma_f32_16x16x32_bf16 v[102:105], v[164:167], v[180:183], v[102:105]
	v_mfma_f32_16x16x32_bf16 v[90:93], v[156:159], v[188:191], v[90:93]
	v_mfma_f32_16x16x32_bf16 v[86:89], v[164:167], v[188:191], v[86:89]
	v_mfma_f32_16x16x32_bf16 v[74:77], v[156:159], v[196:199], v[74:77]
	v_mfma_f32_16x16x32_bf16 v[70:73], v[164:167], v[196:199], v[70:73]
	v_mfma_f32_16x16x32_bf16 v[122:125], v[160:163], v[176:179], v[122:125]
	v_mfma_f32_16x16x32_bf16 v[118:121], v[168:171], v[176:179], v[118:121]
	v_mfma_f32_16x16x32_bf16 v[106:109], v[160:163], v[184:187], v[106:109]
	v_mfma_f32_16x16x32_bf16 v[102:105], v[168:171], v[184:187], v[102:105]
	v_mfma_f32_16x16x32_bf16 v[90:93], v[160:163], v[192:195], v[90:93]
	v_mfma_f32_16x16x32_bf16 v[86:89], v[168:171], v[192:195], v[86:89]
	v_mfma_f32_16x16x32_bf16 v[74:77], v[160:163], v[200:203], v[74:77]
	v_mfma_f32_16x16x32_bf16 v[70:73], v[168:171], v[200:203], v[70:73]
	s_barrier
	s_add_i32 s57, s57, s42
	v_lshl_add_u64 v[204:205], s[34:35], 0, v[134:135]
	s_mov_b32 m0, s57
	ds_read_b128 v[172:175], v5 offset:16384
	ds_read_b128 v[176:179], v5 offset:17408
	ds_read_b128 v[180:183], v5 offset:18432
	ds_read_b128 v[184:187], v5 offset:19456
	ds_read_b128 v[188:191], v5 offset:20480
	ds_read_b128 v[192:195], v5 offset:21504
	ds_read_b128 v[196:199], v5 offset:22528
	ds_read_b128 v[200:203], v5 offset:23552
	global_load_lds_dwordx4 v[204:205], off
	s_add_i32 m0, s57, 0x2000
	v_lshl_add_u64 v[204:205], s[34:35], 0, v[138:139]
	s_add_u32 s34, s34, 0x20000
	s_addc_u32 s35, s35, 0
	s_add_i32 s57, s60, s42
	global_load_lds_dwordx4 v[204:205], off
	v_lshl_add_u64 v[204:205], s[34:35], 0, v[134:135]
	s_mov_b32 m0, s57
	s_nop 0
	global_load_lds_dwordx4 v[204:205], off
	v_lshl_add_u64 v[204:205], s[34:35], 0, v[138:139]
	s_add_i32 m0, s57, 0x2000
	s_nop 0
	global_load_lds_dwordx4 v[204:205], off
	v_lshl_add_u64 v[204:205], s[30:31], 0, v[2:3]
	s_mov_b32 m0, s43
	s_nop 0
	global_load_lds_dwordx4 v[204:205], off
	v_lshl_add_u64 v[204:205], s[30:31], 0, v[136:137]
	s_mov_b32 m0, s44
	s_nop 0
	global_load_lds_dwordx4 v[204:205], off
	s_waitcnt vmcnt(8)
	s_waitcnt lgkmcnt(0)
	s_barrier
	v_mfma_f32_16x16x32_bf16 v[66:69], v[140:143], v[172:175], v[66:69]
	v_mfma_f32_16x16x32_bf16 v[62:65], v[148:151], v[172:175], v[62:65]
	v_mfma_f32_16x16x32_bf16 v[50:53], v[140:143], v[180:183], v[50:53]
	v_mfma_f32_16x16x32_bf16 v[46:49], v[148:151], v[180:183], v[46:49]
	v_mfma_f32_16x16x32_bf16 v[34:37], v[140:143], v[188:191], v[34:37]
	v_mfma_f32_16x16x32_bf16 v[30:33], v[148:151], v[188:191], v[30:33]
	v_mfma_f32_16x16x32_bf16 v[18:21], v[140:143], v[196:199], v[18:21]
	v_mfma_f32_16x16x32_bf16 v[14:17], v[148:151], v[196:199], v[14:17]
	v_mfma_f32_16x16x32_bf16 v[66:69], v[144:147], v[176:179], v[66:69]
	v_mfma_f32_16x16x32_bf16 v[62:65], v[152:155], v[176:179], v[62:65]
	v_mfma_f32_16x16x32_bf16 v[50:53], v[144:147], v[184:187], v[50:53]
	v_mfma_f32_16x16x32_bf16 v[46:49], v[152:155], v[184:187], v[46:49]
	v_mfma_f32_16x16x32_bf16 v[34:37], v[144:147], v[192:195], v[34:37]
	v_mfma_f32_16x16x32_bf16 v[30:33], v[152:155], v[192:195], v[30:33]
	v_mfma_f32_16x16x32_bf16 v[18:21], v[144:147], v[200:203], v[18:21]
	v_mfma_f32_16x16x32_bf16 v[14:17], v[152:155], v[200:203], v[14:17]
	v_mfma_f32_16x16x32_bf16 v[58:61], v[156:159], v[172:175], v[58:61]
	v_mfma_f32_16x16x32_bf16 v[54:57], v[164:167], v[172:175], v[54:57]
	v_mfma_f32_16x16x32_bf16 v[42:45], v[156:159], v[180:183], v[42:45]
	v_mfma_f32_16x16x32_bf16 v[38:41], v[164:167], v[180:183], v[38:41]
	v_mfma_f32_16x16x32_bf16 v[26:29], v[156:159], v[188:191], v[26:29]
	v_mfma_f32_16x16x32_bf16 v[22:25], v[164:167], v[188:191], v[22:25]
	v_mfma_f32_16x16x32_bf16 v[10:13], v[156:159], v[196:199], v[10:13]
	v_mfma_f32_16x16x32_bf16 v[6:9], v[164:167], v[196:199], v[6:9]
	v_mfma_f32_16x16x32_bf16 v[58:61], v[160:163], v[176:179], v[58:61]
	v_mfma_f32_16x16x32_bf16 v[54:57], v[168:171], v[176:179], v[54:57]
	v_mfma_f32_16x16x32_bf16 v[42:45], v[160:163], v[184:187], v[42:45]
	v_mfma_f32_16x16x32_bf16 v[38:41], v[168:171], v[184:187], v[38:41]
	v_mfma_f32_16x16x32_bf16 v[26:29], v[160:163], v[192:195], v[26:29]
	v_mfma_f32_16x16x32_bf16 v[22:25], v[168:171], v[192:195], v[22:25]
	v_mfma_f32_16x16x32_bf16 v[10:13], v[160:163], v[200:203], v[10:13]
	v_mfma_f32_16x16x32_bf16 v[6:9], v[168:171], v[200:203], v[6:9]
	s_barrier
	s_add_i32 s34, 0, 0x18000
	s_add_i32 s35, 0, 0x1c000
	v_add_u32_e32 v152, s34, v1
	v_add_u32_e32 v168, s35, v1
	ds_read_b128 v[140:143], v152
	ds_read_b128 v[144:147], v152 offset:1024
	ds_read_b128 v[148:151], v152 offset:2048
	ds_read_b128 v[152:155], v152 offset:3072
	ds_read_b128 v[156:159], v168
	ds_read_b128 v[160:163], v168 offset:1024
	ds_read_b128 v[164:167], v168 offset:2048
	ds_read_b128 v[168:171], v168 offset:3072
	s_add_u32 s30, s30, 0x20000
	s_addc_u32 s31, s31, 0
	s_mov_b32 m0, s45
	v_lshl_add_u64 v[204:205], s[30:31], 0, v[2:3]
	ds_read_b128 v[172:175], v5 offset:32768
	ds_read_b128 v[176:179], v5 offset:33792
	ds_read_b128 v[180:183], v5 offset:34816
	ds_read_b128 v[184:187], v5 offset:35840
	ds_read_b128 v[188:191], v5 offset:36864
	ds_read_b128 v[192:195], v5 offset:37888
	ds_read_b128 v[196:199], v5 offset:38912
	ds_read_b128 v[200:203], v5 offset:39936
	global_load_lds_dwordx4 v[204:205], off
	v_lshl_add_u64 v[204:205], s[30:31], 0, v[136:137]
	s_mov_b32 m0, s46
	s_nop 0
	global_load_lds_dwordx4 v[204:205], off
	s_waitcnt vmcnt(8)
	s_waitcnt lgkmcnt(0)
	s_barrier
	v_mfma_f32_16x16x32_bf16 v[130:133], v[140:143], v[172:175], v[130:133]
	v_mfma_f32_16x16x32_bf16 v[126:129], v[148:151], v[172:175], v[126:129]
	v_mfma_f32_16x16x32_bf16 v[114:117], v[140:143], v[180:183], v[114:117]
	v_mfma_f32_16x16x32_bf16 v[110:113], v[148:151], v[180:183], v[110:113]
	v_mfma_f32_16x16x32_bf16 v[98:101], v[140:143], v[188:191], v[98:101]
	v_mfma_f32_16x16x32_bf16 v[94:97], v[148:151], v[188:191], v[94:97]
	v_mfma_f32_16x16x32_bf16 v[82:85], v[140:143], v[196:199], v[82:85]
	v_mfma_f32_16x16x32_bf16 v[78:81], v[148:151], v[196:199], v[78:81]
	v_mfma_f32_16x16x32_bf16 v[130:133], v[144:147], v[176:179], v[130:133]
	v_mfma_f32_16x16x32_bf16 v[126:129], v[152:155], v[176:179], v[126:129]
	v_mfma_f32_16x16x32_bf16 v[114:117], v[144:147], v[184:187], v[114:117]
	v_mfma_f32_16x16x32_bf16 v[110:113], v[152:155], v[184:187], v[110:113]
	v_mfma_f32_16x16x32_bf16 v[98:101], v[144:147], v[192:195], v[98:101]
	v_mfma_f32_16x16x32_bf16 v[94:97], v[152:155], v[192:195], v[94:97]
	v_mfma_f32_16x16x32_bf16 v[82:85], v[144:147], v[200:203], v[82:85]
	v_mfma_f32_16x16x32_bf16 v[78:81], v[152:155], v[200:203], v[78:81]
	v_mfma_f32_16x16x32_bf16 v[122:125], v[156:159], v[172:175], v[122:125]
	v_mfma_f32_16x16x32_bf16 v[118:121], v[164:167], v[172:175], v[118:121]
	v_mfma_f32_16x16x32_bf16 v[106:109], v[156:159], v[180:183], v[106:109]
	v_mfma_f32_16x16x32_bf16 v[102:105], v[164:167], v[180:183], v[102:105]
	v_mfma_f32_16x16x32_bf16 v[90:93], v[156:159], v[188:191], v[90:93]
	v_mfma_f32_16x16x32_bf16 v[86:89], v[164:167], v[188:191], v[86:89]
	v_mfma_f32_16x16x32_bf16 v[74:77], v[156:159], v[196:199], v[74:77]
	v_mfma_f32_16x16x32_bf16 v[70:73], v[164:167], v[196:199], v[70:73]
	v_mfma_f32_16x16x32_bf16 v[122:125], v[160:163], v[176:179], v[122:125]
	v_mfma_f32_16x16x32_bf16 v[118:121], v[168:171], v[176:179], v[118:121]
	v_mfma_f32_16x16x32_bf16 v[106:109], v[160:163], v[184:187], v[106:109]
	v_mfma_f32_16x16x32_bf16 v[102:105], v[168:171], v[184:187], v[102:105]
	v_mfma_f32_16x16x32_bf16 v[90:93], v[160:163], v[192:195], v[90:93]
	v_mfma_f32_16x16x32_bf16 v[86:89], v[168:171], v[192:195], v[86:89]
	v_mfma_f32_16x16x32_bf16 v[74:77], v[160:163], v[200:203], v[74:77]
	v_mfma_f32_16x16x32_bf16 v[70:73], v[168:171], v[200:203], v[70:73]
	s_barrier
	s_add_i32 s30, s34, s42
	v_lshl_add_u64 v[204:205], s[28:29], 0, v[134:135]
	s_mov_b32 m0, s30
	ds_read_b128 v[172:175], v5 offset:49152
	ds_read_b128 v[176:179], v5 offset:50176
	ds_read_b128 v[180:183], v5 offset:51200
	ds_read_b128 v[184:187], v5 offset:52224
	ds_read_b128 v[188:191], v5 offset:53248
	ds_read_b128 v[192:195], v5 offset:54272
	ds_read_b128 v[196:199], v5 offset:55296
	ds_read_b128 v[200:203], v5 offset:56320
	global_load_lds_dwordx4 v[204:205], off
	s_add_i32 m0, s30, 0x2000
	v_lshl_add_u64 v[204:205], s[28:29], 0, v[138:139]
	s_add_u32 s28, s28, 0x20000
	s_addc_u32 s29, s29, 0
	s_add_i32 s30, s35, s42
	global_load_lds_dwordx4 v[204:205], off
	v_lshl_add_u64 v[204:205], s[28:29], 0, v[134:135]
	s_mov_b32 m0, s30
	s_nop 0
	global_load_lds_dwordx4 v[204:205], off
	v_lshl_add_u64 v[204:205], s[28:29], 0, v[138:139]
	s_add_i32 m0, s30, 0x2000
	s_nop 0
	global_load_lds_dwordx4 v[204:205], off
	v_lshl_add_u64 v[204:205], s[26:27], 0, v[2:3]
	s_mov_b32 m0, s49
	s_nop 0
	global_load_lds_dwordx4 v[204:205], off
	v_lshl_add_u64 v[204:205], s[26:27], 0, v[136:137]
	s_mov_b32 m0, s50
	s_nop 0
	global_load_lds_dwordx4 v[204:205], off
	s_waitcnt vmcnt(8)
	s_waitcnt lgkmcnt(0)
	s_barrier
	v_mfma_f32_16x16x32_bf16 v[66:69], v[140:143], v[172:175], v[66:69]
	v_mfma_f32_16x16x32_bf16 v[62:65], v[148:151], v[172:175], v[62:65]
	v_mfma_f32_16x16x32_bf16 v[50:53], v[140:143], v[180:183], v[50:53]
	v_mfma_f32_16x16x32_bf16 v[46:49], v[148:151], v[180:183], v[46:49]
	v_mfma_f32_16x16x32_bf16 v[34:37], v[140:143], v[188:191], v[34:37]
	v_mfma_f32_16x16x32_bf16 v[30:33], v[148:151], v[188:191], v[30:33]
	v_mfma_f32_16x16x32_bf16 v[18:21], v[140:143], v[196:199], v[18:21]
	v_mfma_f32_16x16x32_bf16 v[14:17], v[148:151], v[196:199], v[14:17]
	v_mfma_f32_16x16x32_bf16 v[66:69], v[144:147], v[176:179], v[66:69]
	v_mfma_f32_16x16x32_bf16 v[62:65], v[152:155], v[176:179], v[62:65]
	v_mfma_f32_16x16x32_bf16 v[50:53], v[144:147], v[184:187], v[50:53]
	v_mfma_f32_16x16x32_bf16 v[46:49], v[152:155], v[184:187], v[46:49]
	v_mfma_f32_16x16x32_bf16 v[34:37], v[144:147], v[192:195], v[34:37]
	v_mfma_f32_16x16x32_bf16 v[30:33], v[152:155], v[192:195], v[30:33]
	v_mfma_f32_16x16x32_bf16 v[18:21], v[144:147], v[200:203], v[18:21]
	v_mfma_f32_16x16x32_bf16 v[14:17], v[152:155], v[200:203], v[14:17]
	v_mfma_f32_16x16x32_bf16 v[58:61], v[156:159], v[172:175], v[58:61]
	v_mfma_f32_16x16x32_bf16 v[54:57], v[164:167], v[172:175], v[54:57]
	v_mfma_f32_16x16x32_bf16 v[42:45], v[156:159], v[180:183], v[42:45]
	v_mfma_f32_16x16x32_bf16 v[38:41], v[164:167], v[180:183], v[38:41]
	v_mfma_f32_16x16x32_bf16 v[26:29], v[156:159], v[188:191], v[26:29]
	v_mfma_f32_16x16x32_bf16 v[22:25], v[164:167], v[188:191], v[22:25]
	v_mfma_f32_16x16x32_bf16 v[10:13], v[156:159], v[196:199], v[10:13]
	v_mfma_f32_16x16x32_bf16 v[6:9], v[164:167], v[196:199], v[6:9]
	v_mfma_f32_16x16x32_bf16 v[58:61], v[160:163], v[176:179], v[58:61]
	v_mfma_f32_16x16x32_bf16 v[54:57], v[168:171], v[176:179], v[54:57]
	v_mfma_f32_16x16x32_bf16 v[42:45], v[160:163], v[184:187], v[42:45]
	v_mfma_f32_16x16x32_bf16 v[38:41], v[168:171], v[184:187], v[38:41]
	v_mfma_f32_16x16x32_bf16 v[26:29], v[160:163], v[192:195], v[26:29]
	v_mfma_f32_16x16x32_bf16 v[22:25], v[168:171], v[192:195], v[22:25]
	v_mfma_f32_16x16x32_bf16 v[10:13], v[160:163], v[200:203], v[10:13]
	v_mfma_f32_16x16x32_bf16 v[6:9], v[168:171], v[200:203], v[6:9]
	s_barrier
	s_add_i32 s56, s56, 2
	s_add_u32 s52, s52, 0x100
	s_addc_u32 s53, s53, 0
	s_add_u32 s54, s54, 0x100
	s_addc_u32 s55, s55, 0
	s_cmp_gt_u32 s56, 5
	s_cbranch_scc0 .LBB0_480
	s_and_b64 vcc, exec, s[8:9]
	s_cbranch_vccz .LBB0_483
	s_barrier

.LBB0_536:
	s_add_u32 s48, s45, 0xffffff80
	s_addc_u32 s49, s46, -1
	s_cmp_eq_u32 s47, 4
	s_cselect_b32 s22, s41, s45
	s_cselect_b32 s23, s7, s46
	s_cselect_b32 s25, s9, s44
	s_cselect_b32 s24, s42, s43
	s_add_u32 s18, s22, 0x80
	s_addc_u32 s19, s23, 0
	s_add_u32 s20, s24, 0x80
	s_addc_u32 s21, s25, 0
	s_add_i32 s50, 0, 0x10000
	s_add_i32 s51, 0, 0x14000
	v_add_u32_e32 v152, s50, v1
	v_add_u32_e32 v168, s51, v1
	ds_read_b128 v[140:143], v152
	ds_read_b128 v[144:147], v152 offset:1024
	ds_read_b128 v[148:151], v152 offset:2048
	ds_read_b128 v[152:155], v152 offset:3072
	ds_read_b128 v[156:159], v168
	ds_read_b128 v[160:163], v168 offset:1024
	ds_read_b128 v[164:167], v168 offset:2048
	ds_read_b128 v[168:171], v168 offset:3072
	s_add_u32 s48, s48, 0x20000
	s_addc_u32 s49, s49, 0
	v_lshl_add_u64 v[204:205], s[48:49], 0, v[2:3]
	s_add_i32 m0, s15, 0xc000
	ds_read_b128 v[172:175], v5
	ds_read_b128 v[176:179], v5 offset:1024
	ds_read_b128 v[180:183], v5 offset:2048
	ds_read_b128 v[184:187], v5 offset:3072
	ds_read_b128 v[188:191], v5 offset:4096
	ds_read_b128 v[192:195], v5 offset:5120
	ds_read_b128 v[196:199], v5 offset:6144
	ds_read_b128 v[200:203], v5 offset:7168
	global_load_lds_dwordx4 v[204:205], off
	v_lshl_add_u64 v[204:205], s[48:49], 0, v[136:137]
	s_add_i32 m0, s15, 0xe000
	s_nop 0
	global_load_lds_dwordx4 v[204:205], off
	s_waitcnt vmcnt(8)
	s_waitcnt lgkmcnt(0)
	s_barrier
	v_mfma_f32_16x16x32_bf16 v[130:133], v[140:143], v[172:175], v[130:133]
	v_mfma_f32_16x16x32_bf16 v[126:129], v[148:151], v[172:175], v[126:129]
	v_mfma_f32_16x16x32_bf16 v[122:125], v[140:143], v[180:183], v[122:125]
	v_mfma_f32_16x16x32_bf16 v[114:117], v[148:151], v[180:183], v[114:117]
	v_mfma_f32_16x16x32_bf16 v[106:109], v[140:143], v[188:191], v[106:109]
	v_mfma_f32_16x16x32_bf16 v[98:101], v[148:151], v[188:191], v[98:101]
	v_mfma_f32_16x16x32_bf16 v[90:93], v[140:143], v[196:199], v[90:93]
	v_mfma_f32_16x16x32_bf16 v[82:85], v[148:151], v[196:199], v[82:85]
	v_mfma_f32_16x16x32_bf16 v[130:133], v[144:147], v[176:179], v[130:133]
	v_mfma_f32_16x16x32_bf16 v[126:129], v[152:155], v[176:179], v[126:129]
	v_mfma_f32_16x16x32_bf16 v[122:125], v[144:147], v[184:187], v[122:125]
	v_mfma_f32_16x16x32_bf16 v[114:117], v[152:155], v[184:187], v[114:117]
	v_mfma_f32_16x16x32_bf16 v[106:109], v[144:147], v[192:195], v[106:109]
	v_mfma_f32_16x16x32_bf16 v[98:101], v[152:155], v[192:195], v[98:101]
	v_mfma_f32_16x16x32_bf16 v[90:93], v[144:147], v[200:203], v[90:93]
	v_mfma_f32_16x16x32_bf16 v[82:85], v[152:155], v[200:203], v[82:85]
	v_mfma_f32_16x16x32_bf16 v[118:121], v[156:159], v[172:175], v[118:121]
	v_mfma_f32_16x16x32_bf16 v[110:113], v[164:167], v[172:175], v[110:113]
	v_mfma_f32_16x16x32_bf16 v[102:105], v[156:159], v[180:183], v[102:105]
	v_mfma_f32_16x16x32_bf16 v[94:97], v[164:167], v[180:183], v[94:97]
	v_mfma_f32_16x16x32_bf16 v[86:89], v[156:159], v[188:191], v[86:89]
	v_mfma_f32_16x16x32_bf16 v[78:81], v[164:167], v[188:191], v[78:81]
	v_mfma_f32_16x16x32_bf16 v[74:77], v[156:159], v[196:199], v[74:77]
	v_mfma_f32_16x16x32_bf16 v[70:73], v[164:167], v[196:199], v[70:73]
	v_mfma_f32_16x16x32_bf16 v[118:121], v[160:163], v[176:179], v[118:121]
	v_mfma_f32_16x16x32_bf16 v[110:113], v[168:171], v[176:179], v[110:113]
	v_mfma_f32_16x16x32_bf16 v[102:105], v[160:163], v[184:187], v[102:105]
	v_mfma_f32_16x16x32_bf16 v[94:97], v[168:171], v[184:187], v[94:97]
	v_mfma_f32_16x16x32_bf16 v[86:89], v[160:163], v[192:195], v[86:89]
	v_mfma_f32_16x16x32_bf16 v[78:81], v[168:171], v[192:195], v[78:81]
	v_mfma_f32_16x16x32_bf16 v[74:77], v[160:163], v[200:203], v[74:77]
	v_mfma_f32_16x16x32_bf16 v[70:73], v[168:171], v[200:203], v[70:73]
	s_barrier
	s_add_i32 s48, s50, s29
	v_lshl_add_u64 v[204:205], s[24:25], 0, v[134:135]
	s_mov_b32 m0, s48
	ds_read_b128 v[172:175], v5 offset:16384
	ds_read_b128 v[176:179], v5 offset:17408
	ds_read_b128 v[180:183], v5 offset:18432
	ds_read_b128 v[184:187], v5 offset:19456
	ds_read_b128 v[188:191], v5 offset:20480
	ds_read_b128 v[192:195], v5 offset:21504
	ds_read_b128 v[196:199], v5 offset:22528
	ds_read_b128 v[200:203], v5 offset:23552
	global_load_lds_dwordx4 v[204:205], off
	s_add_i32 m0, s48, 0x2000
	v_lshl_add_u64 v[204:205], s[24:25], 0, v[138:139]
	s_add_u32 s24, s24, 0x20000
	s_addc_u32 s25, s25, 0
	s_add_i32 s48, s51, s29
	global_load_lds_dwordx4 v[204:205], off
	v_lshl_add_u64 v[204:205], s[24:25], 0, v[134:135]
	s_mov_b32 m0, s48
	s_nop 0
	global_load_lds_dwordx4 v[204:205], off
	v_lshl_add_u64 v[204:205], s[24:25], 0, v[138:139]
	s_add_i32 m0, s48, 0x2000
	s_nop 0
	global_load_lds_dwordx4 v[204:205], off
	v_lshl_add_u64 v[204:205], s[22:23], 0, v[2:3]
	s_mov_b32 m0, s15
	s_nop 0
	global_load_lds_dwordx4 v[204:205], off
	v_lshl_add_u64 v[204:205], s[22:23], 0, v[136:137]
	s_mov_b32 m0, s17
	s_nop 0
	global_load_lds_dwordx4 v[204:205], off
	s_waitcnt vmcnt(8)
	s_waitcnt lgkmcnt(0)
	s_barrier
	v_mfma_f32_16x16x32_bf16 v[66:69], v[140:143], v[172:175], v[66:69]
	v_mfma_f32_16x16x32_bf16 v[62:65], v[148:151], v[172:175], v[62:65]
	v_mfma_f32_16x16x32_bf16 v[58:61], v[140:143], v[180:183], v[58:61]
	v_mfma_f32_16x16x32_bf16 v[50:53], v[148:151], v[180:183], v[50:53]
	v_mfma_f32_16x16x32_bf16 v[42:45], v[140:143], v[188:191], v[42:45]
	v_mfma_f32_16x16x32_bf16 v[34:37], v[148:151], v[188:191], v[34:37]
	v_mfma_f32_16x16x32_bf16 v[26:29], v[140:143], v[196:199], v[26:29]
	v_mfma_f32_16x16x32_bf16 v[18:21], v[148:151], v[196:199], v[18:21]
	v_mfma_f32_16x16x32_bf16 v[66:69], v[144:147], v[176:179], v[66:69]
	v_mfma_f32_16x16x32_bf16 v[62:65], v[152:155], v[176:179], v[62:65]
	v_mfma_f32_16x16x32_bf16 v[58:61], v[144:147], v[184:187], v[58:61]
	v_mfma_f32_16x16x32_bf16 v[50:53], v[152:155], v[184:187], v[50:53]
	v_mfma_f32_16x16x32_bf16 v[42:45], v[144:147], v[192:195], v[42:45]
	v_mfma_f32_16x16x32_bf16 v[34:37], v[152:155], v[192:195], v[34:37]
	v_mfma_f32_16x16x32_bf16 v[26:29], v[144:147], v[200:203], v[26:29]
	v_mfma_f32_16x16x32_bf16 v[18:21], v[152:155], v[200:203], v[18:21]
	v_mfma_f32_16x16x32_bf16 v[54:57], v[156:159], v[172:175], v[54:57]
	v_mfma_f32_16x16x32_bf16 v[46:49], v[164:167], v[172:175], v[46:49]
	v_mfma_f32_16x16x32_bf16 v[38:41], v[156:159], v[180:183], v[38:41]
	v_mfma_f32_16x16x32_bf16 v[30:33], v[164:167], v[180:183], v[30:33]
	v_mfma_f32_16x16x32_bf16 v[22:25], v[156:159], v[188:191], v[22:25]
	v_mfma_f32_16x16x32_bf16 v[14:17], v[164:167], v[188:191], v[14:17]
	v_mfma_f32_16x16x32_bf16 v[10:13], v[156:159], v[196:199], v[10:13]
	v_mfma_f32_16x16x32_bf16 v[6:9], v[164:167], v[196:199], v[6:9]
	v_mfma_f32_16x16x32_bf16 v[54:57], v[160:163], v[176:179], v[54:57]
	v_mfma_f32_16x16x32_bf16 v[46:49], v[168:171], v[176:179], v[46:49]
	v_mfma_f32_16x16x32_bf16 v[38:41], v[160:163], v[184:187], v[38:41]
	v_mfma_f32_16x16x32_bf16 v[30:33], v[168:171], v[184:187], v[30:33]
	v_mfma_f32_16x16x32_bf16 v[22:25], v[160:163], v[192:195], v[22:25]
	v_mfma_f32_16x16x32_bf16 v[14:17], v[168:171], v[192:195], v[14:17]
	v_mfma_f32_16x16x32_bf16 v[10:13], v[160:163], v[200:203], v[10:13]
	v_mfma_f32_16x16x32_bf16 v[6:9], v[168:171], v[200:203], v[6:9]
	s_barrier
	s_add_i32 s24, 0, 0x18000
	s_add_i32 s25, 0, 0x1c000
	v_add_u32_e32 v152, s24, v1
	v_add_u32_e32 v168, s25, v1
	ds_read_b128 v[140:143], v152
	ds_read_b128 v[144:147], v152 offset:1024
	ds_read_b128 v[148:151], v152 offset:2048
	ds_read_b128 v[152:155], v152 offset:3072
	ds_read_b128 v[156:159], v168
	ds_read_b128 v[160:163], v168 offset:1024
	ds_read_b128 v[164:167], v168 offset:2048
	ds_read_b128 v[168:171], v168 offset:3072
	s_add_u32 s22, s22, 0x20000
	s_addc_u32 s23, s23, 0
	s_mov_b32 m0, s31
	v_lshl_add_u64 v[204:205], s[22:23], 0, v[2:3]
	ds_read_b128 v[172:175], v5 offset:32768
	ds_read_b128 v[176:179], v5 offset:33792
	ds_read_b128 v[180:183], v5 offset:34816
	ds_read_b128 v[184:187], v5 offset:35840
	ds_read_b128 v[188:191], v5 offset:36864
	ds_read_b128 v[192:195], v5 offset:37888
	ds_read_b128 v[196:199], v5 offset:38912
	ds_read_b128 v[200:203], v5 offset:39936
	global_load_lds_dwordx4 v[204:205], off
	v_lshl_add_u64 v[204:205], s[22:23], 0, v[136:137]
	s_mov_b32 m0, s33
	s_nop 0
	global_load_lds_dwordx4 v[204:205], off
	s_waitcnt vmcnt(8)
	s_waitcnt lgkmcnt(0)
	s_barrier
	v_mfma_f32_16x16x32_bf16 v[130:133], v[140:143], v[172:175], v[130:133]
	v_mfma_f32_16x16x32_bf16 v[126:129], v[148:151], v[172:175], v[126:129]
	v_mfma_f32_16x16x32_bf16 v[122:125], v[140:143], v[180:183], v[122:125]
	v_mfma_f32_16x16x32_bf16 v[114:117], v[148:151], v[180:183], v[114:117]
	v_mfma_f32_16x16x32_bf16 v[106:109], v[140:143], v[188:191], v[106:109]
	v_mfma_f32_16x16x32_bf16 v[98:101], v[148:151], v[188:191], v[98:101]
	v_mfma_f32_16x16x32_bf16 v[90:93], v[140:143], v[196:199], v[90:93]
	v_mfma_f32_16x16x32_bf16 v[82:85], v[148:151], v[196:199], v[82:85]
	v_mfma_f32_16x16x32_bf16 v[130:133], v[144:147], v[176:179], v[130:133]
	v_mfma_f32_16x16x32_bf16 v[126:129], v[152:155], v[176:179], v[126:129]
	v_mfma_f32_16x16x32_bf16 v[122:125], v[144:147], v[184:187], v[122:125]
	v_mfma_f32_16x16x32_bf16 v[114:117], v[152:155], v[184:187], v[114:117]
	v_mfma_f32_16x16x32_bf16 v[106:109], v[144:147], v[192:195], v[106:109]
	v_mfma_f32_16x16x32_bf16 v[98:101], v[152:155], v[192:195], v[98:101]
	v_mfma_f32_16x16x32_bf16 v[90:93], v[144:147], v[200:203], v[90:93]
	v_mfma_f32_16x16x32_bf16 v[82:85], v[152:155], v[200:203], v[82:85]
	v_mfma_f32_16x16x32_bf16 v[118:121], v[156:159], v[172:175], v[118:121]
	v_mfma_f32_16x16x32_bf16 v[110:113], v[164:167], v[172:175], v[110:113]
	v_mfma_f32_16x16x32_bf16 v[102:105], v[156:159], v[180:183], v[102:105]
	v_mfma_f32_16x16x32_bf16 v[94:97], v[164:167], v[180:183], v[94:97]
	v_mfma_f32_16x16x32_bf16 v[86:89], v[156:159], v[188:191], v[86:89]
	v_mfma_f32_16x16x32_bf16 v[78:81], v[164:167], v[188:191], v[78:81]
	v_mfma_f32_16x16x32_bf16 v[74:77], v[156:159], v[196:199], v[74:77]
	v_mfma_f32_16x16x32_bf16 v[70:73], v[164:167], v[196:199], v[70:73]
	v_mfma_f32_16x16x32_bf16 v[118:121], v[160:163], v[176:179], v[118:121]
	v_mfma_f32_16x16x32_bf16 v[110:113], v[168:171], v[176:179], v[110:113]
	v_mfma_f32_16x16x32_bf16 v[102:105], v[160:163], v[184:187], v[102:105]
	v_mfma_f32_16x16x32_bf16 v[94:97], v[168:171], v[184:187], v[94:97]
	v_mfma_f32_16x16x32_bf16 v[86:89], v[160:163], v[192:195], v[86:89]
	v_mfma_f32_16x16x32_bf16 v[78:81], v[168:171], v[192:195], v[78:81]
	v_mfma_f32_16x16x32_bf16 v[74:77], v[160:163], v[200:203], v[74:77]
	v_mfma_f32_16x16x32_bf16 v[70:73], v[168:171], v[200:203], v[70:73]
	s_barrier
	s_add_i32 s22, s24, s29
	v_lshl_add_u64 v[204:205], s[20:21], 0, v[134:135]
	s_mov_b32 m0, s22
	ds_read_b128 v[172:175], v5 offset:49152
	ds_read_b128 v[176:179], v5 offset:50176
	ds_read_b128 v[180:183], v5 offset:51200
	ds_read_b128 v[184:187], v5 offset:52224
	ds_read_b128 v[188:191], v5 offset:53248
	ds_read_b128 v[192:195], v5 offset:54272
	ds_read_b128 v[196:199], v5 offset:55296
	ds_read_b128 v[200:203], v5 offset:56320
	global_load_lds_dwordx4 v[204:205], off
	s_add_i32 m0, s22, 0x2000
	v_lshl_add_u64 v[204:205], s[20:21], 0, v[138:139]
	s_add_u32 s20, s20, 0x20000
	s_addc_u32 s21, s21, 0
	s_add_i32 s22, s25, s29
	global_load_lds_dwordx4 v[204:205], off
	v_lshl_add_u64 v[204:205], s[20:21], 0, v[134:135]
	s_mov_b32 m0, s22
	s_nop 0
	global_load_lds_dwordx4 v[204:205], off
	v_lshl_add_u64 v[204:205], s[20:21], 0, v[138:139]
	s_add_i32 m0, s22, 0x2000
	s_nop 0
	global_load_lds_dwordx4 v[204:205], off
	v_lshl_add_u64 v[204:205], s[18:19], 0, v[2:3]
	s_mov_b32 m0, s38
	s_nop 0
	global_load_lds_dwordx4 v[204:205], off
	v_lshl_add_u64 v[204:205], s[18:19], 0, v[136:137]
	s_mov_b32 m0, s39
	s_nop 0
	global_load_lds_dwordx4 v[204:205], off
	s_waitcnt vmcnt(8)
	s_waitcnt lgkmcnt(0)
	s_barrier
	v_mfma_f32_16x16x32_bf16 v[66:69], v[140:143], v[172:175], v[66:69]
	v_mfma_f32_16x16x32_bf16 v[62:65], v[148:151], v[172:175], v[62:65]
	v_mfma_f32_16x16x32_bf16 v[58:61], v[140:143], v[180:183], v[58:61]
	v_mfma_f32_16x16x32_bf16 v[50:53], v[148:151], v[180:183], v[50:53]
	v_mfma_f32_16x16x32_bf16 v[42:45], v[140:143], v[188:191], v[42:45]
	v_mfma_f32_16x16x32_bf16 v[34:37], v[148:151], v[188:191], v[34:37]
	v_mfma_f32_16x16x32_bf16 v[26:29], v[140:143], v[196:199], v[26:29]
	v_mfma_f32_16x16x32_bf16 v[18:21], v[148:151], v[196:199], v[18:21]
	v_mfma_f32_16x16x32_bf16 v[66:69], v[144:147], v[176:179], v[66:69]
	v_mfma_f32_16x16x32_bf16 v[62:65], v[152:155], v[176:179], v[62:65]
	v_mfma_f32_16x16x32_bf16 v[58:61], v[144:147], v[184:187], v[58:61]
	v_mfma_f32_16x16x32_bf16 v[50:53], v[152:155], v[184:187], v[50:53]
	v_mfma_f32_16x16x32_bf16 v[42:45], v[144:147], v[192:195], v[42:45]
	v_mfma_f32_16x16x32_bf16 v[34:37], v[152:155], v[192:195], v[34:37]
	v_mfma_f32_16x16x32_bf16 v[26:29], v[144:147], v[200:203], v[26:29]
	v_mfma_f32_16x16x32_bf16 v[18:21], v[152:155], v[200:203], v[18:21]
	v_mfma_f32_16x16x32_bf16 v[54:57], v[156:159], v[172:175], v[54:57]
	v_mfma_f32_16x16x32_bf16 v[46:49], v[164:167], v[172:175], v[46:49]
	v_mfma_f32_16x16x32_bf16 v[38:41], v[156:159], v[180:183], v[38:41]
	v_mfma_f32_16x16x32_bf16 v[30:33], v[164:167], v[180:183], v[30:33]
	v_mfma_f32_16x16x32_bf16 v[22:25], v[156:159], v[188:191], v[22:25]
	v_mfma_f32_16x16x32_bf16 v[14:17], v[164:167], v[188:191], v[14:17]
	v_mfma_f32_16x16x32_bf16 v[10:13], v[156:159], v[196:199], v[10:13]
	v_mfma_f32_16x16x32_bf16 v[6:9], v[164:167], v[196:199], v[6:9]
	v_mfma_f32_16x16x32_bf16 v[54:57], v[160:163], v[176:179], v[54:57]
	v_mfma_f32_16x16x32_bf16 v[46:49], v[168:171], v[176:179], v[46:49]
	v_mfma_f32_16x16x32_bf16 v[38:41], v[160:163], v[184:187], v[38:41]
	v_mfma_f32_16x16x32_bf16 v[30:33], v[168:171], v[184:187], v[30:33]
	v_mfma_f32_16x16x32_bf16 v[22:25], v[160:163], v[192:195], v[22:25]
	v_mfma_f32_16x16x32_bf16 v[14:17], v[168:171], v[192:195], v[14:17]
	v_mfma_f32_16x16x32_bf16 v[10:13], v[160:163], v[200:203], v[10:13]
	v_mfma_f32_16x16x32_bf16 v[6:9], v[168:171], v[200:203], v[6:9]
	s_barrier
	s_add_i32 s47, s47, 2
	s_add_u32 s43, s43, 0x100
	s_addc_u32 s44, s44, 0
	s_add_u32 s45, s45, 0x100
	s_addc_u32 s46, s46, 0
	s_cmp_gt_u32 s47, 5
	s_cbranch_scc0 .LBB0_536
	s_lshl_b32 s20, s16, 8
	v_mov_b32_e32 v140, v0
	s_mov_b64 s[18:19], s[84:85]
	s_lshl_b32 s7, s14, 8
	s_ashr_i32 s21, s20, 31
	s_add_i32 s7, s7, s34
	s_lshl_b64 s[20:21], s[20:21], 1
	v_and_b32_e32 v142, 15, v140
	s_add_u32 s18, s18, s20
	v_or_b32_e32 v146, s7, v142
	v_lshrrev_b32_e32 v140, 1, v140
	s_addc_u32 s19, s19, s21
	s_ashr_i32 s9, s7, 11
	v_mov_b32_e32 v143, s7
	s_movk_i32 s7, 0x7cf
	v_and_or_b32 v140, v140, 24, s35
	s_mulk_i32 s9, 0x810
	v_bitop3_b32 v142, v142, s7, v143 bitop3:0xc8
	v_lshlrev_b32_e32 v140, 1, v140
	v_mov_b32_e32 v141, v4
	v_add_u32_e32 v142, s9, v142
	v_lshl_add_u64 v[140:141], s[18:19], 0, v[140:141]
	s_mov_b64 s[18:19], 0x2c900000
	v_ashrrev_i32_e32 v143, 31, v142
	v_lshl_add_u64 v[140:141], v[140:141], 0, s[18:19]
	v_lshlrev_b64 v[144:145], 13, v[142:143]
	v_lshl_add_u64 v[144:145], v[140:141], 0, v[144:145]
	v_cvt_pk_bf16_f32 v130, v130, v131
	v_cvt_pk_bf16_f32 v131, v132, v133
	v_cvt_pk_bf16_f32 v132, v126, v127
	v_cvt_pk_bf16_f32 v133, v128, v129
	global_store_dwordx4 v[144:145], v[130:133], off nt
	v_cvt_pk_bf16_f32 v118, v118, v119
	v_cvt_pk_bf16_f32 v119, v120, v121
	v_cvt_pk_bf16_f32 v120, v110, v111
	v_add_u32_e32 v110, 16, v142
	v_ashrrev_i32_e32 v111, 31, v110
	v_lshlrev_b64 v[110:111], 13, v[110:111]
	v_cvt_pk_bf16_f32 v121, v112, v113
	global_store_dwordx4 v[144:145], v[118:121], off offset:256 nt
	s_movk_i32 s7, 0x810
	s_and_b64 vcc, exec, s[0:1]
	v_lshl_add_u64 v[118:119], v[140:141], 0, v[110:111]
	v_cvt_pk_bf16_f32 v110, v122, v123
	v_cvt_pk_bf16_f32 v111, v124, v125
	v_cvt_pk_bf16_f32 v112, v114, v115
	v_cvt_pk_bf16_f32 v113, v116, v117
	global_store_dwordx4 v[118:119], v[110:113], off nt
	v_cvt_pk_bf16_f32 v102, v102, v103
	v_cvt_pk_bf16_f32 v103, v104, v105
	v_cvt_pk_bf16_f32 v104, v94, v95
	v_add_u32_e32 v94, 32, v142
	v_ashrrev_i32_e32 v95, 31, v94
	v_lshlrev_b64 v[94:95], 13, v[94:95]
	v_cvt_pk_bf16_f32 v105, v96, v97
	global_store_dwordx4 v[118:119], v[102:105], off offset:256 nt
	s_mov_b32 s16, s8
	s_mov_b32 s14, s6
	v_lshl_add_u64 v[102:103], v[140:141], 0, v[94:95]
	v_cvt_pk_bf16_f32 v94, v106, v107
	v_cvt_pk_bf16_f32 v95, v108, v109
	v_cvt_pk_bf16_f32 v96, v98, v99
	v_cvt_pk_bf16_f32 v97, v100, v101
	global_store_dwordx4 v[102:103], v[94:97], off nt
	v_cvt_pk_bf16_f32 v86, v86, v87
	v_cvt_pk_bf16_f32 v87, v88, v89
	v_cvt_pk_bf16_f32 v88, v78, v79
	v_add_u32_e32 v78, 48, v142
	v_ashrrev_i32_e32 v79, 31, v78
	v_lshlrev_b64 v[78:79], 13, v[78:79]
	v_cvt_pk_bf16_f32 v89, v80, v81
	global_store_dwordx4 v[102:103], v[86:89], off offset:256 nt
	s_mov_b64 s[20:21], s[10:11]
	s_mov_b64 s[18:19], s[12:13]
	v_lshl_add_u64 v[86:87], v[140:141], 0, v[78:79]
	v_cvt_pk_bf16_f32 v78, v90, v91
	v_cvt_pk_bf16_f32 v79, v92, v93
	v_cvt_pk_bf16_f32 v80, v82, v83
	v_cvt_pk_bf16_f32 v81, v84, v85
	global_store_dwordx4 v[86:87], v[78:81], off nt
	v_cvt_pk_bf16_f32 v74, v74, v75
	v_cvt_pk_bf16_f32 v75, v76, v77
	v_cvt_pk_bf16_f32 v76, v70, v71
	v_add_u32_e32 v70, 0x80, v146
	v_ashrrev_i32_e32 v71, 11, v70
	v_and_b32_e32 v70, 0x7cf, v70
	v_mad_i32_i24 v70, v71, s7, v70
	v_ashrrev_i32_e32 v71, 31, v70
	v_cvt_pk_bf16_f32 v77, v72, v73
	v_lshlrev_b64 v[72:73], 13, v[70:71]
	global_store_dwordx4 v[86:87], v[74:77], off offset:256 nt
	v_lshl_add_u64 v[72:73], v[140:141], 0, v[72:73]
	v_cvt_pk_bf16_f32 v66, v66, v67
	v_cvt_pk_bf16_f32 v67, v68, v69
	v_cvt_pk_bf16_f32 v68, v62, v63
	v_cvt_pk_bf16_f32 v69, v64, v65
	global_store_dwordx4 v[72:73], v[66:69], off nt
	v_cvt_pk_bf16_f32 v54, v54, v55
	v_cvt_pk_bf16_f32 v55, v56, v57
	v_cvt_pk_bf16_f32 v56, v46, v47
	v_add_u32_e32 v46, 16, v70
	v_ashrrev_i32_e32 v47, 31, v46
	v_lshlrev_b64 v[46:47], 13, v[46:47]
	v_cvt_pk_bf16_f32 v57, v48, v49
	global_store_dwordx4 v[72:73], v[54:57], off offset:256 nt
	s_mov_b32 s51, 0x40c000
	s_mov_b32 s47, 0x120000
	v_lshl_add_u64 v[54:55], v[140:141], 0, v[46:47]
	v_cvt_pk_bf16_f32 v46, v58, v59
	v_cvt_pk_bf16_f32 v47, v60, v61
	v_cvt_pk_bf16_f32 v48, v50, v51
	v_cvt_pk_bf16_f32 v49, v52, v53
	global_store_dwordx4 v[54:55], v[46:49], off nt
	v_cvt_pk_bf16_f32 v38, v38, v39
	v_cvt_pk_bf16_f32 v39, v40, v41
	v_cvt_pk_bf16_f32 v40, v30, v31
	v_add_u32_e32 v30, 32, v70
	v_ashrrev_i32_e32 v31, 31, v30
	v_lshlrev_b64 v[30:31], 13, v[30:31]
	v_cvt_pk_bf16_f32 v41, v32, v33
	global_store_dwordx4 v[54:55], v[38:41], off offset:256 nt
	s_mov_b64 s[48:49], 0x7ffff
	s_nop 0
	v_lshl_add_u64 v[38:39], v[140:141], 0, v[30:31]
	v_cvt_pk_bf16_f32 v30, v42, v43
	v_cvt_pk_bf16_f32 v31, v44, v45
	v_cvt_pk_bf16_f32 v32, v34, v35
	v_cvt_pk_bf16_f32 v33, v36, v37
	global_store_dwordx4 v[38:39], v[30:33], off nt
	v_cvt_pk_bf16_f32 v22, v22, v23
	v_cvt_pk_bf16_f32 v23, v24, v25
	v_cvt_pk_bf16_f32 v24, v14, v15
	v_add_u32_e32 v14, 48, v70
	v_ashrrev_i32_e32 v15, 31, v14
	v_lshlrev_b64 v[14:15], 13, v[14:15]
	v_cvt_pk_bf16_f32 v25, v16, v17
	global_store_dwordx4 v[38:39], v[22:25], off offset:256 nt
	s_nop 1
	v_lshl_add_u64 v[22:23], v[140:141], 0, v[14:15]
	v_cvt_pk_bf16_f32 v14, v26, v27
	v_cvt_pk_bf16_f32 v15, v28, v29
	v_cvt_pk_bf16_f32 v16, v18, v19
	v_cvt_pk_bf16_f32 v17, v20, v21
	global_store_dwordx4 v[22:23], v[14:17], off nt
	v_cvt_pk_bf16_f32 v10, v10, v11
	v_cvt_pk_bf16_f32 v11, v12, v13
	v_cvt_pk_bf16_f32 v12, v6, v7
	v_cvt_pk_bf16_f32 v13, v8, v9
	global_store_dwordx4 v[22:23], v[10:13], off offset:256 nt
	s_cbranch_vccz .LBB0_529
	s_waitcnt vmcnt(0)
	s_cmpk_gt_u32 s28, 0xff
	s_cbranch_scc1 .LBB0_540
	s_barrier

.LBB0_924:
	s_add_u32 s48, s45, 0xffffff80
	s_addc_u32 s49, s46, -1
	s_cmp_eq_u32 s47, 60
	s_cselect_b32 s22, s9, s45
	s_cselect_b32 s23, s7, s46
	s_cselect_b32 s25, s11, s44
	s_cselect_b32 s24, s13, s33
	s_add_u32 s18, s22, 0x80
	s_addc_u32 s19, s23, 0
	s_add_u32 s20, s24, 0x80
	s_addc_u32 s21, s25, 0
	s_add_i32 s50, 0, 0x10000
	s_add_i32 s51, 0, 0x14000
	v_add_u32_e32 v90, s50, v1
	v_add_u32_e32 v162, s51, v1
	ds_read_b128 v[78:81], v90
	ds_read_b128 v[82:85], v90 offset:1024
	ds_read_b128 v[86:89], v90 offset:2048
	ds_read_b128 v[90:93], v90 offset:3072
	ds_read_b128 v[142:145], v162
	ds_read_b128 v[146:149], v162 offset:1024
	ds_read_b128 v[158:161], v162 offset:2048
	ds_read_b128 v[162:165], v162 offset:3072
	s_add_u32 s48, s48, 0x100000
	s_addc_u32 s49, s49, 0
	v_lshl_add_u64 v[198:199], s[48:49], 0, v[2:3]
	s_add_i32 m0, s35, 0xc000
	ds_read_b128 v[166:169], v5
	ds_read_b128 v[170:173], v5 offset:1024
	ds_read_b128 v[174:177], v5 offset:2048
	ds_read_b128 v[178:181], v5 offset:3072
	ds_read_b128 v[182:185], v5 offset:4096
	ds_read_b128 v[186:189], v5 offset:5120
	ds_read_b128 v[190:193], v5 offset:6144
	ds_read_b128 v[194:197], v5 offset:7168
	global_load_lds_dwordx4 v[198:199], off
	v_lshl_add_u64 v[198:199], s[48:49], 0, v[218:219]
	s_add_i32 m0, s35, 0xe000
	s_nop 0
	global_load_lds_dwordx4 v[198:199], off
	s_waitcnt vmcnt(8)
	s_waitcnt lgkmcnt(0)
	s_barrier
	v_mfma_f32_16x16x32_bf16 v[154:157], v[78:81], v[166:169], v[154:157]
	v_mfma_f32_16x16x32_bf16 v[150:153], v[86:89], v[166:169], v[150:153]
	v_mfma_f32_16x16x32_bf16 v[134:137], v[78:81], v[174:177], v[134:137]
	v_mfma_f32_16x16x32_bf16 v[126:129], v[86:89], v[174:177], v[126:129]
	v_mfma_f32_16x16x32_bf16 v[118:121], v[78:81], v[182:185], v[118:121]
	v_mfma_f32_16x16x32_bf16 v[110:113], v[86:89], v[182:185], v[110:113]
	v_mfma_f32_16x16x32_bf16 v[102:105], v[78:81], v[190:193], v[102:105]
	v_mfma_f32_16x16x32_bf16 v[94:97], v[86:89], v[190:193], v[94:97]
	v_mfma_f32_16x16x32_bf16 v[154:157], v[82:85], v[170:173], v[154:157]
	v_mfma_f32_16x16x32_bf16 v[150:153], v[90:93], v[170:173], v[150:153]
	v_mfma_f32_16x16x32_bf16 v[134:137], v[82:85], v[178:181], v[134:137]
	v_mfma_f32_16x16x32_bf16 v[126:129], v[90:93], v[178:181], v[126:129]
	v_mfma_f32_16x16x32_bf16 v[118:121], v[82:85], v[186:189], v[118:121]
	v_mfma_f32_16x16x32_bf16 v[110:113], v[90:93], v[186:189], v[110:113]
	v_mfma_f32_16x16x32_bf16 v[102:105], v[82:85], v[194:197], v[102:105]
	v_mfma_f32_16x16x32_bf16 v[94:97], v[90:93], v[194:197], v[94:97]
	v_mfma_f32_16x16x32_bf16 v[138:141], v[142:145], v[166:169], v[138:141]
	v_mfma_f32_16x16x32_bf16 v[130:133], v[158:161], v[166:169], v[130:133]
	v_mfma_f32_16x16x32_bf16 v[122:125], v[142:145], v[174:177], v[122:125]
	v_mfma_f32_16x16x32_bf16 v[114:117], v[158:161], v[174:177], v[114:117]
	v_mfma_f32_16x16x32_bf16 v[106:109], v[142:145], v[182:185], v[106:109]
	v_mfma_f32_16x16x32_bf16 v[98:101], v[158:161], v[182:185], v[98:101]
	v_mfma_f32_16x16x32_bf16 v[74:77], v[142:145], v[190:193], v[74:77]
	v_mfma_f32_16x16x32_bf16 v[70:73], v[158:161], v[190:193], v[70:73]
	v_mfma_f32_16x16x32_bf16 v[138:141], v[146:149], v[170:173], v[138:141]
	v_mfma_f32_16x16x32_bf16 v[130:133], v[162:165], v[170:173], v[130:133]
	v_mfma_f32_16x16x32_bf16 v[122:125], v[146:149], v[178:181], v[122:125]
	v_mfma_f32_16x16x32_bf16 v[114:117], v[162:165], v[178:181], v[114:117]
	v_mfma_f32_16x16x32_bf16 v[106:109], v[146:149], v[186:189], v[106:109]
	v_mfma_f32_16x16x32_bf16 v[98:101], v[162:165], v[186:189], v[98:101]
	v_mfma_f32_16x16x32_bf16 v[74:77], v[146:149], v[194:197], v[74:77]
	v_mfma_f32_16x16x32_bf16 v[70:73], v[162:165], v[194:197], v[70:73]
	s_barrier
	s_add_i32 s48, s50, s29
	v_lshl_add_u64 v[198:199], s[24:25], 0, v[216:217]
	s_mov_b32 m0, s48
	ds_read_b128 v[166:169], v5 offset:16384
	ds_read_b128 v[170:173], v5 offset:17408
	ds_read_b128 v[174:177], v5 offset:18432
	ds_read_b128 v[178:181], v5 offset:19456
	ds_read_b128 v[182:185], v5 offset:20480
	ds_read_b128 v[186:189], v5 offset:21504
	ds_read_b128 v[190:193], v5 offset:22528
	ds_read_b128 v[194:197], v5 offset:23552
	global_load_lds_dwordx4 v[198:199], off
	s_add_i32 m0, s48, 0x2000
	v_lshl_add_u64 v[198:199], s[24:25], 0, v[220:221]
	s_add_u32 s24, s24, 0x100000
	s_addc_u32 s25, s25, 0
	s_add_i32 s48, s51, s29
	global_load_lds_dwordx4 v[198:199], off
	v_lshl_add_u64 v[198:199], s[24:25], 0, v[216:217]
	s_mov_b32 m0, s48
	s_nop 0
	global_load_lds_dwordx4 v[198:199], off
	v_lshl_add_u64 v[198:199], s[24:25], 0, v[220:221]
	s_add_i32 m0, s48, 0x2000
	s_nop 0
	global_load_lds_dwordx4 v[198:199], off
	v_lshl_add_u64 v[198:199], s[22:23], 0, v[2:3]
	s_mov_b32 m0, s35
	s_nop 0
	global_load_lds_dwordx4 v[198:199], off
	v_lshl_add_u64 v[198:199], s[22:23], 0, v[218:219]
	s_mov_b32 m0, s36
	s_nop 0
	global_load_lds_dwordx4 v[198:199], off
	s_waitcnt vmcnt(8)
	s_waitcnt lgkmcnt(0)
	s_barrier
	v_mfma_f32_16x16x32_bf16 v[66:69], v[78:81], v[166:169], v[66:69]
	v_mfma_f32_16x16x32_bf16 v[62:65], v[86:89], v[166:169], v[62:65]
	v_mfma_f32_16x16x32_bf16 v[54:57], v[78:81], v[174:177], v[54:57]
	v_mfma_f32_16x16x32_bf16 v[46:49], v[86:89], v[174:177], v[46:49]
	v_mfma_f32_16x16x32_bf16 v[38:41], v[78:81], v[182:185], v[38:41]
	v_mfma_f32_16x16x32_bf16 v[30:33], v[86:89], v[182:185], v[30:33]
	v_mfma_f32_16x16x32_bf16 v[22:25], v[78:81], v[190:193], v[22:25]
	v_mfma_f32_16x16x32_bf16 v[14:17], v[86:89], v[190:193], v[14:17]
	v_mfma_f32_16x16x32_bf16 v[66:69], v[82:85], v[170:173], v[66:69]
	v_mfma_f32_16x16x32_bf16 v[62:65], v[90:93], v[170:173], v[62:65]
	v_mfma_f32_16x16x32_bf16 v[54:57], v[82:85], v[178:181], v[54:57]
	v_mfma_f32_16x16x32_bf16 v[46:49], v[90:93], v[178:181], v[46:49]
	v_mfma_f32_16x16x32_bf16 v[38:41], v[82:85], v[186:189], v[38:41]
	v_mfma_f32_16x16x32_bf16 v[30:33], v[90:93], v[186:189], v[30:33]
	v_mfma_f32_16x16x32_bf16 v[22:25], v[82:85], v[194:197], v[22:25]
	v_mfma_f32_16x16x32_bf16 v[14:17], v[90:93], v[194:197], v[14:17]
	v_mfma_f32_16x16x32_bf16 v[58:61], v[142:145], v[166:169], v[58:61]
	v_mfma_f32_16x16x32_bf16 v[50:53], v[158:161], v[166:169], v[50:53]
	v_mfma_f32_16x16x32_bf16 v[42:45], v[142:145], v[174:177], v[42:45]
	v_mfma_f32_16x16x32_bf16 v[34:37], v[158:161], v[174:177], v[34:37]
	v_mfma_f32_16x16x32_bf16 v[26:29], v[142:145], v[182:185], v[26:29]
	v_mfma_f32_16x16x32_bf16 v[18:21], v[158:161], v[182:185], v[18:21]
	v_mfma_f32_16x16x32_bf16 v[10:13], v[142:145], v[190:193], v[10:13]
	v_mfma_f32_16x16x32_bf16 v[6:9], v[158:161], v[190:193], v[6:9]
	v_mfma_f32_16x16x32_bf16 v[58:61], v[146:149], v[170:173], v[58:61]
	v_mfma_f32_16x16x32_bf16 v[50:53], v[162:165], v[170:173], v[50:53]
	v_mfma_f32_16x16x32_bf16 v[42:45], v[146:149], v[178:181], v[42:45]
	v_mfma_f32_16x16x32_bf16 v[34:37], v[162:165], v[178:181], v[34:37]
	v_mfma_f32_16x16x32_bf16 v[26:29], v[146:149], v[186:189], v[26:29]
	v_mfma_f32_16x16x32_bf16 v[18:21], v[162:165], v[186:189], v[18:21]
	v_mfma_f32_16x16x32_bf16 v[10:13], v[146:149], v[194:197], v[10:13]
	v_mfma_f32_16x16x32_bf16 v[6:9], v[162:165], v[194:197], v[6:9]
	s_barrier
	s_add_i32 s24, 0, 0x18000
	s_add_i32 s25, 0, 0x1c000
	v_add_u32_e32 v90, s24, v1
	v_add_u32_e32 v162, s25, v1
	ds_read_b128 v[78:81], v90
	ds_read_b128 v[82:85], v90 offset:1024
	ds_read_b128 v[86:89], v90 offset:2048
	ds_read_b128 v[90:93], v90 offset:3072
	ds_read_b128 v[142:145], v162
	ds_read_b128 v[146:149], v162 offset:1024
	ds_read_b128 v[158:161], v162 offset:2048
	ds_read_b128 v[162:165], v162 offset:3072
	s_add_u32 s22, s22, 0x100000
	s_addc_u32 s23, s23, 0
	s_mov_b32 m0, s37
	v_lshl_add_u64 v[198:199], s[22:23], 0, v[2:3]
	ds_read_b128 v[166:169], v5 offset:32768
	ds_read_b128 v[170:173], v5 offset:33792
	ds_read_b128 v[174:177], v5 offset:34816
	ds_read_b128 v[178:181], v5 offset:35840
	ds_read_b128 v[182:185], v5 offset:36864
	ds_read_b128 v[186:189], v5 offset:37888
	ds_read_b128 v[190:193], v5 offset:38912
	ds_read_b128 v[194:197], v5 offset:39936
	global_load_lds_dwordx4 v[198:199], off
	v_lshl_add_u64 v[198:199], s[22:23], 0, v[218:219]
	s_mov_b32 m0, s38
	s_nop 0
	global_load_lds_dwordx4 v[198:199], off
	s_waitcnt vmcnt(8)
	s_waitcnt lgkmcnt(0)
	s_barrier
	v_mfma_f32_16x16x32_bf16 v[154:157], v[78:81], v[166:169], v[154:157]
	v_mfma_f32_16x16x32_bf16 v[150:153], v[86:89], v[166:169], v[150:153]
	v_mfma_f32_16x16x32_bf16 v[134:137], v[78:81], v[174:177], v[134:137]
	v_mfma_f32_16x16x32_bf16 v[126:129], v[86:89], v[174:177], v[126:129]
	v_mfma_f32_16x16x32_bf16 v[118:121], v[78:81], v[182:185], v[118:121]
	v_mfma_f32_16x16x32_bf16 v[110:113], v[86:89], v[182:185], v[110:113]
	v_mfma_f32_16x16x32_bf16 v[102:105], v[78:81], v[190:193], v[102:105]
	v_mfma_f32_16x16x32_bf16 v[94:97], v[86:89], v[190:193], v[94:97]
	v_mfma_f32_16x16x32_bf16 v[154:157], v[82:85], v[170:173], v[154:157]
	v_mfma_f32_16x16x32_bf16 v[150:153], v[90:93], v[170:173], v[150:153]
	v_mfma_f32_16x16x32_bf16 v[134:137], v[82:85], v[178:181], v[134:137]
	v_mfma_f32_16x16x32_bf16 v[126:129], v[90:93], v[178:181], v[126:129]
	v_mfma_f32_16x16x32_bf16 v[118:121], v[82:85], v[186:189], v[118:121]
	v_mfma_f32_16x16x32_bf16 v[110:113], v[90:93], v[186:189], v[110:113]
	v_mfma_f32_16x16x32_bf16 v[102:105], v[82:85], v[194:197], v[102:105]
	v_mfma_f32_16x16x32_bf16 v[94:97], v[90:93], v[194:197], v[94:97]
	v_mfma_f32_16x16x32_bf16 v[138:141], v[142:145], v[166:169], v[138:141]
	v_mfma_f32_16x16x32_bf16 v[130:133], v[158:161], v[166:169], v[130:133]
	v_mfma_f32_16x16x32_bf16 v[122:125], v[142:145], v[174:177], v[122:125]
	v_mfma_f32_16x16x32_bf16 v[114:117], v[158:161], v[174:177], v[114:117]
	v_mfma_f32_16x16x32_bf16 v[106:109], v[142:145], v[182:185], v[106:109]
	v_mfma_f32_16x16x32_bf16 v[98:101], v[158:161], v[182:185], v[98:101]
	v_mfma_f32_16x16x32_bf16 v[74:77], v[142:145], v[190:193], v[74:77]
	v_mfma_f32_16x16x32_bf16 v[70:73], v[158:161], v[190:193], v[70:73]
	v_mfma_f32_16x16x32_bf16 v[138:141], v[146:149], v[170:173], v[138:141]
	v_mfma_f32_16x16x32_bf16 v[130:133], v[162:165], v[170:173], v[130:133]
	v_mfma_f32_16x16x32_bf16 v[122:125], v[146:149], v[178:181], v[122:125]
	v_mfma_f32_16x16x32_bf16 v[114:117], v[162:165], v[178:181], v[114:117]
	v_mfma_f32_16x16x32_bf16 v[106:109], v[146:149], v[186:189], v[106:109]
	v_mfma_f32_16x16x32_bf16 v[98:101], v[162:165], v[186:189], v[98:101]
	v_mfma_f32_16x16x32_bf16 v[74:77], v[146:149], v[194:197], v[74:77]
	v_mfma_f32_16x16x32_bf16 v[70:73], v[162:165], v[194:197], v[70:73]
	s_barrier
	s_add_i32 s22, s24, s29
	v_lshl_add_u64 v[198:199], s[20:21], 0, v[216:217]
	s_mov_b32 m0, s22
	ds_read_b128 v[166:169], v5 offset:49152
	ds_read_b128 v[170:173], v5 offset:50176
	ds_read_b128 v[174:177], v5 offset:51200
	ds_read_b128 v[178:181], v5 offset:52224
	ds_read_b128 v[182:185], v5 offset:53248
	ds_read_b128 v[186:189], v5 offset:54272
	ds_read_b128 v[190:193], v5 offset:55296
	ds_read_b128 v[194:197], v5 offset:56320
	global_load_lds_dwordx4 v[198:199], off
	s_add_i32 m0, s22, 0x2000
	v_lshl_add_u64 v[198:199], s[20:21], 0, v[220:221]
	s_add_u32 s20, s20, 0x100000
	s_addc_u32 s21, s21, 0
	s_add_i32 s22, s25, s29
	global_load_lds_dwordx4 v[198:199], off
	v_lshl_add_u64 v[198:199], s[20:21], 0, v[216:217]
	s_mov_b32 m0, s22
	s_nop 0
	global_load_lds_dwordx4 v[198:199], off
	v_lshl_add_u64 v[198:199], s[20:21], 0, v[220:221]
	s_add_i32 m0, s22, 0x2000
	s_nop 0
	global_load_lds_dwordx4 v[198:199], off
	v_lshl_add_u64 v[198:199], s[18:19], 0, v[2:3]
	s_mov_b32 m0, s41
	s_nop 0
	global_load_lds_dwordx4 v[198:199], off
	v_lshl_add_u64 v[198:199], s[18:19], 0, v[218:219]
	s_mov_b32 m0, s42
	s_nop 0
	global_load_lds_dwordx4 v[198:199], off
	s_waitcnt vmcnt(8)
	s_waitcnt lgkmcnt(0)
	s_barrier
	v_mfma_f32_16x16x32_bf16 v[66:69], v[78:81], v[166:169], v[66:69]
	v_mfma_f32_16x16x32_bf16 v[62:65], v[86:89], v[166:169], v[62:65]
	v_mfma_f32_16x16x32_bf16 v[54:57], v[78:81], v[174:177], v[54:57]
	v_mfma_f32_16x16x32_bf16 v[46:49], v[86:89], v[174:177], v[46:49]
	v_mfma_f32_16x16x32_bf16 v[38:41], v[78:81], v[182:185], v[38:41]
	v_mfma_f32_16x16x32_bf16 v[30:33], v[86:89], v[182:185], v[30:33]
	v_mfma_f32_16x16x32_bf16 v[22:25], v[78:81], v[190:193], v[22:25]
	v_mfma_f32_16x16x32_bf16 v[14:17], v[86:89], v[190:193], v[14:17]
	v_mfma_f32_16x16x32_bf16 v[66:69], v[82:85], v[170:173], v[66:69]
	v_mfma_f32_16x16x32_bf16 v[62:65], v[90:93], v[170:173], v[62:65]
	v_mfma_f32_16x16x32_bf16 v[54:57], v[82:85], v[178:181], v[54:57]
	v_mfma_f32_16x16x32_bf16 v[46:49], v[90:93], v[178:181], v[46:49]
	v_mfma_f32_16x16x32_bf16 v[38:41], v[82:85], v[186:189], v[38:41]
	v_mfma_f32_16x16x32_bf16 v[30:33], v[90:93], v[186:189], v[30:33]
	v_mfma_f32_16x16x32_bf16 v[22:25], v[82:85], v[194:197], v[22:25]
	v_mfma_f32_16x16x32_bf16 v[14:17], v[90:93], v[194:197], v[14:17]
	v_mfma_f32_16x16x32_bf16 v[58:61], v[142:145], v[166:169], v[58:61]
	v_mfma_f32_16x16x32_bf16 v[50:53], v[158:161], v[166:169], v[50:53]
	v_mfma_f32_16x16x32_bf16 v[42:45], v[142:145], v[174:177], v[42:45]
	v_mfma_f32_16x16x32_bf16 v[34:37], v[158:161], v[174:177], v[34:37]
	v_mfma_f32_16x16x32_bf16 v[26:29], v[142:145], v[182:185], v[26:29]
	v_mfma_f32_16x16x32_bf16 v[18:21], v[158:161], v[182:185], v[18:21]
	v_mfma_f32_16x16x32_bf16 v[10:13], v[142:145], v[190:193], v[10:13]
	v_mfma_f32_16x16x32_bf16 v[6:9], v[158:161], v[190:193], v[6:9]
	v_mfma_f32_16x16x32_bf16 v[58:61], v[146:149], v[170:173], v[58:61]
	v_mfma_f32_16x16x32_bf16 v[50:53], v[162:165], v[170:173], v[50:53]
	v_mfma_f32_16x16x32_bf16 v[42:45], v[146:149], v[178:181], v[42:45]
	v_mfma_f32_16x16x32_bf16 v[34:37], v[162:165], v[178:181], v[34:37]
	v_mfma_f32_16x16x32_bf16 v[26:29], v[146:149], v[186:189], v[26:29]
	v_mfma_f32_16x16x32_bf16 v[18:21], v[162:165], v[186:189], v[18:21]
	v_mfma_f32_16x16x32_bf16 v[10:13], v[146:149], v[194:197], v[10:13]
	v_mfma_f32_16x16x32_bf16 v[6:9], v[162:165], v[194:197], v[6:9]
	s_barrier
	s_add_i32 s47, s47, 2
	s_add_u32 s33, s33, 0x100
	s_addc_u32 s44, s44, 0
	s_add_u32 s45, s45, 0x100
	s_addc_u32 s46, s46, 0
	s_cmp_gt_u32 s47, 61
	s_cbranch_scc0 .LBB0_924
	v_mov_b32_e32 v142, v0
	s_mov_b64 s[20:21], s[84:85]
	s_add_u32 s7, s20, 0x4179c000
	v_readlane_b32 s18, v254, 26
	s_addc_u32 s9, s21, 0
	v_readlane_b32 s19, v254, 27
	v_readlane_b32 s44, v253, 35
	s_and_b64 s[18:19], s[18:19], exec
	v_readlane_b32 s45, v253, 36
	v_bfe_u32 v144, v142, 4, 2
	s_cselect_b32 s23, s9, s45
	s_cselect_b32 s22, s7, s44
	s_cselect_b32 s19, s83, s9
	s_cselect_b32 s18, s82, s7
	s_lshl_b32 s7, s8, 8
	s_lshl_b32 s6, s6, 8
	v_lshl_or_b32 v78, v144, 3, s7
	s_add_i32 s6, s6, s39
	v_or_b32_e32 v226, s40, v78
	v_ashrrev_i32_e32 v227, 31, v226
	v_readlane_b32 s8, v254, 9
	v_and_or_b32 v230, v142, 15, s6
	v_lshlrev_b64 v[244:245], 2, v[226:227]
	v_readlane_b32 s9, v254, 10
	v_lshl_add_u64 v[142:143], v[226:227], 1, s[20:21]
	s_mov_b64 s[6:7], 0x10f80000
	v_ashrrev_i32_e32 v231, 31, v230
	v_or_b32_e32 v240, 16, v230
	v_lshl_add_u64 v[82:83], s[8:9], 0, v[244:245]
	v_lshl_add_u64 v[228:229], s[22:23], 0, v[244:245]
	v_lshl_add_u64 v[224:225], v[142:143], 0, s[6:7]
	v_lshl_add_u64 v[142:143], v[230:231], 2, s[20:21]
	s_mov_b64 s[8:9], 0x18400
	v_lshlrev_b64 v[248:249], 14, v[230:231]
	v_ashrrev_i32_e32 v241, 31, v240
	v_or_b32_e32 v236, 32, v230
	v_or_b32_e32 v232, 48, v230
	v_lshl_add_u64 v[222:223], v[142:143], 0, s[8:9]
	v_lshl_add_u64 v[142:143], v[228:229], 0, v[248:249]
	v_lshlrev_b64 v[242:243], 14, v[240:241]
	v_ashrrev_i32_e32 v237, 31, v236
	v_ashrrev_i32_e32 v233, 31, v232
	global_load_dwordx4 v[86:89], v[82:83], off offset:16
	global_load_dwordx4 v[90:93], v[82:83], off
	global_load_dwordx4 v[78:81], v[82:83], off offset:528
	s_nop 0
	global_load_dwordx4 v[82:85], v[82:83], off offset:512
	s_nop 0
	global_load_dwordx4 v[206:209], v[142:143], off offset:16
	global_load_dwordx4 v[210:213], v[142:143], off
	global_load_dwordx4 v[198:201], v[142:143], off offset:528
	global_load_dwordx4 v[202:205], v[142:143], off offset:512
	v_lshl_add_u64 v[142:143], v[228:229], 0, v[242:243]
	v_lshlrev_b64 v[238:239], 14, v[236:237]
	v_lshlrev_b64 v[234:235], 14, v[232:233]
	global_load_dwordx4 v[190:193], v[142:143], off offset:16
	global_load_dwordx4 v[194:197], v[142:143], off
	global_load_dwordx4 v[182:185], v[142:143], off offset:528
	global_load_dwordx4 v[186:189], v[142:143], off offset:512
	v_lshl_add_u64 v[142:143], v[228:229], 0, v[238:239]
	v_lshl_add_u64 v[146:147], v[228:229], 0, v[234:235]
	v_cmp_eq_u32_e64 s[6:7], 0, v144
	global_load_dwordx4 v[174:177], v[142:143], off offset:16
	global_load_dwordx4 v[178:181], v[142:143], off
	global_load_dwordx4 v[166:169], v[142:143], off offset:528
	global_load_dwordx4 v[170:173], v[142:143], off offset:512
	global_load_dwordx4 v[158:161], v[146:147], off offset:16
	global_load_dwordx4 v[162:165], v[146:147], off
	s_nop 0
	global_load_dwordx4 v[142:145], v[146:147], off offset:528
	s_nop 0
	global_load_dwordx4 v[146:149], v[146:147], off offset:512
	v_lshl_add_u64 v[248:249], s[18:19], 0, v[248:249]
	v_lshl_add_u64 v[244:245], v[248:249], 0, v[244:245]
	s_mov_b64 s[20:21], -1
	s_andn2_b64 vcc, exec, s[60:61]
	v_readlane_b32 s46, v253, 37
	v_readlane_b32 s47, v253, 38
	v_readlane_b32 s48, v253, 39
	v_readlane_b32 s49, v253, 40
	v_readlane_b32 s50, v253, 41
	v_readlane_b32 s51, v253, 42
	v_readlane_b32 s52, v253, 43
	v_readlane_b32 s53, v253, 44
	v_readlane_b32 s54, v253, 45
	v_readlane_b32 s55, v253, 46
	v_readlane_b32 s56, v253, 47
	v_readlane_b32 s57, v253, 48
	v_readlane_b32 s58, v253, 49
	v_readlane_b32 s59, v253, 50
	s_waitcnt vmcnt(0)
	v_pk_add_f32 v[206:207], v[150:151], v[206:207]
	v_cndmask_b32_e64 v150, 0, 1, s[60:61]
	v_pk_add_f32 v[212:213], v[156:157], v[212:213]
	v_pk_add_f32 v[210:211], v[154:155], v[210:211]
	v_pk_add_f32 v[208:209], v[152:153], v[208:209]
	v_cmp_ne_u32_e64 s[8:9], 1, v150
	v_pk_add_f32 v[150:151], v[138:139], v[202:203]
	v_pk_add_f32 v[154:155], v[130:131], v[198:199]
	global_store_dwordx4 v[244:245], v[210:213], off
	global_store_dwordx4 v[244:245], v[206:209], off offset:16
	s_cbranch_vccnz .LBB0_929
	v_mul_f32_e32 v138, v211, v211
	v_mul_f32_e32 v139, v213, v213
	v_fmac_f32_e32 v138, v210, v210
	v_fmac_f32_e32 v139, v212, v212
	v_add_f32_e32 v138, v138, v139
	v_mul_f32_e32 v139, v207, v207
	v_fmac_f32_e32 v139, v206, v206
	v_add_f32_e32 v138, v138, v139
	v_mul_f32_e32 v139, v209, v209
	v_lshlrev_b64 v[130:131], 12, v[230:231]
	v_fmac_f32_e32 v139, v208, v208
	v_pk_mul_f32 v[152:153], v[90:91], v[210:211]
	v_pk_mul_f32 v[156:157], v[88:89], v[208:209]
	v_lshl_add_u64 v[130:131], v[130:131], 1, v[224:225]
	v_add_f32_e32 v231, v139, v138
	v_pk_mul_f32 v[138:139], v[92:93], v[212:213]
	v_pk_mul_f32 v[198:199], v[86:87], v[206:207]
	v_cvt_pk_bf16_f32 v206, v152, v153
	v_cvt_pk_bf16_f32 v207, v138, v139
	v_pk_add_f32 v[152:153], v[140:141], v[204:205]
	v_cvt_pk_bf16_f32 v208, v198, v199
	v_cvt_pk_bf16_f32 v209, v156, v157
	v_pk_add_f32 v[156:157], v[132:133], v[200:201]
	global_store_dwordx4 v[130:131], v[206:209], off
	global_store_dwordx4 v[244:245], v[150:153], off offset:512
	global_store_dwordx4 v[244:245], v[154:157], off offset:528
	v_pk_mul_f32 v[202:203], v[80:81], v[156:157]
	v_pk_mul_f32 v[138:139], v[84:85], v[152:153]
	v_mul_f32_e32 v157, v157, v157
	v_fmac_f32_e32 v157, v156, v156
	v_mul_f32_e32 v156, v151, v151
	v_mul_f32_e32 v153, v153, v153
	v_fmac_f32_e32 v156, v150, v150
	v_fmac_f32_e32 v153, v152, v152
	v_add_f32_e32 v152, v156, v153
	v_mul_f32_e32 v153, v155, v155
	v_fmac_f32_e32 v153, v154, v154
	v_add_f32_e32 v152, v152, v153
	v_add_f32_e32 v152, v157, v152
	v_add_f32_e32 v152, v231, v152
	ds_swizzle_b32 v153, v152 offset:swizzle(SWAP,16)
	v_pk_mul_f32 v[208:209], v[78:79], v[154:155]
	v_pk_mul_f32 v[198:199], v[82:83], v[150:151]
	s_nop 0
	v_cvt_pk_bf16_f32 v206, v198, v199
	v_cvt_pk_bf16_f32 v207, v138, v139
	v_cvt_pk_bf16_f32 v208, v208, v209
	v_cvt_pk_bf16_f32 v209, v202, v203
	global_store_dwordx4 v[130:131], v[206:209], off offset:256
	s_waitcnt lgkmcnt(0)
	v_add_f32_e32 v130, v152, v153
	v_mov_b32_e32 v131, v130
	s_nop 1
	v_permlane32_swap_b32_e32 v130, v131
	s_and_saveexec_b64 s[20:21], s[6:7]
	s_cbranch_execz .LBB0_928
	v_add_f32_e32 v130, v130, v131
	global_atomic_add_f32 v[222:223], v130, off
